# context scan: y=S.r cross-lane reduction batched per 8 steps as a transpose-reduce (bank-masked DPP) instead of one all-reduce + select per step
# speedup vs baseline: 1.0359x; 1.0020x over previous
.LBB0_957:
	s_bitcmp0_b32 s21, 0
	s_cselect_b32 s20, 0, s69
	v_lshl_add_u32 v88, v117, 2, s20
	ds_read_b128 v[50:53], v88
	ds_read_b128 v[54:57], v88 offset:16
	ds_read_b128 v[58:61], v88 offset:256
	ds_read_b128 v[62:65], v88 offset:272
	ds_read_b128 v[66:69], v88 offset:512
	ds_read_b128 v[70:73], v88 offset:528
	ds_read_b128 v[74:77], v88 offset:768
	ds_read_b128 v[78:81], v88 offset:784
	ds_read_b128 v[82:85], v88 offset:1024
	ds_read_b128 v[90:93], v88 offset:1040
	s_waitcnt lgkmcnt(5)
	v_pk_mul_f32 v[86:87], v[24:25], v[66:67]
	s_cselect_b32 s20, s96, s97
	v_pk_fma_f32 v[86:87], v[26:27], v[68:69], v[86:87]
	v_lshl_add_u32 v104, v28, 2, s20
	s_waitcnt lgkmcnt(4)
	v_pk_fma_f32 v[86:87], v[20:21], v[70:71], v[86:87]
	ds_read2st64_b64 v[94:97], v104 offset1:3
	ds_read_b128 v[98:101], v88 offset:1536
	ds_read_b128 v[106:109], v88 offset:1552
	ds_read_b128 v[110:113], v88 offset:1792
	ds_read_b128 v[120:123], v88 offset:1808
	ds_read_b128 v[124:127], v88 offset:2048
	ds_read_b128 v[128:131], v88 offset:2064
	ds_read_b128 v[132:135], v88 offset:2304
	ds_read_b128 v[146:149], v88 offset:2320
	ds_read_b128 v[150:153], v88 offset:2560
	ds_read_b128 v[154:157], v88 offset:2576
	v_pk_fma_f32 v[86:87], v[22:23], v[72:73], v[86:87]
	s_waitcnt lgkmcnt(10)
	v_pk_mul_f32 v[102:103], v[58:59], v[94:95] op_sel_hi:[1,0]
	v_add_f32_e32 v86, v86, v87
	s_andn2_b64 vcc, exec, s[0:1]
	s_nop 0
	v_add_f32_dpp v86, v86, v86 quad_perm:[1,0,3,2] row_mask:0xf bank_mask:0xf bound_ctrl:1
	s_nop 1
	v_add_f32_dpp v86, v86, v86 quad_perm:[2,3,0,1] row_mask:0xf bank_mask:0xf bound_ctrl:1
	s_nop 1
	v_add_f32_dpp v86, v86, v86 row_half_mirror row_mask:0xf bank_mask:0xf bound_ctrl:1
	v_pk_fma_f32 v[102:103], v[86:87], v[74:75], v[102:103] op_sel_hi:[0,1,1]
	v_pk_fma_f32 v[102:103], v[24:25], v[50:51], v[102:103]
	v_pk_mul_f32 v[24:25], v[60:61], v[94:95] op_sel_hi:[1,0]
	s_nop 0
	v_pk_fma_f32 v[24:25], v[86:87], v[76:77], v[24:25] op_sel_hi:[0,1,1]
	v_pk_fma_f32 v[114:115], v[26:27], v[52:53], v[24:25]
	v_pk_mul_f32 v[24:25], v[62:63], v[94:95] op_sel_hi:[1,0]
	s_nop 0
	v_pk_fma_f32 v[24:25], v[86:87], v[78:79], v[24:25] op_sel_hi:[0,1,1]
	v_pk_fma_f32 v[158:159], v[20:21], v[54:55], v[24:25]
	v_pk_mul_f32 v[20:21], v[64:65], v[94:95] op_sel_hi:[1,0]
	v_pk_mul_f32 v[24:25], v[58:59], v[94:95] op_sel:[0,1]
	v_pk_fma_f32 v[20:21], v[86:87], v[80:81], v[20:21] op_sel_hi:[0,1,1]
	v_pk_fma_f32 v[160:161], v[22:23], v[56:57], v[20:21]
	v_pk_mul_f32 v[22:23], v[16:17], v[66:67]
	v_pk_mul_f32 v[20:21], v[82:83], v[102:103]
	v_pk_fma_f32 v[22:23], v[18:19], v[68:69], v[22:23]
	v_pk_fma_f32 v[20:21], v[114:115], v[84:85], v[20:21]
	v_pk_fma_f32 v[22:23], v[12:13], v[70:71], v[22:23]
	v_pk_fma_f32 v[20:21], v[158:159], v[90:91], v[20:21]
	v_pk_fma_f32 v[22:23], v[14:15], v[72:73], v[22:23]
	v_pk_fma_f32 v[20:21], v[160:161], v[92:93], v[20:21]
	v_add_f32_e32 v22, v22, v23
	s_nop 1
	v_add_f32_dpp v22, v22, v22 quad_perm:[1,0,3,2] row_mask:0xf bank_mask:0xf bound_ctrl:1
	s_nop 1
	v_add_f32_dpp v22, v22, v22 quad_perm:[2,3,0,1] row_mask:0xf bank_mask:0xf bound_ctrl:1
	s_nop 1
	v_add_f32_dpp v22, v22, v22 row_half_mirror row_mask:0xf bank_mask:0xf bound_ctrl:1
	v_pk_fma_f32 v[24:25], v[22:23], v[74:75], v[24:25] op_sel_hi:[0,1,1]
	v_pk_fma_f32 v[58:59], v[16:17], v[50:51], v[24:25]
	v_pk_mul_f32 v[16:17], v[60:61], v[94:95] op_sel:[0,1]
	s_nop 0
	v_pk_fma_f32 v[16:17], v[22:23], v[76:77], v[16:17] op_sel_hi:[0,1,1]
	v_pk_fma_f32 v[162:163], v[18:19], v[52:53], v[16:17]
	v_pk_mul_f32 v[16:17], v[62:63], v[94:95] op_sel:[0,1]
	s_nop 0
	v_pk_fma_f32 v[16:17], v[22:23], v[78:79], v[16:17] op_sel_hi:[0,1,1]
	v_pk_fma_f32 v[54:55], v[12:13], v[54:55], v[16:17]
	v_pk_mul_f32 v[12:13], v[64:65], v[94:95] op_sel:[0,1]
	s_waitcnt lgkmcnt(7)
	v_pk_mul_f32 v[94:95], v[110:111], v[96:97] op_sel:[0,1]
	v_pk_fma_f32 v[12:13], v[22:23], v[80:81], v[12:13] op_sel_hi:[0,1,1]
	v_pk_fma_f32 v[56:57], v[14:15], v[56:57], v[12:13]
	v_pk_mul_f32 v[12:13], v[82:83], v[58:59]
	v_add_f32_e32 v210, v20, v21
	v_pk_fma_f32 v[12:13], v[162:163], v[84:85], v[12:13]
	s_nop 0
	v_pk_fma_f32 v[12:13], v[54:55], v[90:91], v[12:13]
	s_waitcnt lgkmcnt(5)
	v_pk_mul_f32 v[90:91], v[124:125], v[102:103]
	v_pk_fma_f32 v[12:13], v[56:57], v[92:93], v[12:13]
	v_pk_fma_f32 v[90:91], v[114:115], v[126:127], v[90:91]
	v_pk_mul_f32 v[92:93], v[110:111], v[96:97] op_sel_hi:[1,0]
	s_waitcnt lgkmcnt(4)
	v_pk_fma_f32 v[90:91], v[158:159], v[128:129], v[90:91]
	v_add_f32_e32 v218, v12, v13
	v_pk_fma_f32 v[90:91], v[160:161], v[130:131], v[90:91]
	v_add_f32_e32 v90, v90, v91
	s_nop 0
	s_nop 0
	v_add_f32_dpp v90, v90, v90 quad_perm:[1,0,3,2] row_mask:0xf bank_mask:0xf bound_ctrl:1
	s_nop 1
	v_add_f32_dpp v90, v90, v90 quad_perm:[2,3,0,1] row_mask:0xf bank_mask:0xf bound_ctrl:1
	ds_read_b128 v[12:15], v88 offset:3072
	ds_read_b128 v[16:19], v88 offset:3088
	ds_read_b128 v[20:23], v88 offset:3328
	ds_read_b128 v[24:27], v88 offset:3344
	ds_read_b128 v[60:63], v88 offset:3584
	ds_read_b128 v[64:67], v88 offset:3600
	ds_read_b128 v[68:71], v88 offset:3840
	ds_read_b128 v[72:75], v88 offset:3856
	ds_read_b128 v[76:79], v88 offset:4096
	ds_read_b128 v[80:83], v88 offset:4112
	ds_read2st64_b64 v[84:87], v104 offset0:6 offset1:9
	v_add_f32_dpp v90, v90, v90 row_half_mirror row_mask:0xf bank_mask:0xf bound_ctrl:1
	s_waitcnt lgkmcnt(14)
	v_pk_fma_f32 v[92:93], v[90:91], v[132:133], v[92:93] op_sel_hi:[0,1,1]
	v_pk_fma_f32 v[102:103], v[102:103], v[98:99], v[92:93]
	v_pk_mul_f32 v[92:93], v[112:113], v[96:97] op_sel_hi:[1,0]
	v_pk_fma_f32 v[92:93], v[90:91], v[134:135], v[92:93] op_sel_hi:[0,1,1]
	v_pk_fma_f32 v[114:115], v[114:115], v[100:101], v[92:93]
	v_pk_mul_f32 v[92:93], v[120:121], v[96:97] op_sel_hi:[1,0]
	s_waitcnt lgkmcnt(13)
	v_pk_fma_f32 v[92:93], v[90:91], v[146:147], v[92:93] op_sel_hi:[0,1,1]
	v_pk_fma_f32 v[158:159], v[158:159], v[106:107], v[92:93]
	v_pk_mul_f32 v[92:93], v[122:123], v[96:97] op_sel_hi:[1,0]
	v_pk_fma_f32 v[90:91], v[90:91], v[148:149], v[92:93] op_sel_hi:[0,1,1]
	v_pk_mul_f32 v[92:93], v[124:125], v[58:59]
	v_pk_fma_f32 v[160:161], v[160:161], v[108:109], v[90:91]
	v_pk_fma_f32 v[92:93], v[162:163], v[126:127], v[92:93]
	s_waitcnt lgkmcnt(12)
	v_pk_mul_f32 v[90:91], v[150:151], v[102:103]
	v_pk_fma_f32 v[92:93], v[54:55], v[128:129], v[92:93]
	v_pk_fma_f32 v[90:91], v[114:115], v[152:153], v[90:91]
	v_pk_fma_f32 v[92:93], v[56:57], v[130:131], v[92:93]
	s_waitcnt lgkmcnt(11)
	v_pk_fma_f32 v[90:91], v[158:159], v[154:155], v[90:91]
	v_add_f32_e32 v92, v92, v93
	v_pk_fma_f32 v[90:91], v[160:161], v[156:157], v[90:91]
	s_nop 0
	v_add_f32_dpp v92, v92, v92 quad_perm:[1,0,3,2] row_mask:0xf bank_mask:0xf bound_ctrl:1
	s_nop 1
	v_add_f32_dpp v92, v92, v92 quad_perm:[2,3,0,1] row_mask:0xf bank_mask:0xf bound_ctrl:1
	s_nop 1
	v_add_f32_dpp v92, v92, v92 row_half_mirror row_mask:0xf bank_mask:0xf bound_ctrl:1
	v_pk_fma_f32 v[94:95], v[92:93], v[132:133], v[94:95] op_sel_hi:[0,1,1]
	v_pk_fma_f32 v[164:165], v[58:59], v[98:99], v[94:95]
	v_pk_mul_f32 v[58:59], v[112:113], v[96:97] op_sel:[0,1]
	s_nop 0
	v_pk_fma_f32 v[58:59], v[92:93], v[134:135], v[58:59] op_sel_hi:[0,1,1]
	v_pk_fma_f32 v[162:163], v[162:163], v[100:101], v[58:59]
	v_pk_mul_f32 v[58:59], v[120:121], v[96:97] op_sel:[0,1]
	s_nop 0
	v_pk_fma_f32 v[58:59], v[92:93], v[146:147], v[58:59] op_sel_hi:[0,1,1]
	v_pk_fma_f32 v[166:167], v[54:55], v[106:107], v[58:59]
	s_waitcnt lgkmcnt(6)
	v_pk_mul_f32 v[58:59], v[60:61], v[102:103]
	v_pk_mul_f32 v[54:55], v[122:123], v[96:97] op_sel:[0,1]
	v_pk_fma_f32 v[58:59], v[114:115], v[62:63], v[58:59]
	v_pk_mul_f32 v[60:61], v[60:61], v[164:165]
	s_waitcnt lgkmcnt(5)
	v_pk_fma_f32 v[58:59], v[158:159], v[64:65], v[58:59]
	v_pk_fma_f32 v[54:55], v[92:93], v[148:149], v[54:55] op_sel_hi:[0,1,1]
	v_pk_fma_f32 v[58:59], v[160:161], v[66:67], v[58:59]
	v_pk_fma_f32 v[60:61], v[162:163], v[62:63], v[60:61]
	v_pk_fma_f32 v[168:169], v[56:57], v[108:109], v[54:55]
	v_add_f32_e32 v58, v58, v59
	v_pk_fma_f32 v[60:61], v[166:167], v[64:65], v[60:61]
	v_pk_mul_f32 v[54:55], v[150:151], v[164:165]
	v_add_f32_dpp v58, v58, v58 quad_perm:[1,0,3,2] row_mask:0xf bank_mask:0xf bound_ctrl:1
	v_pk_fma_f32 v[60:61], v[168:169], v[66:67], v[60:61]
	s_waitcnt lgkmcnt(0)
	v_pk_mul_f32 v[150:151], v[20:21], v[84:85] op_sel_hi:[1,0]
	v_add_f32_dpp v58, v58, v58 quad_perm:[2,3,0,1] row_mask:0xf bank_mask:0xf bound_ctrl:1
	v_add_f32_e32 v60, v60, v61
	v_pk_mul_f32 v[20:21], v[20:21], v[84:85] op_sel:[0,1]
	v_add_f32_dpp v58, v58, v58 row_half_mirror row_mask:0xf bank_mask:0xf bound_ctrl:1
	v_add_f32_dpp v60, v60, v60 quad_perm:[1,0,3,2] row_mask:0xf bank_mask:0xf bound_ctrl:1
	v_pk_fma_f32 v[150:151], v[58:59], v[68:69], v[150:151] op_sel_hi:[0,1,1]
	v_pk_fma_f32 v[102:103], v[102:103], v[12:13], v[150:151]
	v_add_f32_dpp v60, v60, v60 quad_perm:[2,3,0,1] row_mask:0xf bank_mask:0xf bound_ctrl:1
	v_pk_mul_f32 v[150:151], v[22:23], v[84:85] op_sel_hi:[1,0]
	v_pk_fma_f32 v[54:55], v[162:163], v[152:153], v[54:55]
	v_add_f32_dpp v60, v60, v60 row_half_mirror row_mask:0xf bank_mask:0xf bound_ctrl:1
	v_pk_fma_f32 v[150:151], v[58:59], v[70:71], v[150:151] op_sel_hi:[0,1,1]
	v_pk_fma_f32 v[20:21], v[60:61], v[68:69], v[20:21] op_sel_hi:[0,1,1]
	v_pk_fma_f32 v[54:55], v[166:167], v[154:155], v[54:55]
	v_pk_fma_f32 v[114:115], v[114:115], v[14:15], v[150:151]
	v_pk_mul_f32 v[150:151], v[24:25], v[84:85] op_sel_hi:[1,0]
	v_pk_fma_f32 v[64:65], v[164:165], v[12:13], v[20:21]
	v_pk_mul_f32 v[12:13], v[22:23], v[84:85] op_sel:[0,1]
	v_pk_fma_f32 v[54:55], v[168:169], v[156:157], v[54:55]
	v_pk_fma_f32 v[150:151], v[58:59], v[72:73], v[150:151] op_sel_hi:[0,1,1]
	v_pk_fma_f32 v[12:13], v[60:61], v[70:71], v[12:13] op_sel_hi:[0,1,1]
	v_add_f32_e32 v211, v90, v91
	v_add_f32_e32 v219, v54, v55
	ds_read_b128 v[90:93], v88 offset:4608
	ds_read_b128 v[94:97], v88 offset:4624
	ds_read_b128 v[98:101], v88 offset:4864
	ds_read_b128 v[106:109], v88 offset:4880
	ds_read_b128 v[110:113], v88 offset:5120
	ds_read_b128 v[120:123], v88 offset:5136
	ds_read_b128 v[124:127], v88 offset:5376
	ds_read_b128 v[128:131], v88 offset:5392
	ds_read_b128 v[132:135], v88 offset:5632
	ds_read_b128 v[146:149], v88 offset:5648
	v_pk_fma_f32 v[170:171], v[158:159], v[16:17], v[150:151]
	v_pk_mul_f32 v[150:151], v[26:27], v[84:85] op_sel_hi:[1,0]
	v_pk_fma_f32 v[66:67], v[162:163], v[14:15], v[12:13]
	v_pk_mul_f32 v[12:13], v[24:25], v[84:85] op_sel:[0,1]
	s_waitcnt lgkmcnt(5)
	v_pk_mul_f32 v[62:63], v[110:111], v[102:103]
	v_pk_fma_f32 v[58:59], v[58:59], v[74:75], v[150:151] op_sel_hi:[0,1,1]
	v_pk_fma_f32 v[12:13], v[60:61], v[72:73], v[12:13] op_sel_hi:[0,1,1]
	v_pk_fma_f32 v[62:63], v[114:115], v[112:113], v[62:63]
	v_pk_fma_f32 v[172:173], v[160:161], v[18:19], v[58:59]
	v_pk_fma_f32 v[162:163], v[166:167], v[16:17], v[12:13]
	v_pk_mul_f32 v[12:13], v[26:27], v[84:85] op_sel:[0,1]
	s_waitcnt lgkmcnt(4)
	v_pk_fma_f32 v[62:63], v[170:171], v[120:121], v[62:63]
	v_pk_mul_f32 v[110:111], v[110:111], v[64:65]
	v_pk_fma_f32 v[12:13], v[60:61], v[74:75], v[12:13] op_sel_hi:[0,1,1]
	v_pk_fma_f32 v[62:63], v[172:173], v[122:123], v[62:63]
	v_pk_fma_f32 v[110:111], v[66:67], v[112:113], v[110:111]
	v_pk_fma_f32 v[84:85], v[168:169], v[18:19], v[12:13]
	v_add_f32_e32 v62, v62, v63
	v_pk_fma_f32 v[110:111], v[162:163], v[120:121], v[110:111]
	v_pk_mul_f32 v[164:165], v[98:99], v[86:87] op_sel_hi:[1,0]
	v_add_f32_dpp v62, v62, v62 quad_perm:[1,0,3,2] row_mask:0xf bank_mask:0xf bound_ctrl:1
	v_pk_fma_f32 v[110:111], v[84:85], v[122:123], v[110:111]
	v_pk_mul_f32 v[58:59], v[76:77], v[102:103]
	v_add_f32_dpp v62, v62, v62 quad_perm:[2,3,0,1] row_mask:0xf bank_mask:0xf bound_ctrl:1
	v_add_f32_e32 v105, v110, v111
	v_pk_mul_f32 v[98:99], v[98:99], v[86:87] op_sel:[0,1]
	v_add_f32_dpp v62, v62, v62 row_half_mirror row_mask:0xf bank_mask:0xf bound_ctrl:1
	v_add_f32_dpp v105, v105, v105 quad_perm:[1,0,3,2] row_mask:0xf bank_mask:0xf bound_ctrl:1
	s_waitcnt lgkmcnt(3)
	v_pk_fma_f32 v[164:165], v[62:63], v[124:125], v[164:165] op_sel_hi:[0,1,1]
	v_pk_fma_f32 v[102:103], v[102:103], v[90:91], v[164:165]
	v_add_f32_dpp v105, v105, v105 quad_perm:[2,3,0,1] row_mask:0xf bank_mask:0xf bound_ctrl:1
	v_pk_mul_f32 v[164:165], v[100:101], v[86:87] op_sel_hi:[1,0]
	v_pk_mul_f32 v[12:13], v[76:77], v[64:65]
	v_add_f32_dpp v110, v105, v105 row_half_mirror row_mask:0xf bank_mask:0xf bound_ctrl:1
	v_pk_fma_f32 v[164:165], v[62:63], v[126:127], v[164:165] op_sel_hi:[0,1,1]
	v_pk_fma_f32 v[98:99], v[110:111], v[124:125], v[98:99] op_sel_hi:[0,1,1]
	v_pk_fma_f32 v[58:59], v[114:115], v[78:79], v[58:59]
	v_pk_fma_f32 v[12:13], v[66:67], v[78:79], v[12:13]
	v_pk_fma_f32 v[114:115], v[114:115], v[92:93], v[164:165]
	v_pk_mul_f32 v[164:165], v[106:107], v[86:87] op_sel_hi:[1,0]
	v_pk_fma_f32 v[168:169], v[64:65], v[90:91], v[98:99]
	v_pk_mul_f32 v[64:65], v[100:101], v[86:87] op_sel:[0,1]
	v_pk_fma_f32 v[58:59], v[170:171], v[80:81], v[58:59]
	v_pk_fma_f32 v[12:13], v[162:163], v[80:81], v[12:13]
	s_waitcnt lgkmcnt(2)
	v_pk_fma_f32 v[164:165], v[62:63], v[128:129], v[164:165] op_sel_hi:[0,1,1]
	v_pk_fma_f32 v[64:65], v[110:111], v[126:127], v[64:65] op_sel_hi:[0,1,1]
	v_pk_fma_f32 v[58:59], v[172:173], v[82:83], v[58:59]
	v_pk_fma_f32 v[60:61], v[84:85], v[82:83], v[12:13]
	ds_read_b128 v[12:15], v88 offset:6144
	ds_read_b128 v[16:19], v88 offset:6160
	ds_read_b128 v[20:23], v88 offset:6400
	ds_read_b128 v[24:27], v88 offset:6416
	ds_read_b128 v[68:71], v88 offset:6656
	ds_read_b128 v[72:75], v88 offset:6672
	ds_read_b128 v[76:79], v88 offset:6912
	ds_read_b128 v[80:83], v88 offset:6928
	ds_read_b128 v[150:153], v88 offset:7168
	ds_read_b128 v[154:157], v88 offset:7184
	ds_read2st64_b64 v[158:161], v104 offset0:12 offset1:15
	v_pk_fma_f32 v[164:165], v[170:171], v[94:95], v[164:165]
	v_pk_mul_f32 v[166:167], v[108:109], v[86:87] op_sel_hi:[1,0]
	v_pk_fma_f32 v[170:171], v[66:67], v[92:93], v[64:65]
	s_waitcnt lgkmcnt(6)
	v_pk_mul_f32 v[66:67], v[68:69], v[102:103]
	v_pk_fma_f32 v[62:63], v[62:63], v[130:131], v[166:167] op_sel_hi:[0,1,1]
	v_pk_mul_f32 v[64:65], v[106:107], v[86:87] op_sel:[0,1]
	v_pk_fma_f32 v[66:67], v[114:115], v[70:71], v[66:67]
	v_pk_fma_f32 v[166:167], v[172:173], v[96:97], v[62:63]
	v_pk_fma_f32 v[64:65], v[110:111], v[128:129], v[64:65] op_sel_hi:[0,1,1]
	s_waitcnt lgkmcnt(5)
	v_pk_fma_f32 v[66:67], v[164:165], v[72:73], v[66:67]
	v_pk_fma_f32 v[162:163], v[162:163], v[94:95], v[64:65]
	v_pk_mul_f32 v[64:65], v[108:109], v[86:87] op_sel:[0,1]
	v_pk_fma_f32 v[66:67], v[166:167], v[74:75], v[66:67]
	v_pk_fma_f32 v[64:65], v[110:111], v[130:131], v[64:65] op_sel_hi:[0,1,1]
	v_add_f32_e32 v66, v66, v67
	v_pk_mul_f32 v[62:63], v[132:133], v[102:103]
	v_pk_fma_f32 v[172:173], v[84:85], v[96:97], v[64:65]
	v_pk_mul_f32 v[64:65], v[132:133], v[168:169]
	v_add_f32_dpp v66, v66, v66 quad_perm:[1,0,3,2] row_mask:0xf bank_mask:0xf bound_ctrl:1
	v_pk_mul_f32 v[68:69], v[68:69], v[168:169]
	v_pk_fma_f32 v[62:63], v[114:115], v[134:135], v[62:63]
	v_pk_fma_f32 v[64:65], v[170:171], v[134:135], v[64:65]
	v_add_f32_dpp v66, v66, v66 quad_perm:[2,3,0,1] row_mask:0xf bank_mask:0xf bound_ctrl:1
	v_pk_fma_f32 v[68:69], v[170:171], v[70:71], v[68:69]
	v_pk_fma_f32 v[62:63], v[164:165], v[146:147], v[62:63]
	v_pk_fma_f32 v[64:65], v[162:163], v[146:147], v[64:65]
	v_add_f32_dpp v66, v66, v66 row_half_mirror row_mask:0xf bank_mask:0xf bound_ctrl:1
	s_waitcnt lgkmcnt(0)
	v_pk_mul_f32 v[146:147], v[20:21], v[158:159] op_sel_hi:[1,0]
	v_pk_fma_f32 v[68:69], v[162:163], v[72:73], v[68:69]
	v_pk_fma_f32 v[146:147], v[66:67], v[76:77], v[146:147] op_sel_hi:[0,1,1]
	v_pk_fma_f32 v[68:69], v[172:173], v[74:75], v[68:69]
	v_pk_fma_f32 v[102:103], v[102:103], v[12:13], v[146:147]
	v_pk_mul_f32 v[146:147], v[22:23], v[158:159] op_sel_hi:[1,0]
	v_add_f32_e32 v68, v68, v69
	v_pk_fma_f32 v[146:147], v[66:67], v[78:79], v[146:147] op_sel_hi:[0,1,1]
	v_pk_fma_f32 v[114:115], v[114:115], v[14:15], v[146:147]
	v_add_f32_dpp v68, v68, v68 quad_perm:[1,0,3,2] row_mask:0xf bank_mask:0xf bound_ctrl:1
	v_pk_mul_f32 v[146:147], v[24:25], v[158:159] op_sel_hi:[1,0]
	v_pk_mul_f32 v[20:21], v[20:21], v[158:159] op_sel:[0,1]
	v_add_f32_dpp v68, v68, v68 quad_perm:[2,3,0,1] row_mask:0xf bank_mask:0xf bound_ctrl:1
	v_pk_fma_f32 v[146:147], v[66:67], v[80:81], v[146:147] op_sel_hi:[0,1,1]
	ds_read_b128 v[84:87], v88 offset:7680
	ds_read_b128 v[90:93], v88 offset:7696
	ds_read_b128 v[94:97], v88 offset:7936
	ds_read_b128 v[98:101], v88 offset:7952
	ds_read_b128 v[106:109], v88 offset:8192
	ds_read_b128 v[110:113], v88 offset:8208
	ds_read_b128 v[120:123], v88 offset:8448
	ds_read_b128 v[124:127], v88 offset:8464
	ds_read_b128 v[128:131], v88 offset:8704
	ds_read_b128 v[132:135], v88 offset:8720
	v_add_f32_dpp v68, v68, v68 row_half_mirror row_mask:0xf bank_mask:0xf bound_ctrl:1
	v_pk_fma_f32 v[174:175], v[164:165], v[16:17], v[146:147]
	v_pk_mul_f32 v[146:147], v[26:27], v[158:159] op_sel_hi:[1,0]
	v_pk_fma_f32 v[20:21], v[68:69], v[76:77], v[20:21] op_sel_hi:[0,1,1]
	s_waitcnt lgkmcnt(5)
	v_pk_mul_f32 v[70:71], v[106:107], v[102:103]
	v_pk_fma_f32 v[66:67], v[66:67], v[82:83], v[146:147] op_sel_hi:[0,1,1]
	v_pk_fma_f32 v[72:73], v[168:169], v[12:13], v[20:21]
	v_pk_mul_f32 v[12:13], v[22:23], v[158:159] op_sel:[0,1]
	v_pk_fma_f32 v[70:71], v[114:115], v[108:109], v[70:71]
	v_pk_fma_f32 v[176:177], v[166:167], v[18:19], v[66:67]
	v_pk_fma_f32 v[12:13], v[68:69], v[78:79], v[12:13] op_sel_hi:[0,1,1]
	s_waitcnt lgkmcnt(4)
	v_pk_fma_f32 v[70:71], v[174:175], v[110:111], v[70:71]
	v_pk_fma_f32 v[74:75], v[170:171], v[14:15], v[12:13]
	v_pk_mul_f32 v[12:13], v[24:25], v[158:159] op_sel:[0,1]
	v_pk_fma_f32 v[70:71], v[176:177], v[112:113], v[70:71]
	v_pk_fma_f32 v[12:13], v[68:69], v[80:81], v[12:13] op_sel_hi:[0,1,1]
	v_add_f32_e32 v70, v70, v71
	v_pk_fma_f32 v[170:171], v[162:163], v[16:17], v[12:13]
	v_pk_mul_f32 v[12:13], v[26:27], v[158:159] op_sel:[0,1]
	v_add_f32_dpp v70, v70, v70 quad_perm:[1,0,3,2] row_mask:0xf bank_mask:0xf bound_ctrl:1
	v_pk_fma_f32 v[12:13], v[68:69], v[82:83], v[12:13] op_sel_hi:[0,1,1]
	v_pk_mul_f32 v[106:107], v[106:107], v[72:73]
	v_add_f32_dpp v70, v70, v70 quad_perm:[2,3,0,1] row_mask:0xf bank_mask:0xf bound_ctrl:1
	v_pk_fma_f32 v[64:65], v[172:173], v[148:149], v[64:65]
	v_pk_fma_f32 v[158:159], v[172:173], v[18:19], v[12:13]
	v_add_f32_dpp v70, v70, v70 row_half_mirror row_mask:0xf bank_mask:0xf bound_ctrl:1
	v_pk_mul_f32 v[172:173], v[94:95], v[160:161] op_sel_hi:[1,0]
	v_pk_fma_f32 v[106:107], v[74:75], v[108:109], v[106:107]
	s_waitcnt lgkmcnt(3)
	v_pk_fma_f32 v[172:173], v[70:71], v[120:121], v[172:173] op_sel_hi:[0,1,1]
	v_pk_fma_f32 v[106:107], v[170:171], v[110:111], v[106:107]
	v_pk_mul_f32 v[66:67], v[150:151], v[102:103]
	v_pk_fma_f32 v[102:103], v[102:103], v[84:85], v[172:173]
	v_pk_mul_f32 v[172:173], v[96:97], v[160:161] op_sel_hi:[1,0]
	v_pk_fma_f32 v[106:107], v[158:159], v[112:113], v[106:107]
	v_pk_fma_f32 v[172:173], v[70:71], v[122:123], v[172:173] op_sel_hi:[0,1,1]
	v_add_f32_e32 v105, v106, v107
	v_pk_fma_f32 v[66:67], v[114:115], v[152:153], v[66:67]
	v_pk_fma_f32 v[114:115], v[114:115], v[86:87], v[172:173]
	v_pk_mul_f32 v[172:173], v[98:99], v[160:161] op_sel_hi:[1,0]
	v_add_f32_dpp v105, v105, v105 quad_perm:[1,0,3,2] row_mask:0xf bank_mask:0xf bound_ctrl:1
	s_waitcnt lgkmcnt(2)
	v_pk_fma_f32 v[172:173], v[70:71], v[124:125], v[172:173] op_sel_hi:[0,1,1]
	v_pk_fma_f32 v[66:67], v[174:175], v[154:155], v[66:67]
	v_add_f32_dpp v105, v105, v105 quad_perm:[2,3,0,1] row_mask:0xf bank_mask:0xf bound_ctrl:1
	v_pk_fma_f32 v[172:173], v[174:175], v[90:91], v[172:173]
	v_pk_mul_f32 v[174:175], v[100:101], v[160:161] op_sel_hi:[1,0]
	v_add_f32_dpp v106, v105, v105 row_half_mirror row_mask:0xf bank_mask:0xf bound_ctrl:1
	v_pk_mul_f32 v[94:95], v[94:95], v[160:161] op_sel:[0,1]
	v_pk_mul_f32 v[12:13], v[150:151], v[72:73]
	v_pk_fma_f32 v[70:71], v[70:71], v[126:127], v[174:175] op_sel_hi:[0,1,1]
	v_pk_fma_f32 v[94:95], v[106:107], v[120:121], v[94:95] op_sel_hi:[0,1,1]
	v_pk_fma_f32 v[66:67], v[176:177], v[156:157], v[66:67]
	v_pk_fma_f32 v[12:13], v[74:75], v[152:153], v[12:13]
	v_pk_fma_f32 v[174:175], v[176:177], v[92:93], v[70:71]
	v_pk_fma_f32 v[176:177], v[72:73], v[84:85], v[94:95]
	v_pk_mul_f32 v[72:73], v[96:97], v[160:161] op_sel:[0,1]
	v_pk_fma_f32 v[12:13], v[170:171], v[154:155], v[12:13]
	v_pk_fma_f32 v[72:73], v[106:107], v[122:123], v[72:73] op_sel_hi:[0,1,1]
	v_pk_fma_f32 v[62:63], v[166:167], v[148:149], v[62:63]
	v_pk_fma_f32 v[68:69], v[158:159], v[156:157], v[12:13]
	ds_read_b128 v[12:15], v88 offset:9216
	ds_read_b128 v[16:19], v88 offset:9232
	ds_read_b128 v[20:23], v88 offset:9472
	ds_read_b128 v[24:27], v88 offset:9488
	ds_read_b128 v[76:79], v88 offset:9728
	ds_read_b128 v[80:83], v88 offset:9744
	ds_read_b128 v[146:149], v88 offset:9984
	ds_read_b128 v[150:153], v88 offset:10000
	ds_read_b128 v[154:157], v88 offset:10240
	ds_read_b128 v[162:165], v88 offset:10256
	ds_read2st64_b64 v[166:169], v104 offset0:18 offset1:21
	v_pk_fma_f32 v[178:179], v[74:75], v[86:87], v[72:73]
	s_waitcnt lgkmcnt(6)
	v_pk_mul_f32 v[74:75], v[76:77], v[102:103]
	v_pk_mul_f32 v[72:73], v[98:99], v[160:161] op_sel:[0,1]
	v_pk_fma_f32 v[74:75], v[114:115], v[78:79], v[74:75]
	v_pk_fma_f32 v[72:73], v[106:107], v[124:125], v[72:73] op_sel_hi:[0,1,1]
	s_waitcnt lgkmcnt(5)
	v_pk_fma_f32 v[74:75], v[172:173], v[80:81], v[74:75]
	v_pk_fma_f32 v[170:171], v[170:171], v[90:91], v[72:73]
	v_pk_fma_f32 v[74:75], v[174:175], v[82:83], v[74:75]
	v_pk_mul_f32 v[72:73], v[100:101], v[160:161] op_sel:[0,1]
	v_add_f32_e32 v74, v74, v75
	v_pk_mul_f32 v[76:77], v[76:77], v[176:177]
	v_pk_fma_f32 v[72:73], v[106:107], v[126:127], v[72:73] op_sel_hi:[0,1,1]
	v_add_f32_dpp v74, v74, v74 quad_perm:[1,0,3,2] row_mask:0xf bank_mask:0xf bound_ctrl:1
	s_waitcnt lgkmcnt(0)
	v_pk_mul_f32 v[160:161], v[20:21], v[166:167] op_sel_hi:[1,0]
	v_pk_fma_f32 v[76:77], v[178:179], v[78:79], v[76:77]
	v_add_f32_dpp v74, v74, v74 quad_perm:[2,3,0,1] row_mask:0xf bank_mask:0xf bound_ctrl:1
	v_pk_fma_f32 v[158:159], v[158:159], v[92:93], v[72:73]
	v_pk_fma_f32 v[76:77], v[170:171], v[80:81], v[76:77]
	v_add_f32_dpp v74, v74, v74 row_half_mirror row_mask:0xf bank_mask:0xf bound_ctrl:1
	v_pk_fma_f32 v[160:161], v[74:75], v[146:147], v[160:161] op_sel_hi:[0,1,1]
	v_pk_mul_f32 v[70:71], v[128:129], v[102:103]
	v_pk_fma_f32 v[102:103], v[102:103], v[12:13], v[160:161]
	v_pk_mul_f32 v[160:161], v[22:23], v[166:167] op_sel_hi:[1,0]
	v_pk_fma_f32 v[76:77], v[158:159], v[82:83], v[76:77]
	v_pk_mul_f32 v[72:73], v[128:129], v[176:177]
	v_pk_fma_f32 v[160:161], v[74:75], v[148:149], v[160:161] op_sel_hi:[0,1,1]
	v_add_f32_e32 v76, v76, v77
	v_pk_fma_f32 v[70:71], v[114:115], v[130:131], v[70:71]
	v_pk_fma_f32 v[72:73], v[178:179], v[130:131], v[72:73]
	v_pk_fma_f32 v[114:115], v[114:115], v[14:15], v[160:161]
	v_pk_mul_f32 v[160:161], v[24:25], v[166:167] op_sel_hi:[1,0]
	v_add_f32_dpp v76, v76, v76 quad_perm:[1,0,3,2] row_mask:0xf bank_mask:0xf bound_ctrl:1
	v_pk_fma_f32 v[70:71], v[172:173], v[132:133], v[70:71]
	v_pk_fma_f32 v[72:73], v[170:171], v[132:133], v[72:73]
	v_pk_fma_f32 v[160:161], v[74:75], v[150:151], v[160:161] op_sel_hi:[0,1,1]
	v_add_f32_dpp v76, v76, v76 quad_perm:[2,3,0,1] row_mask:0xf bank_mask:0xf bound_ctrl:1
	v_pk_fma_f32 v[70:71], v[174:175], v[134:135], v[70:71]
	v_pk_fma_f32 v[72:73], v[158:159], v[134:135], v[72:73]
	ds_read_b128 v[84:87], v88 offset:10752
	ds_read_b128 v[90:93], v88 offset:10768
	ds_read_b128 v[94:97], v88 offset:11008
	ds_read_b128 v[98:101], v88 offset:11024
	ds_read_b128 v[106:109], v88 offset:11264
	ds_read_b128 v[110:113], v88 offset:11280
	ds_read_b128 v[120:123], v88 offset:11520
	ds_read_b128 v[124:127], v88 offset:11536
	ds_read_b128 v[128:131], v88 offset:11776
	ds_read_b128 v[132:135], v88 offset:11792
	v_pk_fma_f32 v[180:181], v[172:173], v[16:17], v[160:161]
	v_pk_mul_f32 v[160:161], v[26:27], v[166:167] op_sel_hi:[1,0]
	v_add_f32_dpp v76, v76, v76 row_half_mirror row_mask:0xf bank_mask:0xf bound_ctrl:1
	v_pk_mul_f32 v[20:21], v[20:21], v[166:167] op_sel:[0,1]
	s_waitcnt lgkmcnt(5)
	v_pk_mul_f32 v[78:79], v[106:107], v[102:103]
	v_pk_fma_f32 v[74:75], v[74:75], v[152:153], v[160:161] op_sel_hi:[0,1,1]
	v_pk_fma_f32 v[20:21], v[76:77], v[146:147], v[20:21] op_sel_hi:[0,1,1]
	v_pk_fma_f32 v[78:79], v[114:115], v[108:109], v[78:79]
	v_pk_fma_f32 v[182:183], v[174:175], v[18:19], v[74:75]
	v_pk_fma_f32 v[80:81], v[176:177], v[12:13], v[20:21]
	v_pk_mul_f32 v[12:13], v[22:23], v[166:167] op_sel:[0,1]
	s_waitcnt lgkmcnt(4)
	v_pk_fma_f32 v[78:79], v[180:181], v[110:111], v[78:79]
	v_pk_fma_f32 v[12:13], v[76:77], v[148:149], v[12:13] op_sel_hi:[0,1,1]
	v_pk_fma_f32 v[78:79], v[182:183], v[112:113], v[78:79]
	v_pk_fma_f32 v[82:83], v[178:179], v[14:15], v[12:13]
	v_pk_mul_f32 v[12:13], v[24:25], v[166:167] op_sel:[0,1]
	v_add_f32_e32 v78, v78, v79
	v_pk_fma_f32 v[12:13], v[76:77], v[150:151], v[12:13] op_sel_hi:[0,1,1]
	v_pk_fma_f32 v[178:179], v[170:171], v[16:17], v[12:13]
	v_add_f32_dpp v78, v78, v78 quad_perm:[1,0,3,2] row_mask:0xf bank_mask:0xf bound_ctrl:1
	v_pk_mul_f32 v[12:13], v[26:27], v[166:167] op_sel:[0,1]
	v_pk_mul_f32 v[106:107], v[106:107], v[80:81]
	v_add_f32_dpp v78, v78, v78 quad_perm:[2,3,0,1] row_mask:0xf bank_mask:0xf bound_ctrl:1
	v_pk_fma_f32 v[12:13], v[76:77], v[152:153], v[12:13] op_sel_hi:[0,1,1]
	v_pk_mul_f32 v[184:185], v[94:95], v[168:169] op_sel_hi:[1,0]
	v_add_f32_dpp v78, v78, v78 row_half_mirror row_mask:0xf bank_mask:0xf bound_ctrl:1
	v_pk_fma_f32 v[106:107], v[82:83], v[108:109], v[106:107]
	v_pk_fma_f32 v[166:167], v[158:159], v[18:19], v[12:13]
	s_waitcnt lgkmcnt(3)
	v_pk_fma_f32 v[184:185], v[78:79], v[120:121], v[184:185] op_sel_hi:[0,1,1]
	v_pk_fma_f32 v[106:107], v[178:179], v[110:111], v[106:107]
	v_pk_mul_f32 v[74:75], v[154:155], v[102:103]
	v_pk_fma_f32 v[102:103], v[102:103], v[84:85], v[184:185]
	v_pk_mul_f32 v[184:185], v[96:97], v[168:169] op_sel_hi:[1,0]
	v_pk_fma_f32 v[106:107], v[166:167], v[112:113], v[106:107]
	v_pk_fma_f32 v[184:185], v[78:79], v[122:123], v[184:185] op_sel_hi:[0,1,1]
	v_add_f32_e32 v105, v106, v107
	v_pk_fma_f32 v[74:75], v[114:115], v[156:157], v[74:75]
	v_pk_mul_f32 v[12:13], v[154:155], v[80:81]
	v_pk_fma_f32 v[114:115], v[114:115], v[86:87], v[184:185]
	v_pk_mul_f32 v[184:185], v[98:99], v[168:169] op_sel_hi:[1,0]
	v_add_f32_dpp v105, v105, v105 quad_perm:[1,0,3,2] row_mask:0xf bank_mask:0xf bound_ctrl:1
	v_pk_fma_f32 v[12:13], v[82:83], v[156:157], v[12:13]
	s_waitcnt lgkmcnt(2)
	v_pk_fma_f32 v[184:185], v[78:79], v[124:125], v[184:185] op_sel_hi:[0,1,1]
	v_add_f32_dpp v105, v105, v105 quad_perm:[2,3,0,1] row_mask:0xf bank_mask:0xf bound_ctrl:1
	v_pk_fma_f32 v[74:75], v[180:181], v[162:163], v[74:75]
	v_pk_fma_f32 v[12:13], v[178:179], v[162:163], v[12:13]
	v_pk_fma_f32 v[180:181], v[180:181], v[90:91], v[184:185]
	v_pk_mul_f32 v[184:185], v[100:101], v[168:169] op_sel_hi:[1,0]
	v_add_f32_dpp v106, v105, v105 row_half_mirror row_mask:0xf bank_mask:0xf bound_ctrl:1
	v_pk_mul_f32 v[94:95], v[94:95], v[168:169] op_sel:[0,1]
	v_pk_fma_f32 v[74:75], v[182:183], v[164:165], v[74:75]
	v_pk_fma_f32 v[76:77], v[166:167], v[164:165], v[12:13]
	ds_read_b128 v[12:15], v88 offset:12288
	ds_read_b128 v[16:19], v88 offset:12304
	ds_read_b128 v[20:23], v88 offset:12544
	ds_read_b128 v[24:27], v88 offset:12560
	ds_read_b128 v[146:149], v88 offset:12800
	ds_read_b128 v[150:153], v88 offset:12816
	ds_read_b128 v[154:157], v88 offset:13056
	ds_read_b128 v[158:161], v88 offset:13072
	ds_read_b128 v[162:165], v88 offset:13312
	ds_read_b128 v[170:173], v88 offset:13328
	ds_read2st64_b64 v[174:177], v104 offset0:24 offset1:27
	v_pk_fma_f32 v[78:79], v[78:79], v[126:127], v[184:185] op_sel_hi:[0,1,1]
	v_pk_fma_f32 v[94:95], v[106:107], v[120:121], v[94:95] op_sel_hi:[0,1,1]
	s_waitcnt lgkmcnt(6)
	v_pk_mul_f32 v[184:185], v[146:147], v[102:103]
	v_pk_fma_f32 v[84:85], v[80:81], v[84:85], v[94:95]
	v_pk_mul_f32 v[80:81], v[96:97], v[168:169] op_sel:[0,1]
	v_pk_fma_f32 v[184:185], v[114:115], v[148:149], v[184:185]
	v_pk_fma_f32 v[182:183], v[182:183], v[92:93], v[78:79]
	v_pk_fma_f32 v[80:81], v[106:107], v[122:123], v[80:81] op_sel_hi:[0,1,1]
	s_waitcnt lgkmcnt(5)
	v_pk_fma_f32 v[184:185], v[180:181], v[150:151], v[184:185]
	v_pk_fma_f32 v[82:83], v[82:83], v[86:87], v[80:81]
	v_pk_mul_f32 v[80:81], v[98:99], v[168:169] op_sel:[0,1]
	v_pk_fma_f32 v[184:185], v[182:183], v[152:153], v[184:185]
	v_pk_fma_f32 v[80:81], v[106:107], v[124:125], v[80:81] op_sel_hi:[0,1,1]
	v_add_f32_e32 v105, v184, v185
	v_pk_fma_f32 v[86:87], v[178:179], v[90:91], v[80:81]
	v_pk_mul_f32 v[80:81], v[100:101], v[168:169] op_sel:[0,1]
	v_add_f32_dpp v105, v105, v105 quad_perm:[1,0,3,2] row_mask:0xf bank_mask:0xf bound_ctrl:1
	v_pk_mul_f32 v[146:147], v[146:147], v[84:85]
	v_pk_fma_f32 v[80:81], v[106:107], v[126:127], v[80:81] op_sel_hi:[0,1,1]
	v_add_f32_dpp v105, v105, v105 quad_perm:[2,3,0,1] row_mask:0xf bank_mask:0xf bound_ctrl:1
	v_pk_fma_f32 v[146:147], v[82:83], v[148:149], v[146:147]
	v_pk_fma_f32 v[178:179], v[166:167], v[92:93], v[80:81]
	v_add_f32_dpp v184, v105, v105 row_half_mirror row_mask:0xf bank_mask:0xf bound_ctrl:1
	s_waitcnt lgkmcnt(0)
	v_pk_mul_f32 v[186:187], v[20:21], v[174:175] op_sel_hi:[1,0]
	v_pk_fma_f32 v[146:147], v[86:87], v[150:151], v[146:147]
	v_pk_fma_f32 v[186:187], v[184:185], v[154:155], v[186:187] op_sel_hi:[0,1,1]
	v_pk_fma_f32 v[146:147], v[178:179], v[152:153], v[146:147]
	v_pk_mul_f32 v[78:79], v[128:129], v[102:103]
	v_pk_fma_f32 v[102:103], v[102:103], v[12:13], v[186:187]
	v_pk_mul_f32 v[186:187], v[22:23], v[174:175] op_sel_hi:[1,0]
	v_add_f32_e32 v105, v146, v147
	v_pk_mul_f32 v[80:81], v[128:129], v[84:85]
	v_pk_fma_f32 v[186:187], v[184:185], v[156:157], v[186:187] op_sel_hi:[0,1,1]
	v_add_f32_dpp v105, v105, v105 quad_perm:[1,0,3,2] row_mask:0xf bank_mask:0xf bound_ctrl:1
	v_pk_fma_f32 v[78:79], v[114:115], v[130:131], v[78:79]
	v_pk_fma_f32 v[80:81], v[82:83], v[130:131], v[80:81]
	v_pk_fma_f32 v[114:115], v[114:115], v[14:15], v[186:187]
	v_pk_mul_f32 v[186:187], v[24:25], v[174:175] op_sel_hi:[1,0]
	v_add_f32_dpp v105, v105, v105 quad_perm:[2,3,0,1] row_mask:0xf bank_mask:0xf bound_ctrl:1
	v_pk_fma_f32 v[78:79], v[180:181], v[132:133], v[78:79]
	v_pk_fma_f32 v[80:81], v[86:87], v[132:133], v[80:81]
	v_pk_fma_f32 v[186:187], v[184:185], v[158:159], v[186:187] op_sel_hi:[0,1,1]
	v_add_f32_dpp v146, v105, v105 row_half_mirror row_mask:0xf bank_mask:0xf bound_ctrl:1
	v_pk_mul_f32 v[20:21], v[20:21], v[174:175] op_sel:[0,1]
	v_pk_fma_f32 v[78:79], v[182:183], v[134:135], v[78:79]
	v_pk_fma_f32 v[80:81], v[178:179], v[134:135], v[80:81]
	ds_read_b128 v[90:93], v88 offset:13824
	ds_read_b128 v[94:97], v88 offset:13840
	ds_read_b128 v[98:101], v88 offset:14080
	ds_read_b128 v[106:109], v88 offset:14096
	ds_read_b128 v[110:113], v88 offset:14336
	ds_read_b128 v[120:123], v88 offset:14352
	ds_read_b128 v[124:127], v88 offset:14592
	ds_read_b128 v[128:131], v88 offset:14608
	ds_read_b128 v[132:135], v88 offset:14848
	ds_read_b128 v[166:169], v88 offset:14864
	v_pk_fma_f32 v[186:187], v[180:181], v[16:17], v[186:187]
	v_pk_mul_f32 v[180:181], v[26:27], v[174:175] op_sel_hi:[1,0]
	v_pk_fma_f32 v[20:21], v[146:147], v[154:155], v[20:21] op_sel_hi:[0,1,1]
	s_waitcnt lgkmcnt(5)
	v_pk_mul_f32 v[190:191], v[110:111], v[102:103]
	v_pk_fma_f32 v[180:181], v[184:185], v[160:161], v[180:181] op_sel_hi:[0,1,1]
	v_pk_fma_f32 v[184:185], v[84:85], v[12:13], v[20:21]
	v_pk_mul_f32 v[12:13], v[22:23], v[174:175] op_sel:[0,1]
	v_pk_fma_f32 v[190:191], v[114:115], v[112:113], v[190:191]
	v_pk_fma_f32 v[182:183], v[182:183], v[18:19], v[180:181]
	v_pk_fma_f32 v[12:13], v[146:147], v[156:157], v[12:13] op_sel_hi:[0,1,1]
	s_waitcnt lgkmcnt(4)
	v_pk_fma_f32 v[190:191], v[186:187], v[120:121], v[190:191]
	v_pk_fma_f32 v[188:189], v[82:83], v[14:15], v[12:13]
	v_pk_mul_f32 v[12:13], v[24:25], v[174:175] op_sel:[0,1]
	v_pk_fma_f32 v[190:191], v[182:183], v[122:123], v[190:191]
	v_pk_fma_f32 v[12:13], v[146:147], v[158:159], v[12:13] op_sel_hi:[0,1,1]
	v_add_f32_e32 v105, v190, v191
	v_pk_fma_f32 v[86:87], v[86:87], v[16:17], v[12:13]
	v_pk_mul_f32 v[12:13], v[26:27], v[174:175] op_sel:[0,1]
	v_add_f32_dpp v105, v105, v105 quad_perm:[1,0,3,2] row_mask:0xf bank_mask:0xf bound_ctrl:1
	v_pk_mul_f32 v[110:111], v[110:111], v[184:185]
	v_pk_fma_f32 v[12:13], v[146:147], v[160:161], v[12:13] op_sel_hi:[0,1,1]
	v_add_f32_dpp v105, v105, v105 quad_perm:[2,3,0,1] row_mask:0xf bank_mask:0xf bound_ctrl:1
	v_pk_fma_f32 v[110:111], v[188:189], v[112:113], v[110:111]
	v_pk_fma_f32 v[174:175], v[178:179], v[18:19], v[12:13]
	v_add_f32_dpp v190, v105, v105 row_half_mirror row_mask:0xf bank_mask:0xf bound_ctrl:1
	v_pk_mul_f32 v[192:193], v[98:99], v[176:177] op_sel_hi:[1,0]
	v_pk_fma_f32 v[110:111], v[86:87], v[120:121], v[110:111]
	s_waitcnt lgkmcnt(3)
	v_pk_fma_f32 v[192:193], v[190:191], v[124:125], v[192:193] op_sel_hi:[0,1,1]
	v_pk_fma_f32 v[110:111], v[174:175], v[122:123], v[110:111]
	v_pk_mul_f32 v[180:181], v[162:163], v[102:103]
	v_pk_fma_f32 v[102:103], v[102:103], v[90:91], v[192:193]
	v_pk_mul_f32 v[192:193], v[100:101], v[176:177] op_sel_hi:[1,0]
	v_add_f32_e32 v105, v110, v111
	v_pk_mul_f32 v[12:13], v[162:163], v[184:185]
	v_pk_fma_f32 v[192:193], v[190:191], v[126:127], v[192:193] op_sel_hi:[0,1,1]
	v_add_f32_dpp v105, v105, v105 quad_perm:[1,0,3,2] row_mask:0xf bank_mask:0xf bound_ctrl:1
	v_pk_fma_f32 v[180:181], v[114:115], v[164:165], v[180:181]
	v_pk_fma_f32 v[12:13], v[188:189], v[164:165], v[12:13]
	v_pk_fma_f32 v[114:115], v[114:115], v[92:93], v[192:193]
	v_pk_mul_f32 v[192:193], v[106:107], v[176:177] op_sel_hi:[1,0]
	v_add_f32_dpp v105, v105, v105 quad_perm:[2,3,0,1] row_mask:0xf bank_mask:0xf bound_ctrl:1
	v_pk_fma_f32 v[180:181], v[186:187], v[170:171], v[180:181]
	v_pk_fma_f32 v[12:13], v[86:87], v[170:171], v[12:13]
	s_waitcnt lgkmcnt(2)
	v_pk_fma_f32 v[192:193], v[190:191], v[128:129], v[192:193] op_sel_hi:[0,1,1]
	v_add_f32_dpp v110, v105, v105 row_half_mirror row_mask:0xf bank_mask:0xf bound_ctrl:1
	v_pk_mul_f32 v[98:99], v[98:99], v[176:177] op_sel:[0,1]
	v_pk_fma_f32 v[180:181], v[182:183], v[172:173], v[180:181]
	v_pk_fma_f32 v[12:13], v[174:175], v[172:173], v[12:13]
	v_pk_fma_f32 v[186:187], v[186:187], v[94:95], v[192:193]
	v_pk_mul_f32 v[192:193], v[108:109], v[176:177] op_sel_hi:[1,0]
	v_pk_fma_f32 v[98:99], v[110:111], v[124:125], v[98:99] op_sel_hi:[0,1,1]
	v_add_f32_e32 v226, v180, v181
	v_add_f32_e32 v234, v12, v13
	v_pk_fma_f32 v[190:191], v[190:191], v[130:131], v[192:193] op_sel_hi:[0,1,1]
	v_pk_fma_f32 v[192:193], v[184:185], v[90:91], v[98:99]
	v_pk_mul_f32 v[90:91], v[100:101], v[176:177] op_sel:[0,1]
	v_pk_fma_f32 v[90:91], v[110:111], v[126:127], v[90:91] op_sel_hi:[0,1,1]
	v_pk_fma_f32 v[188:189], v[188:189], v[92:93], v[90:91]
	v_pk_mul_f32 v[90:91], v[106:107], v[176:177] op_sel:[0,1]
	ds_read_b128 v[12:15], v88 offset:15360
	ds_read_b128 v[16:19], v88 offset:15376
	ds_read_b128 v[20:23], v88 offset:15616
	ds_read_b128 v[24:27], v88 offset:15632
	ds_read_b128 v[146:149], v88 offset:15872
	ds_read_b128 v[150:153], v88 offset:15888
	ds_read_b128 v[154:157], v88 offset:16128
	ds_read_b128 v[158:161], v88 offset:16144
	ds_read_b128 v[162:165], v88 offset:16384
	ds_read_b128 v[170:173], v88 offset:16400
	ds_read2st64_b64 v[178:181], v104 offset0:30 offset1:33
	v_pk_fma_f32 v[90:91], v[110:111], v[128:129], v[90:91] op_sel_hi:[0,1,1]
	v_pk_fma_f32 v[94:95], v[86:87], v[94:95], v[90:91]
	v_pk_mul_f32 v[86:87], v[108:109], v[176:177] op_sel:[0,1]
	s_waitcnt lgkmcnt(6)
	v_pk_mul_f32 v[92:93], v[146:147], v[102:103]
	v_pk_mul_f32 v[146:147], v[146:147], v[192:193]
	v_pk_fma_f32 v[86:87], v[110:111], v[130:131], v[86:87] op_sel_hi:[0,1,1]
	v_pk_fma_f32 v[92:93], v[114:115], v[148:149], v[92:93]
	v_pk_fma_f32 v[146:147], v[188:189], v[148:149], v[146:147]
	v_pk_fma_f32 v[190:191], v[182:183], v[96:97], v[190:191]
	v_pk_fma_f32 v[96:97], v[174:175], v[96:97], v[86:87]
	s_waitcnt lgkmcnt(5)
	v_pk_fma_f32 v[92:93], v[186:187], v[150:151], v[92:93]
	v_pk_fma_f32 v[146:147], v[94:95], v[150:151], v[146:147]
	v_pk_fma_f32 v[92:93], v[190:191], v[152:153], v[92:93]
	v_pk_fma_f32 v[146:147], v[96:97], v[152:153], v[146:147]
	v_add_f32_e32 v92, v92, v93
	v_add_f32_e32 v105, v146, v147
	s_waitcnt lgkmcnt(0)
	v_pk_mul_f32 v[194:195], v[20:21], v[178:179] op_sel_hi:[1,0]
	v_add_f32_dpp v92, v92, v92 quad_perm:[1,0,3,2] row_mask:0xf bank_mask:0xf bound_ctrl:1
	v_add_f32_dpp v105, v105, v105 quad_perm:[1,0,3,2] row_mask:0xf bank_mask:0xf bound_ctrl:1
	v_pk_mul_f32 v[20:21], v[20:21], v[178:179] op_sel:[0,1]
	v_add_f32_dpp v92, v92, v92 quad_perm:[2,3,0,1] row_mask:0xf bank_mask:0xf bound_ctrl:1
	v_add_f32_dpp v105, v105, v105 quad_perm:[2,3,0,1] row_mask:0xf bank_mask:0xf bound_ctrl:1
	v_pk_mul_f32 v[182:183], v[132:133], v[102:103]
	v_add_f32_dpp v92, v92, v92 row_half_mirror row_mask:0xf bank_mask:0xf bound_ctrl:1
	v_add_f32_dpp v146, v105, v105 row_half_mirror row_mask:0xf bank_mask:0xf bound_ctrl:1
	v_pk_fma_f32 v[194:195], v[92:93], v[154:155], v[194:195] op_sel_hi:[0,1,1]
	v_pk_fma_f32 v[20:21], v[146:147], v[154:155], v[20:21] op_sel_hi:[0,1,1]
	v_pk_mul_f32 v[86:87], v[132:133], v[192:193]
	v_pk_fma_f32 v[102:103], v[102:103], v[12:13], v[194:195]
	v_pk_fma_f32 v[192:193], v[192:193], v[12:13], v[20:21]
	v_pk_mul_f32 v[12:13], v[22:23], v[178:179] op_sel:[0,1]
	v_pk_mul_f32 v[194:195], v[22:23], v[178:179] op_sel_hi:[1,0]
	v_pk_fma_f32 v[12:13], v[146:147], v[156:157], v[12:13] op_sel_hi:[0,1,1]
	v_pk_fma_f32 v[196:197], v[188:189], v[14:15], v[12:13]
	v_pk_mul_f32 v[12:13], v[24:25], v[178:179] op_sel:[0,1]
	v_pk_fma_f32 v[182:183], v[114:115], v[134:135], v[182:183]
	v_pk_fma_f32 v[86:87], v[188:189], v[134:135], v[86:87]
	v_pk_fma_f32 v[194:195], v[92:93], v[156:157], v[194:195] op_sel_hi:[0,1,1]
	v_pk_fma_f32 v[12:13], v[146:147], v[158:159], v[12:13] op_sel_hi:[0,1,1]
	v_pk_fma_f32 v[182:183], v[186:187], v[166:167], v[182:183]
	v_pk_fma_f32 v[86:87], v[94:95], v[166:167], v[86:87]
	v_pk_fma_f32 v[114:115], v[114:115], v[14:15], v[194:195]
	v_pk_mul_f32 v[194:195], v[24:25], v[178:179] op_sel_hi:[1,0]
	v_pk_fma_f32 v[198:199], v[94:95], v[16:17], v[12:13]
	v_pk_mul_f32 v[12:13], v[26:27], v[178:179] op_sel:[0,1]
	v_pk_fma_f32 v[182:183], v[190:191], v[168:169], v[182:183]
	v_pk_fma_f32 v[86:87], v[96:97], v[168:169], v[86:87]
	v_pk_fma_f32 v[194:195], v[92:93], v[158:159], v[194:195] op_sel_hi:[0,1,1]
	v_pk_fma_f32 v[12:13], v[146:147], v[160:161], v[12:13] op_sel_hi:[0,1,1]
	v_add_f32_e32 v227, v182, v183
	v_add_f32_e32 v235, v86, v87
	ds_read_b128 v[98:101], v88 offset:16896
	ds_read_b128 v[106:109], v88 offset:16912
	ds_read_b128 v[110:113], v88 offset:17152
	ds_read_b128 v[120:123], v88 offset:17168
	ds_read_b128 v[124:127], v88 offset:17408
	ds_read_b128 v[128:131], v88 offset:17424
	ds_read_b128 v[132:135], v88 offset:17664
	ds_read_b128 v[166:169], v88 offset:17680
	ds_read_b128 v[174:177], v88 offset:17920
	ds_read_b128 v[182:185], v88 offset:17936
	v_pk_fma_f32 v[194:195], v[186:187], v[16:17], v[194:195]
	v_pk_mul_f32 v[186:187], v[26:27], v[178:179] op_sel_hi:[1,0]
	v_pk_fma_f32 v[178:179], v[96:97], v[18:19], v[12:13]
	s_waitcnt lgkmcnt(5)
	v_pk_mul_f32 v[96:97], v[124:125], v[102:103]
	v_pk_fma_f32 v[92:93], v[92:93], v[160:161], v[186:187] op_sel_hi:[0,1,1]
	v_pk_fma_f32 v[96:97], v[114:115], v[126:127], v[96:97]
	v_pk_fma_f32 v[190:191], v[190:191], v[18:19], v[92:93]
	s_waitcnt lgkmcnt(4)
	v_pk_fma_f32 v[96:97], v[194:195], v[128:129], v[96:97]
	v_pk_mul_f32 v[124:125], v[124:125], v[192:193]
	v_pk_fma_f32 v[96:97], v[190:191], v[130:131], v[96:97]
	v_pk_fma_f32 v[124:125], v[196:197], v[126:127], v[124:125]
	v_add_f32_e32 v96, v96, v97
	v_pk_fma_f32 v[124:125], v[198:199], v[128:129], v[124:125]
	v_pk_mul_f32 v[200:201], v[110:111], v[180:181] op_sel_hi:[1,0]
	v_add_f32_dpp v96, v96, v96 quad_perm:[1,0,3,2] row_mask:0xf bank_mask:0xf bound_ctrl:1
	v_pk_fma_f32 v[124:125], v[178:179], v[130:131], v[124:125]
	v_pk_mul_f32 v[92:93], v[162:163], v[102:103]
	v_add_f32_dpp v96, v96, v96 quad_perm:[2,3,0,1] row_mask:0xf bank_mask:0xf bound_ctrl:1
	v_add_f32_e32 v105, v124, v125
	v_pk_mul_f32 v[110:111], v[110:111], v[180:181] op_sel:[0,1]
	v_add_f32_dpp v96, v96, v96 row_half_mirror row_mask:0xf bank_mask:0xf bound_ctrl:1
	v_add_f32_dpp v105, v105, v105 quad_perm:[1,0,3,2] row_mask:0xf bank_mask:0xf bound_ctrl:1
	s_waitcnt lgkmcnt(3)
	v_pk_fma_f32 v[200:201], v[96:97], v[132:133], v[200:201] op_sel_hi:[0,1,1]
	v_pk_fma_f32 v[102:103], v[102:103], v[98:99], v[200:201]
	v_add_f32_dpp v105, v105, v105 quad_perm:[2,3,0,1] row_mask:0xf bank_mask:0xf bound_ctrl:1
	v_pk_mul_f32 v[200:201], v[112:113], v[180:181] op_sel_hi:[1,0]
	v_pk_mul_f32 v[12:13], v[162:163], v[192:193]
	v_add_f32_dpp v124, v105, v105 row_half_mirror row_mask:0xf bank_mask:0xf bound_ctrl:1
	v_pk_fma_f32 v[200:201], v[96:97], v[134:135], v[200:201] op_sel_hi:[0,1,1]
	v_pk_fma_f32 v[110:111], v[124:125], v[132:133], v[110:111] op_sel_hi:[0,1,1]
	v_pk_fma_f32 v[92:93], v[114:115], v[164:165], v[92:93]
	v_pk_fma_f32 v[12:13], v[196:197], v[164:165], v[12:13]
	v_pk_fma_f32 v[114:115], v[114:115], v[100:101], v[200:201]
	v_pk_mul_f32 v[200:201], v[120:121], v[180:181] op_sel_hi:[1,0]
	v_pk_fma_f32 v[192:193], v[192:193], v[98:99], v[110:111]
	v_pk_mul_f32 v[98:99], v[112:113], v[180:181] op_sel:[0,1]
	v_pk_fma_f32 v[92:93], v[194:195], v[170:171], v[92:93]
	v_pk_fma_f32 v[12:13], v[198:199], v[170:171], v[12:13]
	s_waitcnt lgkmcnt(2)
	v_pk_fma_f32 v[200:201], v[96:97], v[166:167], v[200:201] op_sel_hi:[0,1,1]
	v_pk_fma_f32 v[98:99], v[124:125], v[134:135], v[98:99] op_sel_hi:[0,1,1]
	v_pk_fma_f32 v[92:93], v[190:191], v[172:173], v[92:93]
	v_pk_fma_f32 v[94:95], v[178:179], v[172:173], v[12:13]
	ds_read_b128 v[12:15], v88 offset:18432
	ds_read_b128 v[16:19], v88 offset:18448
	ds_read_b128 v[20:23], v88 offset:18688
	ds_read_b128 v[24:27], v88 offset:18704
	ds_read_b128 v[146:149], v88 offset:18944
	ds_read_b128 v[150:153], v88 offset:18960
	ds_read_b128 v[154:157], v88 offset:19200
	ds_read_b128 v[158:161], v88 offset:19216
	ds_read_b128 v[162:165], v88 offset:19456
	ds_read_b128 v[170:173], v88 offset:19472
	ds_read2st64_b64 v[186:189], v104 offset0:36 offset1:39
	v_pk_fma_f32 v[194:195], v[194:195], v[106:107], v[200:201]
	v_pk_mul_f32 v[200:201], v[122:123], v[180:181] op_sel_hi:[1,0]
	v_pk_fma_f32 v[196:197], v[196:197], v[100:101], v[98:99]
	s_waitcnt lgkmcnt(6)
	v_pk_mul_f32 v[100:101], v[146:147], v[102:103]
	v_pk_fma_f32 v[96:97], v[96:97], v[168:169], v[200:201] op_sel_hi:[0,1,1]
	v_pk_fma_f32 v[100:101], v[114:115], v[148:149], v[100:101]
	v_pk_fma_f32 v[190:191], v[190:191], v[108:109], v[96:97]
	s_waitcnt lgkmcnt(5)
	v_pk_fma_f32 v[100:101], v[194:195], v[150:151], v[100:101]
	s_waitcnt lgkmcnt(0)
	v_pk_mul_f32 v[202:203], v[20:21], v[186:187] op_sel_hi:[1,0]
	v_pk_fma_f32 v[100:101], v[190:191], v[152:153], v[100:101]
	v_pk_mul_f32 v[96:97], v[174:175], v[102:103]
	v_add_f32_e32 v100, v100, v101
	v_pk_fma_f32 v[96:97], v[114:115], v[176:177], v[96:97]
	v_pk_mul_f32 v[98:99], v[120:121], v[180:181] op_sel:[0,1]
	v_add_f32_dpp v100, v100, v100 quad_perm:[1,0,3,2] row_mask:0xf bank_mask:0xf bound_ctrl:1
	v_pk_fma_f32 v[96:97], v[194:195], v[182:183], v[96:97]
	v_pk_fma_f32 v[98:99], v[124:125], v[166:167], v[98:99] op_sel_hi:[0,1,1]
	v_add_f32_dpp v100, v100, v100 quad_perm:[2,3,0,1] row_mask:0xf bank_mask:0xf bound_ctrl:1
	v_pk_fma_f32 v[198:199], v[198:199], v[106:107], v[98:99]
	v_pk_mul_f32 v[98:99], v[122:123], v[180:181] op_sel:[0,1]
	v_add_f32_dpp v100, v100, v100 row_half_mirror row_mask:0xf bank_mask:0xf bound_ctrl:1
	v_pk_fma_f32 v[202:203], v[100:101], v[154:155], v[202:203] op_sel_hi:[0,1,1]
	v_pk_fma_f32 v[202:203], v[102:103], v[12:13], v[202:203]
	v_pk_mul_f32 v[102:103], v[22:23], v[186:187] op_sel_hi:[1,0]
	v_pk_fma_f32 v[98:99], v[124:125], v[168:169], v[98:99] op_sel_hi:[0,1,1]
	v_pk_fma_f32 v[102:103], v[100:101], v[156:157], v[102:103] op_sel_hi:[0,1,1]
	v_pk_fma_f32 v[114:115], v[114:115], v[14:15], v[102:103]
	v_pk_mul_f32 v[102:103], v[24:25], v[186:187] op_sel_hi:[1,0]
	v_pk_fma_f32 v[200:201], v[178:179], v[108:109], v[98:99]
	v_pk_fma_f32 v[102:103], v[100:101], v[158:159], v[102:103] op_sel_hi:[0,1,1]
	v_pk_fma_f32 v[194:195], v[194:195], v[16:17], v[102:103]
	v_pk_mul_f32 v[102:103], v[26:27], v[186:187] op_sel_hi:[1,0]
	v_pk_mul_f32 v[20:21], v[20:21], v[186:187] op_sel:[0,1]
	v_pk_fma_f32 v[100:101], v[100:101], v[160:161], v[102:103] op_sel_hi:[0,1,1]
	v_pk_mul_f32 v[102:103], v[146:147], v[192:193]
	v_pk_mul_f32 v[98:99], v[174:175], v[192:193]
	v_pk_fma_f32 v[102:103], v[196:197], v[148:149], v[102:103]
	v_pk_fma_f32 v[98:99], v[196:197], v[176:177], v[98:99]
	v_pk_fma_f32 v[102:103], v[198:199], v[150:151], v[102:103]
	v_pk_fma_f32 v[98:99], v[198:199], v[182:183], v[98:99]
	v_pk_fma_f32 v[102:103], v[200:201], v[152:153], v[102:103]
	v_pk_fma_f32 v[204:205], v[190:191], v[18:19], v[100:101]
	v_add_f32_e32 v102, v102, v103
	v_pk_mul_f32 v[100:101], v[162:163], v[202:203]
	v_pk_fma_f32 v[96:97], v[190:191], v[184:185], v[96:97]
	v_add_f32_dpp v102, v102, v102 quad_perm:[1,0,3,2] row_mask:0xf bank_mask:0xf bound_ctrl:1
	v_pk_fma_f32 v[100:101], v[114:115], v[164:165], v[100:101]
	v_pk_fma_f32 v[98:99], v[200:201], v[184:185], v[98:99]
	v_add_f32_dpp v102, v102, v102 quad_perm:[2,3,0,1] row_mask:0xf bank_mask:0xf bound_ctrl:1
	ds_read_b128 v[106:109], v88 offset:19968
	ds_read_b128 v[110:113], v88 offset:19984
	ds_read_b128 v[120:123], v88 offset:20224
	ds_read_b128 v[124:127], v88 offset:20240
	ds_read_b128 v[128:131], v88 offset:20480
	ds_read_b128 v[132:135], v88 offset:20496
	ds_read_b128 v[166:169], v88 offset:20736
	ds_read_b128 v[174:177], v88 offset:20752
	ds_read_b128 v[178:181], v88 offset:20992
	ds_read_b128 v[182:185], v88 offset:21008
	v_add_f32_dpp v102, v102, v102 row_half_mirror row_mask:0xf bank_mask:0xf bound_ctrl:1
	v_pk_fma_f32 v[20:21], v[102:103], v[154:155], v[20:21] op_sel_hi:[0,1,1]
	v_pk_fma_f32 v[206:207], v[192:193], v[12:13], v[20:21]
	v_pk_mul_f32 v[12:13], v[22:23], v[186:187] op_sel:[0,1]
	v_pk_fma_f32 v[100:101], v[194:195], v[170:171], v[100:101]
	v_pk_fma_f32 v[12:13], v[102:103], v[156:157], v[12:13] op_sel_hi:[0,1,1]
	v_pk_fma_f32 v[196:197], v[196:197], v[14:15], v[12:13]
	v_pk_mul_f32 v[12:13], v[24:25], v[186:187] op_sel:[0,1]
	v_pk_fma_f32 v[100:101], v[204:205], v[172:173], v[100:101]
	v_pk_fma_f32 v[12:13], v[102:103], v[158:159], v[12:13] op_sel_hi:[0,1,1]
	v_pk_fma_f32 v[198:199], v[198:199], v[16:17], v[12:13]
	v_pk_mul_f32 v[12:13], v[26:27], v[186:187] op_sel:[0,1]
	v_pk_fma_f32 v[12:13], v[102:103], v[160:161], v[12:13] op_sel_hi:[0,1,1]
	v_pk_fma_f32 v[186:187], v[200:201], v[18:19], v[12:13]
	v_pk_mul_f32 v[12:13], v[162:163], v[206:207]
	s_waitcnt lgkmcnt(7)
	v_pk_mul_f32 v[200:201], v[120:121], v[188:189] op_sel_hi:[1,0]
	v_pk_fma_f32 v[12:13], v[196:197], v[164:165], v[12:13]
	v_pk_mul_f32 v[120:121], v[120:121], v[188:189] op_sel:[0,1]
	v_pk_fma_f32 v[12:13], v[198:199], v[170:171], v[12:13]
	v_pk_fma_f32 v[102:103], v[186:187], v[172:173], v[12:13]
	ds_read_b128 v[12:15], v88 offset:21504
	ds_read_b128 v[16:19], v88 offset:21520
	ds_read_b128 v[20:23], v88 offset:21760
	ds_read_b128 v[24:27], v88 offset:21776
	ds_read_b128 v[146:149], v88 offset:22016
	ds_read_b128 v[150:153], v88 offset:22032
	ds_read_b128 v[154:157], v88 offset:22272
	ds_read_b128 v[158:161], v88 offset:22288
	ds_read_b128 v[162:165], v88 offset:22528
	ds_read_b128 v[170:173], v88 offset:22544
	ds_read2st64_b64 v[190:193], v104 offset0:42 offset1:45
	s_waitcnt lgkmcnt(14)
	v_pk_mul_f32 v[104:105], v[128:129], v[202:203]
	v_pk_mul_f32 v[128:129], v[128:129], v[206:207]
	v_pk_fma_f32 v[104:105], v[114:115], v[130:131], v[104:105]
	v_pk_fma_f32 v[128:129], v[196:197], v[130:131], v[128:129]
	v_pk_fma_f32 v[104:105], v[194:195], v[132:133], v[104:105]
	v_pk_fma_f32 v[128:129], v[198:199], v[132:133], v[128:129]
	v_pk_fma_f32 v[104:105], v[204:205], v[134:135], v[104:105]
	v_pk_fma_f32 v[128:129], v[186:187], v[134:135], v[128:129]
	v_add_f32_e32 v104, v104, v105
	v_add_f32_e32 v128, v128, v129
	s_nop 0
	v_add_f32_dpp v104, v104, v104 quad_perm:[1,0,3,2] row_mask:0xf bank_mask:0xf bound_ctrl:1
	v_add_f32_dpp v128, v128, v128 quad_perm:[1,0,3,2] row_mask:0xf bank_mask:0xf bound_ctrl:1
	s_nop 0
	v_add_f32_dpp v104, v104, v104 quad_perm:[2,3,0,1] row_mask:0xf bank_mask:0xf bound_ctrl:1
	v_add_f32_dpp v128, v128, v128 quad_perm:[2,3,0,1] row_mask:0xf bank_mask:0xf bound_ctrl:1
	s_nop 0
	v_add_f32_dpp v104, v104, v104 row_half_mirror row_mask:0xf bank_mask:0xf bound_ctrl:1
	v_add_f32_dpp v128, v128, v128 row_half_mirror row_mask:0xf bank_mask:0xf bound_ctrl:1
	v_pk_fma_f32 v[200:201], v[104:105], v[166:167], v[200:201] op_sel_hi:[0,1,1]
	v_pk_fma_f32 v[120:121], v[128:129], v[166:167], v[120:121] op_sel_hi:[0,1,1]
	v_pk_fma_f32 v[200:201], v[202:203], v[106:107], v[200:201]
	v_pk_mul_f32 v[202:203], v[122:123], v[188:189] op_sel_hi:[1,0]
	v_pk_fma_f32 v[206:207], v[206:207], v[106:107], v[120:121]
	v_pk_mul_f32 v[106:107], v[122:123], v[188:189] op_sel:[0,1]
	v_pk_fma_f32 v[202:203], v[104:105], v[168:169], v[202:203] op_sel_hi:[0,1,1]
	v_pk_fma_f32 v[106:107], v[128:129], v[168:169], v[106:107] op_sel_hi:[0,1,1]
	v_pk_fma_f32 v[114:115], v[114:115], v[108:109], v[202:203]
	v_pk_mul_f32 v[202:203], v[124:125], v[188:189] op_sel_hi:[1,0]
	v_pk_fma_f32 v[208:209], v[196:197], v[108:109], v[106:107]
	v_pk_mul_f32 v[106:107], v[124:125], v[188:189] op_sel:[0,1]
	s_waitcnt lgkmcnt(13)
	v_pk_fma_f32 v[202:203], v[104:105], v[174:175], v[202:203] op_sel_hi:[0,1,1]
	v_pk_fma_f32 v[106:107], v[128:129], v[174:175], v[106:107] op_sel_hi:[0,1,1]
	v_pk_fma_f32 v[202:203], v[194:195], v[110:111], v[202:203]
	v_pk_mul_f32 v[194:195], v[126:127], v[188:189] op_sel_hi:[1,0]
	v_pk_fma_f32 v[110:111], v[198:199], v[110:111], v[106:107]
	v_pk_mul_f32 v[106:107], v[126:127], v[188:189] op_sel:[0,1]
	v_pk_fma_f32 v[104:105], v[104:105], v[176:177], v[194:195] op_sel_hi:[0,1,1]
	v_pk_fma_f32 v[106:107], v[128:129], v[176:177], v[106:107] op_sel_hi:[0,1,1]
	s_waitcnt lgkmcnt(6)
	v_pk_mul_f32 v[108:109], v[146:147], v[200:201]
	v_pk_fma_f32 v[204:205], v[204:205], v[112:113], v[104:105]
	v_pk_mul_f32 v[104:105], v[178:179], v[200:201]
	v_pk_fma_f32 v[112:113], v[186:187], v[112:113], v[106:107]
	v_pk_mul_f32 v[106:107], v[178:179], v[206:207]
	v_pk_fma_f32 v[108:109], v[114:115], v[148:149], v[108:109]
	v_pk_fma_f32 v[104:105], v[114:115], v[180:181], v[104:105]
	v_pk_fma_f32 v[106:107], v[208:209], v[180:181], v[106:107]
	s_waitcnt lgkmcnt(5)
	v_pk_fma_f32 v[108:109], v[202:203], v[150:151], v[108:109]
	v_pk_fma_f32 v[104:105], v[202:203], v[182:183], v[104:105]
	v_pk_fma_f32 v[106:107], v[110:111], v[182:183], v[106:107]
	v_pk_fma_f32 v[108:109], v[204:205], v[152:153], v[108:109]
	v_pk_fma_f32 v[104:105], v[204:205], v[184:185], v[104:105]
	v_pk_fma_f32 v[106:107], v[112:113], v[184:185], v[106:107]
	ds_read_b128 v[120:123], v88 offset:23040
	ds_read_b128 v[124:127], v88 offset:23056
	ds_read_b128 v[128:131], v88 offset:23296
	ds_read_b128 v[132:135], v88 offset:23312
	ds_read_b128 v[166:169], v88 offset:23552
	ds_read_b128 v[174:177], v88 offset:23568
	ds_read_b128 v[178:181], v88 offset:23808
	ds_read_b128 v[182:185], v88 offset:23824
	ds_read_b128 v[186:189], v88 offset:24064
	ds_read_b128 v[194:197], v88 offset:24080
	v_add_f32_e32 v88, v108, v109
	s_waitcnt lgkmcnt(10)
	v_pk_mul_f32 v[108:109], v[20:21], v[190:191] op_sel_hi:[1,0]
	v_pk_mul_f32 v[146:147], v[146:147], v[206:207]
	v_add_f32_dpp v88, v88, v88 quad_perm:[1,0,3,2] row_mask:0xf bank_mask:0xf bound_ctrl:1
	v_pk_fma_f32 v[146:147], v[208:209], v[148:149], v[146:147]
	v_pk_mul_f32 v[20:21], v[20:21], v[190:191] op_sel:[0,1]
	v_add_f32_dpp v88, v88, v88 quad_perm:[2,3,0,1] row_mask:0xf bank_mask:0xf bound_ctrl:1
	v_pk_fma_f32 v[146:147], v[110:111], v[150:151], v[146:147]
	s_nop 0
	v_add_f32_dpp v88, v88, v88 row_half_mirror row_mask:0xf bank_mask:0xf bound_ctrl:1
	v_pk_fma_f32 v[108:109], v[88:89], v[154:155], v[108:109] op_sel_hi:[0,1,1]
	v_pk_fma_f32 v[198:199], v[200:201], v[12:13], v[108:109]
	v_pk_mul_f32 v[108:109], v[22:23], v[190:191] op_sel_hi:[1,0]
	v_pk_fma_f32 v[146:147], v[112:113], v[152:153], v[146:147]
	v_pk_fma_f32 v[108:109], v[88:89], v[156:157], v[108:109] op_sel_hi:[0,1,1]
	v_pk_fma_f32 v[114:115], v[114:115], v[14:15], v[108:109]
	v_pk_mul_f32 v[108:109], v[24:25], v[190:191] op_sel_hi:[1,0]
	v_pk_fma_f32 v[108:109], v[88:89], v[158:159], v[108:109] op_sel_hi:[0,1,1]
	v_pk_fma_f32 v[200:201], v[202:203], v[16:17], v[108:109]
	v_pk_mul_f32 v[108:109], v[26:27], v[190:191] op_sel_hi:[1,0]
	v_pk_fma_f32 v[108:109], v[88:89], v[160:161], v[108:109] op_sel_hi:[0,1,1]
	v_add_f32_e32 v88, v146, v147
	v_pk_fma_f32 v[202:203], v[204:205], v[18:19], v[108:109]
	v_pk_mul_f32 v[108:109], v[162:163], v[198:199]
	v_add_f32_dpp v88, v88, v88 quad_perm:[1,0,3,2] row_mask:0xf bank_mask:0xf bound_ctrl:1
	v_pk_fma_f32 v[108:109], v[114:115], v[164:165], v[108:109]
	s_nop 0
	v_add_f32_dpp v88, v88, v88 quad_perm:[2,3,0,1] row_mask:0xf bank_mask:0xf bound_ctrl:1
	v_pk_fma_f32 v[108:109], v[200:201], v[170:171], v[108:109]
	s_nop 0
	v_add_f32_dpp v88, v88, v88 row_half_mirror row_mask:0xf bank_mask:0xf bound_ctrl:1
	v_pk_fma_f32 v[20:21], v[88:89], v[154:155], v[20:21] op_sel_hi:[0,1,1]
	v_pk_fma_f32 v[12:13], v[206:207], v[12:13], v[20:21]
	v_pk_mul_f32 v[20:21], v[22:23], v[190:191] op_sel:[0,1]
	v_pk_fma_f32 v[108:109], v[202:203], v[172:173], v[108:109]
	v_pk_fma_f32 v[20:21], v[88:89], v[156:157], v[20:21] op_sel_hi:[0,1,1]
	v_pk_fma_f32 v[14:15], v[208:209], v[14:15], v[20:21]
	v_pk_mul_f32 v[20:21], v[24:25], v[190:191] op_sel:[0,1]
	s_nop 0
	v_pk_fma_f32 v[20:21], v[88:89], v[158:159], v[20:21] op_sel_hi:[0,1,1]
	v_pk_fma_f32 v[146:147], v[110:111], v[16:17], v[20:21]
	v_pk_mul_f32 v[16:17], v[26:27], v[190:191] op_sel:[0,1]
	s_nop 0
	v_pk_fma_f32 v[16:17], v[88:89], v[160:161], v[16:17] op_sel_hi:[0,1,1]
	v_pk_fma_f32 v[148:149], v[112:113], v[18:19], v[16:17]
	v_pk_mul_f32 v[16:17], v[162:163], v[12:13]
	s_waitcnt lgkmcnt(7)
	v_pk_mul_f32 v[18:19], v[128:129], v[192:193] op_sel_hi:[1,0]
	v_pk_fma_f32 v[16:17], v[14:15], v[164:165], v[16:17]
	s_nop 0
	v_pk_fma_f32 v[16:17], v[146:147], v[170:171], v[16:17]
	s_nop 0
	v_pk_fma_f32 v[110:111], v[148:149], v[172:173], v[16:17]
	s_waitcnt lgkmcnt(5)
	v_pk_mul_f32 v[16:17], v[166:167], v[198:199]
	s_nop 0
	v_pk_fma_f32 v[16:17], v[114:115], v[168:169], v[16:17]
	s_waitcnt lgkmcnt(4)
	v_pk_fma_f32 v[16:17], v[200:201], v[174:175], v[16:17]
	s_nop 0
	v_pk_fma_f32 v[16:17], v[202:203], v[176:177], v[16:17]
	s_nop 0
	v_add_f32_e32 v16, v16, v17
	s_nop 1
	v_add_f32_dpp v16, v16, v16 quad_perm:[1,0,3,2] row_mask:0xf bank_mask:0xf bound_ctrl:1
	s_nop 1
	v_add_f32_dpp v16, v16, v16 quad_perm:[2,3,0,1] row_mask:0xf bank_mask:0xf bound_ctrl:1
	s_nop 1
	v_add_f32_dpp v16, v16, v16 row_half_mirror row_mask:0xf bank_mask:0xf bound_ctrl:1
	s_waitcnt lgkmcnt(3)
	v_pk_fma_f32 v[18:19], v[16:17], v[178:179], v[18:19] op_sel_hi:[0,1,1]
	v_pk_fma_f32 v[24:25], v[198:199], v[120:121], v[18:19]
	v_pk_mul_f32 v[18:19], v[130:131], v[192:193] op_sel_hi:[1,0]
	s_nop 0
	v_pk_fma_f32 v[18:19], v[16:17], v[180:181], v[18:19] op_sel_hi:[0,1,1]
	v_pk_fma_f32 v[26:27], v[114:115], v[122:123], v[18:19]
	v_pk_mul_f32 v[18:19], v[132:133], v[192:193] op_sel_hi:[1,0]
	s_waitcnt lgkmcnt(2)
	v_pk_fma_f32 v[18:19], v[16:17], v[182:183], v[18:19] op_sel_hi:[0,1,1]
	v_pk_fma_f32 v[20:21], v[200:201], v[124:125], v[18:19]
	v_pk_mul_f32 v[18:19], v[134:135], v[192:193] op_sel_hi:[1,0]
	s_nop 0
	v_pk_fma_f32 v[16:17], v[16:17], v[184:185], v[18:19] op_sel_hi:[0,1,1]
	v_pk_fma_f32 v[22:23], v[202:203], v[126:127], v[16:17]
	s_waitcnt lgkmcnt(1)
	v_pk_mul_f32 v[16:17], v[186:187], v[24:25]
	s_nop 0
	v_pk_fma_f32 v[16:17], v[26:27], v[188:189], v[16:17]
	s_waitcnt lgkmcnt(0)
	v_pk_fma_f32 v[16:17], v[20:21], v[194:195], v[16:17]
	s_nop 0
	v_pk_fma_f32 v[112:113], v[22:23], v[196:197], v[16:17]
	v_pk_mul_f32 v[16:17], v[166:167], v[12:13]
	s_nop 0
	v_pk_fma_f32 v[16:17], v[14:15], v[168:169], v[16:17]
	s_nop 0
	v_pk_fma_f32 v[16:17], v[146:147], v[174:175], v[16:17]
	s_nop 0
	v_pk_fma_f32 v[16:17], v[148:149], v[176:177], v[16:17]
	s_nop 0
	v_add_f32_e32 v16, v16, v17
	s_nop 1
	v_add_f32_dpp v16, v16, v16 quad_perm:[1,0,3,2] row_mask:0xf bank_mask:0xf bound_ctrl:1
	s_nop 1
	v_add_f32_dpp v16, v16, v16 quad_perm:[2,3,0,1] row_mask:0xf bank_mask:0xf bound_ctrl:1
	s_nop 1
	v_add_f32_dpp v88, v16, v16 row_half_mirror row_mask:0xf bank_mask:0xf bound_ctrl:1
	v_pk_mul_f32 v[16:17], v[128:129], v[192:193] op_sel:[0,1]
	s_nop 0
	v_pk_fma_f32 v[16:17], v[88:89], v[178:179], v[16:17] op_sel_hi:[0,1,1]
	v_pk_fma_f32 v[16:17], v[12:13], v[120:121], v[16:17]
	v_pk_mul_f32 v[12:13], v[130:131], v[192:193] op_sel:[0,1]
	v_add_u32_e32 v120, 8, v29
	v_pk_fma_f32 v[12:13], v[88:89], v[180:181], v[12:13] op_sel_hi:[0,1,1]
	v_pk_fma_f32 v[18:19], v[14:15], v[122:123], v[12:13]
	v_pk_mul_f32 v[12:13], v[132:133], v[192:193] op_sel:[0,1]
	v_pk_mul_f32 v[14:15], v[134:135], v[192:193] op_sel:[0,1]
	v_add_u32_e32 v122, s27, v118
	v_pk_fma_f32 v[12:13], v[88:89], v[182:183], v[12:13] op_sel_hi:[0,1,1]
	v_pk_fma_f32 v[14:15], v[88:89], v[184:185], v[14:15] op_sel_hi:[0,1,1]
	v_add_u32_e32 v88, -16, v122
	v_cndmask_b32_e64 v88, v120, v88, s[2:3]
	v_add_u32_e32 v88, s26, v88
	v_mul_lo_u32 v88, v88, s41
	v_lshl_add_u64 v[120:121], v[88:89], 1, v[36:37]
	v_pk_mul_f32 v[114:115], v[186:187], v[16:17]
	v_pk_fma_f32 v[12:13], v[146:147], v[124:125], v[12:13]
	v_pk_fma_f32 v[114:115], v[18:19], v[188:189], v[114:115]
	v_pk_fma_f32 v[14:15], v[148:149], v[126:127], v[14:15]
	v_pk_fma_f32 v[114:115], v[12:13], v[194:195], v[114:115]
	v_add_f32_e32 v212, v58, v59
	v_add_f32_e32 v220, v60, v61
	v_pk_fma_f32 v[114:115], v[14:15], v[196:197], v[114:115]
	s_nop 0
	v_add_f32_e32 v213, v62, v63
	v_add_f32_e32 v221, v64, v65
	s_nop 0
	v_add_f32_e32 v214, v66, v67
	v_add_f32_e32 v222, v68, v69
	s_nop 0
	v_add_f32_e32 v215, v70, v71
	v_add_f32_e32 v223, v72, v73
	s_nop 0
	v_add_f32_e32 v216, v74, v75
	v_add_f32_e32 v224, v76, v77
	s_nop 0
	v_add_f32_e32 v217, v78, v79
	v_add_f32_e32 v225, v80, v81
	s_nop 1
	v_add_f32_dpp v210, v210, v210 row_shl:4 row_mask:0xf bank_mask:0x5 bound_ctrl:1
	v_add_f32_dpp v210, v214, v214 row_shr:4 row_mask:0xf bank_mask:0xa bound_ctrl:1
	v_add_f32_dpp v218, v218, v218 row_shl:4 row_mask:0xf bank_mask:0x5 bound_ctrl:1
	v_add_f32_dpp v218, v222, v222 row_shr:4 row_mask:0xf bank_mask:0xa bound_ctrl:1
	v_add_f32_dpp v211, v211, v211 row_shl:4 row_mask:0xf bank_mask:0x5 bound_ctrl:1
	v_add_f32_dpp v211, v215, v215 row_shr:4 row_mask:0xf bank_mask:0xa bound_ctrl:1
	v_add_f32_dpp v219, v219, v219 row_shl:4 row_mask:0xf bank_mask:0x5 bound_ctrl:1
	v_add_f32_dpp v219, v223, v223 row_shr:4 row_mask:0xf bank_mask:0xa bound_ctrl:1
	v_add_f32_dpp v212, v212, v212 row_shl:4 row_mask:0xf bank_mask:0x5 bound_ctrl:1
	v_add_f32_dpp v212, v216, v216 row_shr:4 row_mask:0xf bank_mask:0xa bound_ctrl:1
	v_add_f32_dpp v220, v220, v220 row_shl:4 row_mask:0xf bank_mask:0x5 bound_ctrl:1
	v_add_f32_dpp v220, v224, v224 row_shr:4 row_mask:0xf bank_mask:0xa bound_ctrl:1
	v_add_f32_dpp v213, v213, v213 row_shl:4 row_mask:0xf bank_mask:0x5 bound_ctrl:1
	v_add_f32_dpp v213, v217, v217 row_shr:4 row_mask:0xf bank_mask:0xa bound_ctrl:1
	v_add_f32_dpp v221, v221, v221 row_shl:4 row_mask:0xf bank_mask:0x5 bound_ctrl:1
	v_add_f32_dpp v221, v225, v225 row_shr:4 row_mask:0xf bank_mask:0xa bound_ctrl:1
	v_and_b32_e32 v214, 1, v137
	v_cmp_ne_u32_e64 s[100:101], 0, v214
	v_add_f32_dpp v210, v210, v210 quad_perm:[1,0,3,2] row_mask:0xf bank_mask:0xf bound_ctrl:1
	v_add_f32_dpp v218, v218, v218 quad_perm:[1,0,3,2] row_mask:0xf bank_mask:0xf bound_ctrl:1
	v_add_f32_dpp v211, v211, v211 quad_perm:[1,0,3,2] row_mask:0xf bank_mask:0xf bound_ctrl:1
	v_add_f32_dpp v219, v219, v219 quad_perm:[1,0,3,2] row_mask:0xf bank_mask:0xf bound_ctrl:1
	v_add_f32_dpp v212, v212, v212 quad_perm:[1,0,3,2] row_mask:0xf bank_mask:0xf bound_ctrl:1
	v_add_f32_dpp v220, v220, v220 quad_perm:[1,0,3,2] row_mask:0xf bank_mask:0xf bound_ctrl:1
	v_add_f32_dpp v213, v213, v213 quad_perm:[1,0,3,2] row_mask:0xf bank_mask:0xf bound_ctrl:1
	v_add_f32_dpp v221, v221, v221 quad_perm:[1,0,3,2] row_mask:0xf bank_mask:0xf bound_ctrl:1
	v_cndmask_b32_e64 v210, v210, v211, s[100:101]
	v_cndmask_b32_e64 v218, v218, v219, s[100:101]
	v_cndmask_b32_e64 v212, v212, v213, s[100:101]
	v_cndmask_b32_e64 v220, v220, v221, s[100:101]
	v_and_b32_e32 v214, 2, v137
	s_nop 0
	v_cmp_ne_u32_e64 s[100:101], 0, v214
	v_add_f32_dpp v210, v210, v210 quad_perm:[2,3,0,1] row_mask:0xf bank_mask:0xf bound_ctrl:1
	v_add_f32_dpp v218, v218, v218 quad_perm:[2,3,0,1] row_mask:0xf bank_mask:0xf bound_ctrl:1
	v_add_f32_dpp v212, v212, v212 quad_perm:[2,3,0,1] row_mask:0xf bank_mask:0xf bound_ctrl:1
	v_add_f32_dpp v220, v220, v220 quad_perm:[2,3,0,1] row_mask:0xf bank_mask:0xf bound_ctrl:1
	s_nop 0
	v_cndmask_b32_e64 v50, v210, v212, s[100:101]
	v_cndmask_b32_e64 v51, v218, v220, s[100:101]
	v_cvt_pk_bf16_f32 v50, v50, v51
	global_store_dword v[120:121], v50, off
	v_add_u32_e32 v50, -8, v122
	v_cndmask_b32_e64 v50, v29, v50, s[2:3]
	v_add_u32_e32 v50, s26, v50
	v_mul_lo_u32 v88, v50, s41
	v_add_f32_e32 v228, v92, v93
	v_add_f32_e32 v236, v94, v95
	v_lshl_add_u64 v[50:51], v[88:89], 1, v[36:37]
	s_nop 0
	v_add_f32_e32 v229, v96, v97
	v_add_f32_e32 v237, v98, v99
	s_nop 0
	v_add_f32_e32 v230, v100, v101
	v_add_f32_e32 v238, v102, v103
	s_nop 0
	v_add_f32_e32 v231, v104, v105
	v_add_f32_e32 v239, v106, v107
	s_nop 0
	v_add_f32_e32 v232, v108, v109
	v_add_f32_e32 v240, v110, v111
	s_nop 0
	v_add_f32_e32 v233, v112, v113
	v_add_f32_e32 v145, v114, v115
	s_nop 0
	s_nop 1
	v_add_f32_dpp v226, v226, v226 row_shl:4 row_mask:0xf bank_mask:0x5 bound_ctrl:1
	v_add_f32_dpp v226, v230, v230 row_shr:4 row_mask:0xf bank_mask:0xa bound_ctrl:1
	v_add_f32_dpp v234, v234, v234 row_shl:4 row_mask:0xf bank_mask:0x5 bound_ctrl:1
	v_add_f32_dpp v234, v238, v238 row_shr:4 row_mask:0xf bank_mask:0xa bound_ctrl:1
	v_add_f32_dpp v227, v227, v227 row_shl:4 row_mask:0xf bank_mask:0x5 bound_ctrl:1
	v_add_f32_dpp v227, v231, v231 row_shr:4 row_mask:0xf bank_mask:0xa bound_ctrl:1
	v_add_f32_dpp v235, v235, v235 row_shl:4 row_mask:0xf bank_mask:0x5 bound_ctrl:1
	v_add_f32_dpp v235, v239, v239 row_shr:4 row_mask:0xf bank_mask:0xa bound_ctrl:1
	v_add_f32_dpp v228, v228, v228 row_shl:4 row_mask:0xf bank_mask:0x5 bound_ctrl:1
	v_add_f32_dpp v228, v232, v232 row_shr:4 row_mask:0xf bank_mask:0xa bound_ctrl:1
	v_add_f32_dpp v236, v236, v236 row_shl:4 row_mask:0xf bank_mask:0x5 bound_ctrl:1
	v_add_f32_dpp v236, v240, v240 row_shr:4 row_mask:0xf bank_mask:0xa bound_ctrl:1
	v_add_f32_dpp v229, v229, v229 row_shl:4 row_mask:0xf bank_mask:0x5 bound_ctrl:1
	v_add_f32_dpp v229, v233, v233 row_shr:4 row_mask:0xf bank_mask:0xa bound_ctrl:1
	v_add_f32_dpp v237, v237, v237 row_shl:4 row_mask:0xf bank_mask:0x5 bound_ctrl:1
	v_add_f32_dpp v237, v145, v145 row_shr:4 row_mask:0xf bank_mask:0xa bound_ctrl:1
	v_and_b32_e32 v230, 1, v137
	v_cmp_ne_u32_e64 s[100:101], 0, v230
	v_add_f32_dpp v226, v226, v226 quad_perm:[1,0,3,2] row_mask:0xf bank_mask:0xf bound_ctrl:1
	v_add_f32_dpp v234, v234, v234 quad_perm:[1,0,3,2] row_mask:0xf bank_mask:0xf bound_ctrl:1
	v_add_f32_dpp v227, v227, v227 quad_perm:[1,0,3,2] row_mask:0xf bank_mask:0xf bound_ctrl:1
	v_add_f32_dpp v235, v235, v235 quad_perm:[1,0,3,2] row_mask:0xf bank_mask:0xf bound_ctrl:1
	v_add_f32_dpp v228, v228, v228 quad_perm:[1,0,3,2] row_mask:0xf bank_mask:0xf bound_ctrl:1
	v_add_f32_dpp v236, v236, v236 quad_perm:[1,0,3,2] row_mask:0xf bank_mask:0xf bound_ctrl:1
	v_add_f32_dpp v229, v229, v229 quad_perm:[1,0,3,2] row_mask:0xf bank_mask:0xf bound_ctrl:1
	v_add_f32_dpp v237, v237, v237 quad_perm:[1,0,3,2] row_mask:0xf bank_mask:0xf bound_ctrl:1
	v_cndmask_b32_e64 v226, v226, v227, s[100:101]
	v_cndmask_b32_e64 v234, v234, v235, s[100:101]
	v_cndmask_b32_e64 v228, v228, v229, s[100:101]
	v_cndmask_b32_e64 v236, v236, v237, s[100:101]
	v_and_b32_e32 v230, 2, v137
	s_nop 0
	v_cmp_ne_u32_e64 s[100:101], 0, v230
	v_add_f32_dpp v226, v226, v226 quad_perm:[2,3,0,1] row_mask:0xf bank_mask:0xf bound_ctrl:1
	v_add_f32_dpp v234, v234, v234 quad_perm:[2,3,0,1] row_mask:0xf bank_mask:0xf bound_ctrl:1
	v_add_f32_dpp v228, v228, v228 quad_perm:[2,3,0,1] row_mask:0xf bank_mask:0xf bound_ctrl:1
	v_add_f32_dpp v236, v236, v236 quad_perm:[2,3,0,1] row_mask:0xf bank_mask:0xf bound_ctrl:1
	s_nop 0
	v_cndmask_b32_e64 v52, v226, v228, s[100:101]
	v_cndmask_b32_e64 v53, v234, v236, s[100:101]
	v_cvt_pk_bf16_f32 v52, v52, v53
	global_store_dword v[50:51], v52, off
	s_cbranch_vccnz .LBB0_954
	s_and_b32 s0, s27, 16
	v_add_u32_e32 v50, s0, v33
	v_mad_u64_u32 v[54:55], s[0:1], v50, s49, v[32:33]
	s_waitcnt vmcnt(5)
	v_lshlrev_b32_e32 v55, 16, v34
	v_and_b32_e32 v56, 0xffff0000, v34
	v_lshlrev_b32_e32 v57, 16, v35
	v_and_b32_e32 v58, 0xffff0000, v35
	v_lshlrev_b32_e32 v50, 16, v30
	v_and_b32_e32 v51, 0xffff0000, v30
	v_lshlrev_b32_e32 v52, 16, v31
	v_and_b32_e32 v53, 0xffff0000, v31
	ds_write_b128 v54, v[50:53] offset:256
	v_xor_b32_e32 v51, 0x80000000, v56
	v_xor_b32_e32 v50, 0x80000000, v55
	v_xor_b32_e32 v53, 0x80000000, v58
	v_xor_b32_e32 v52, 0x80000000, v57
	ds_write_b128 v54, v[50:53] offset:512
	s_waitcnt vmcnt(4)
	v_lshlrev_b32_e32 v50, 16, v38
	v_and_b32_e32 v51, 0xffff0000, v38
	v_lshlrev_b32_e32 v52, 16, v39
	v_and_b32_e32 v53, 0xffff0000, v39
	ds_write_b128 v54, v[0:3]
	ds_write_b128 v54, v[50:53] offset:768
	s_waitcnt vmcnt(3)
	ds_write_b128 v54, v[4:7] offset:1024
	s_waitcnt vmcnt(2)
	ds_write_b128 v54, v[8:11] offset:1280
	s_branch .LBB0_954

.LBB0_1955:
	s_bitcmp0_b32 s21, 0
	s_cselect_b32 s20, 0, s69
	v_lshl_add_u32 v88, v117, 2, s20
	ds_read_b128 v[50:53], v88
	ds_read_b128 v[54:57], v88 offset:16
	ds_read_b128 v[58:61], v88 offset:256
	ds_read_b128 v[62:65], v88 offset:272
	ds_read_b128 v[66:69], v88 offset:512
	ds_read_b128 v[70:73], v88 offset:528
	ds_read_b128 v[74:77], v88 offset:768
	ds_read_b128 v[78:81], v88 offset:784
	ds_read_b128 v[82:85], v88 offset:1024
	ds_read_b128 v[90:93], v88 offset:1040
	s_waitcnt lgkmcnt(5)
	v_pk_mul_f32 v[86:87], v[24:25], v[66:67]
	s_cselect_b32 s20, s96, s97
	v_pk_fma_f32 v[86:87], v[26:27], v[68:69], v[86:87]
	v_lshl_add_u32 v104, v28, 2, s20
	s_waitcnt lgkmcnt(4)
	v_pk_fma_f32 v[86:87], v[20:21], v[70:71], v[86:87]
	ds_read2st64_b64 v[94:97], v104 offset1:3
	ds_read_b128 v[98:101], v88 offset:1536
	ds_read_b128 v[106:109], v88 offset:1552
	ds_read_b128 v[110:113], v88 offset:1792
	ds_read_b128 v[120:123], v88 offset:1808
	ds_read_b128 v[124:127], v88 offset:2048
	ds_read_b128 v[128:131], v88 offset:2064
	ds_read_b128 v[132:135], v88 offset:2304
	ds_read_b128 v[144:147], v88 offset:2320
	ds_read_b128 v[148:151], v88 offset:2560
	ds_read_b128 v[152:155], v88 offset:2576
	v_pk_fma_f32 v[86:87], v[22:23], v[72:73], v[86:87]
	s_waitcnt lgkmcnt(10)
	v_pk_mul_f32 v[102:103], v[58:59], v[94:95] op_sel_hi:[1,0]
	v_add_f32_e32 v86, v86, v87
	s_andn2_b64 vcc, exec, s[0:1]
	s_nop 0
	v_add_f32_dpp v86, v86, v86 quad_perm:[1,0,3,2] row_mask:0xf bank_mask:0xf bound_ctrl:1
	s_nop 1
	v_add_f32_dpp v86, v86, v86 quad_perm:[2,3,0,1] row_mask:0xf bank_mask:0xf bound_ctrl:1
	s_nop 1
	v_add_f32_dpp v86, v86, v86 row_half_mirror row_mask:0xf bank_mask:0xf bound_ctrl:1
	v_pk_fma_f32 v[102:103], v[86:87], v[74:75], v[102:103] op_sel_hi:[0,1,1]
	v_pk_fma_f32 v[102:103], v[24:25], v[50:51], v[102:103]
	v_pk_mul_f32 v[24:25], v[60:61], v[94:95] op_sel_hi:[1,0]
	s_nop 0
	v_pk_fma_f32 v[24:25], v[86:87], v[76:77], v[24:25] op_sel_hi:[0,1,1]
	v_pk_fma_f32 v[114:115], v[26:27], v[52:53], v[24:25]
	v_pk_mul_f32 v[24:25], v[62:63], v[94:95] op_sel_hi:[1,0]
	s_nop 0
	v_pk_fma_f32 v[24:25], v[86:87], v[78:79], v[24:25] op_sel_hi:[0,1,1]
	v_pk_fma_f32 v[156:157], v[20:21], v[54:55], v[24:25]
	v_pk_mul_f32 v[20:21], v[64:65], v[94:95] op_sel_hi:[1,0]
	v_pk_mul_f32 v[24:25], v[58:59], v[94:95] op_sel:[0,1]
	v_pk_fma_f32 v[20:21], v[86:87], v[80:81], v[20:21] op_sel_hi:[0,1,1]
	v_pk_fma_f32 v[158:159], v[22:23], v[56:57], v[20:21]
	v_pk_mul_f32 v[22:23], v[16:17], v[66:67]
	v_pk_mul_f32 v[20:21], v[82:83], v[102:103]
	v_pk_fma_f32 v[22:23], v[18:19], v[68:69], v[22:23]
	v_pk_fma_f32 v[20:21], v[114:115], v[84:85], v[20:21]
	v_pk_fma_f32 v[22:23], v[12:13], v[70:71], v[22:23]
	v_pk_fma_f32 v[20:21], v[156:157], v[90:91], v[20:21]
	v_pk_fma_f32 v[22:23], v[14:15], v[72:73], v[22:23]
	v_pk_fma_f32 v[20:21], v[158:159], v[92:93], v[20:21]
	v_add_f32_e32 v22, v22, v23
	s_nop 1
	v_add_f32_dpp v22, v22, v22 quad_perm:[1,0,3,2] row_mask:0xf bank_mask:0xf bound_ctrl:1
	s_nop 1
	v_add_f32_dpp v22, v22, v22 quad_perm:[2,3,0,1] row_mask:0xf bank_mask:0xf bound_ctrl:1
	s_nop 1
	v_add_f32_dpp v22, v22, v22 row_half_mirror row_mask:0xf bank_mask:0xf bound_ctrl:1
	v_pk_fma_f32 v[24:25], v[22:23], v[74:75], v[24:25] op_sel_hi:[0,1,1]
	v_pk_fma_f32 v[58:59], v[16:17], v[50:51], v[24:25]
	v_pk_mul_f32 v[16:17], v[60:61], v[94:95] op_sel:[0,1]
	s_nop 0
	v_pk_fma_f32 v[16:17], v[22:23], v[76:77], v[16:17] op_sel_hi:[0,1,1]
	v_pk_fma_f32 v[160:161], v[18:19], v[52:53], v[16:17]
	v_pk_mul_f32 v[16:17], v[62:63], v[94:95] op_sel:[0,1]
	s_nop 0
	v_pk_fma_f32 v[16:17], v[22:23], v[78:79], v[16:17] op_sel_hi:[0,1,1]
	v_pk_fma_f32 v[54:55], v[12:13], v[54:55], v[16:17]
	v_pk_mul_f32 v[12:13], v[64:65], v[94:95] op_sel:[0,1]
	s_waitcnt lgkmcnt(7)
	v_pk_mul_f32 v[94:95], v[110:111], v[96:97] op_sel:[0,1]
	v_pk_fma_f32 v[12:13], v[22:23], v[80:81], v[12:13] op_sel_hi:[0,1,1]
	v_pk_fma_f32 v[56:57], v[14:15], v[56:57], v[12:13]
	v_pk_mul_f32 v[12:13], v[82:83], v[58:59]
	v_add_f32_e32 v210, v20, v21
	v_pk_fma_f32 v[12:13], v[160:161], v[84:85], v[12:13]
	s_nop 0
	v_pk_fma_f32 v[12:13], v[54:55], v[90:91], v[12:13]
	s_waitcnt lgkmcnt(5)
	v_pk_mul_f32 v[90:91], v[124:125], v[102:103]
	v_pk_fma_f32 v[12:13], v[56:57], v[92:93], v[12:13]
	v_pk_fma_f32 v[90:91], v[114:115], v[126:127], v[90:91]
	v_pk_mul_f32 v[92:93], v[110:111], v[96:97] op_sel_hi:[1,0]
	s_waitcnt lgkmcnt(4)
	v_pk_fma_f32 v[90:91], v[156:157], v[128:129], v[90:91]
	v_add_f32_e32 v218, v12, v13
	v_pk_fma_f32 v[90:91], v[158:159], v[130:131], v[90:91]
	v_add_f32_e32 v90, v90, v91
	s_nop 0
	s_nop 0
	v_add_f32_dpp v90, v90, v90 quad_perm:[1,0,3,2] row_mask:0xf bank_mask:0xf bound_ctrl:1
	s_nop 1
	v_add_f32_dpp v90, v90, v90 quad_perm:[2,3,0,1] row_mask:0xf bank_mask:0xf bound_ctrl:1
	ds_read_b128 v[12:15], v88 offset:3072
	ds_read_b128 v[16:19], v88 offset:3088
	ds_read_b128 v[20:23], v88 offset:3328
	ds_read_b128 v[24:27], v88 offset:3344
	ds_read_b128 v[60:63], v88 offset:3584
	ds_read_b128 v[64:67], v88 offset:3600
	ds_read_b128 v[68:71], v88 offset:3840
	ds_read_b128 v[72:75], v88 offset:3856
	ds_read_b128 v[76:79], v88 offset:4096
	ds_read_b128 v[80:83], v88 offset:4112
	ds_read2st64_b64 v[84:87], v104 offset0:6 offset1:9
	v_add_f32_dpp v90, v90, v90 row_half_mirror row_mask:0xf bank_mask:0xf bound_ctrl:1
	s_waitcnt lgkmcnt(14)
	v_pk_fma_f32 v[92:93], v[90:91], v[132:133], v[92:93] op_sel_hi:[0,1,1]
	v_pk_fma_f32 v[102:103], v[102:103], v[98:99], v[92:93]
	v_pk_mul_f32 v[92:93], v[112:113], v[96:97] op_sel_hi:[1,0]
	v_pk_fma_f32 v[92:93], v[90:91], v[134:135], v[92:93] op_sel_hi:[0,1,1]
	v_pk_fma_f32 v[114:115], v[114:115], v[100:101], v[92:93]
	v_pk_mul_f32 v[92:93], v[120:121], v[96:97] op_sel_hi:[1,0]
	s_waitcnt lgkmcnt(13)
	v_pk_fma_f32 v[92:93], v[90:91], v[144:145], v[92:93] op_sel_hi:[0,1,1]
	v_pk_fma_f32 v[156:157], v[156:157], v[106:107], v[92:93]
	v_pk_mul_f32 v[92:93], v[122:123], v[96:97] op_sel_hi:[1,0]
	v_pk_fma_f32 v[90:91], v[90:91], v[146:147], v[92:93] op_sel_hi:[0,1,1]
	v_pk_mul_f32 v[92:93], v[124:125], v[58:59]
	v_pk_fma_f32 v[158:159], v[158:159], v[108:109], v[90:91]
	v_pk_fma_f32 v[92:93], v[160:161], v[126:127], v[92:93]
	s_waitcnt lgkmcnt(12)
	v_pk_mul_f32 v[90:91], v[148:149], v[102:103]
	v_pk_fma_f32 v[92:93], v[54:55], v[128:129], v[92:93]
	v_pk_fma_f32 v[90:91], v[114:115], v[150:151], v[90:91]
	v_pk_fma_f32 v[92:93], v[56:57], v[130:131], v[92:93]
	s_waitcnt lgkmcnt(11)
	v_pk_fma_f32 v[90:91], v[156:157], v[152:153], v[90:91]
	v_add_f32_e32 v92, v92, v93
	v_pk_fma_f32 v[90:91], v[158:159], v[154:155], v[90:91]
	s_nop 0
	v_add_f32_dpp v92, v92, v92 quad_perm:[1,0,3,2] row_mask:0xf bank_mask:0xf bound_ctrl:1
	s_nop 1
	v_add_f32_dpp v92, v92, v92 quad_perm:[2,3,0,1] row_mask:0xf bank_mask:0xf bound_ctrl:1
	s_nop 1
	v_add_f32_dpp v92, v92, v92 row_half_mirror row_mask:0xf bank_mask:0xf bound_ctrl:1
	v_pk_fma_f32 v[94:95], v[92:93], v[132:133], v[94:95] op_sel_hi:[0,1,1]
	v_pk_fma_f32 v[162:163], v[58:59], v[98:99], v[94:95]
	v_pk_mul_f32 v[58:59], v[112:113], v[96:97] op_sel:[0,1]
	s_nop 0
	v_pk_fma_f32 v[58:59], v[92:93], v[134:135], v[58:59] op_sel_hi:[0,1,1]
	v_pk_fma_f32 v[160:161], v[160:161], v[100:101], v[58:59]
	v_pk_mul_f32 v[58:59], v[120:121], v[96:97] op_sel:[0,1]
	s_nop 0
	v_pk_fma_f32 v[58:59], v[92:93], v[144:145], v[58:59] op_sel_hi:[0,1,1]
	v_pk_fma_f32 v[164:165], v[54:55], v[106:107], v[58:59]
	s_waitcnt lgkmcnt(6)
	v_pk_mul_f32 v[58:59], v[60:61], v[102:103]
	v_pk_mul_f32 v[54:55], v[122:123], v[96:97] op_sel:[0,1]
	v_pk_fma_f32 v[58:59], v[114:115], v[62:63], v[58:59]
	v_pk_mul_f32 v[60:61], v[60:61], v[162:163]
	s_waitcnt lgkmcnt(5)
	v_pk_fma_f32 v[58:59], v[156:157], v[64:65], v[58:59]
	v_pk_fma_f32 v[54:55], v[92:93], v[146:147], v[54:55] op_sel_hi:[0,1,1]
	v_pk_fma_f32 v[58:59], v[158:159], v[66:67], v[58:59]
	v_pk_fma_f32 v[60:61], v[160:161], v[62:63], v[60:61]
	v_pk_fma_f32 v[166:167], v[56:57], v[108:109], v[54:55]
	v_add_f32_e32 v58, v58, v59
	v_pk_fma_f32 v[60:61], v[164:165], v[64:65], v[60:61]
	v_pk_mul_f32 v[54:55], v[148:149], v[162:163]
	v_add_f32_dpp v58, v58, v58 quad_perm:[1,0,3,2] row_mask:0xf bank_mask:0xf bound_ctrl:1
	v_pk_fma_f32 v[60:61], v[166:167], v[66:67], v[60:61]
	s_waitcnt lgkmcnt(0)
	v_pk_mul_f32 v[148:149], v[20:21], v[84:85] op_sel_hi:[1,0]
	v_add_f32_dpp v58, v58, v58 quad_perm:[2,3,0,1] row_mask:0xf bank_mask:0xf bound_ctrl:1
	v_add_f32_e32 v60, v60, v61
	v_pk_mul_f32 v[20:21], v[20:21], v[84:85] op_sel:[0,1]
	v_add_f32_dpp v58, v58, v58 row_half_mirror row_mask:0xf bank_mask:0xf bound_ctrl:1
	v_add_f32_dpp v60, v60, v60 quad_perm:[1,0,3,2] row_mask:0xf bank_mask:0xf bound_ctrl:1
	v_pk_fma_f32 v[148:149], v[58:59], v[68:69], v[148:149] op_sel_hi:[0,1,1]
	v_pk_fma_f32 v[102:103], v[102:103], v[12:13], v[148:149]
	v_add_f32_dpp v60, v60, v60 quad_perm:[2,3,0,1] row_mask:0xf bank_mask:0xf bound_ctrl:1
	v_pk_mul_f32 v[148:149], v[22:23], v[84:85] op_sel_hi:[1,0]
	v_pk_fma_f32 v[54:55], v[160:161], v[150:151], v[54:55]
	v_add_f32_dpp v60, v60, v60 row_half_mirror row_mask:0xf bank_mask:0xf bound_ctrl:1
	v_pk_fma_f32 v[148:149], v[58:59], v[70:71], v[148:149] op_sel_hi:[0,1,1]
	v_pk_fma_f32 v[20:21], v[60:61], v[68:69], v[20:21] op_sel_hi:[0,1,1]
	v_pk_fma_f32 v[54:55], v[164:165], v[152:153], v[54:55]
	v_pk_fma_f32 v[114:115], v[114:115], v[14:15], v[148:149]
	v_pk_mul_f32 v[148:149], v[24:25], v[84:85] op_sel_hi:[1,0]
	v_pk_fma_f32 v[64:65], v[162:163], v[12:13], v[20:21]
	v_pk_mul_f32 v[12:13], v[22:23], v[84:85] op_sel:[0,1]
	v_pk_fma_f32 v[54:55], v[166:167], v[154:155], v[54:55]
	v_pk_fma_f32 v[148:149], v[58:59], v[72:73], v[148:149] op_sel_hi:[0,1,1]
	v_pk_fma_f32 v[12:13], v[60:61], v[70:71], v[12:13] op_sel_hi:[0,1,1]
	v_add_f32_e32 v211, v90, v91
	v_add_f32_e32 v219, v54, v55
	ds_read_b128 v[90:93], v88 offset:4608
	ds_read_b128 v[94:97], v88 offset:4624
	ds_read_b128 v[98:101], v88 offset:4864
	ds_read_b128 v[106:109], v88 offset:4880
	ds_read_b128 v[110:113], v88 offset:5120
	ds_read_b128 v[120:123], v88 offset:5136
	ds_read_b128 v[124:127], v88 offset:5376
	ds_read_b128 v[128:131], v88 offset:5392
	ds_read_b128 v[132:135], v88 offset:5632
	ds_read_b128 v[144:147], v88 offset:5648
	v_pk_fma_f32 v[168:169], v[156:157], v[16:17], v[148:149]
	v_pk_mul_f32 v[148:149], v[26:27], v[84:85] op_sel_hi:[1,0]
	v_pk_fma_f32 v[66:67], v[160:161], v[14:15], v[12:13]
	v_pk_mul_f32 v[12:13], v[24:25], v[84:85] op_sel:[0,1]
	s_waitcnt lgkmcnt(5)
	v_pk_mul_f32 v[62:63], v[110:111], v[102:103]
	v_pk_fma_f32 v[58:59], v[58:59], v[74:75], v[148:149] op_sel_hi:[0,1,1]
	v_pk_fma_f32 v[12:13], v[60:61], v[72:73], v[12:13] op_sel_hi:[0,1,1]
	v_pk_fma_f32 v[62:63], v[114:115], v[112:113], v[62:63]
	v_pk_fma_f32 v[170:171], v[158:159], v[18:19], v[58:59]
	v_pk_fma_f32 v[160:161], v[164:165], v[16:17], v[12:13]
	v_pk_mul_f32 v[12:13], v[26:27], v[84:85] op_sel:[0,1]
	s_waitcnt lgkmcnt(4)
	v_pk_fma_f32 v[62:63], v[168:169], v[120:121], v[62:63]
	v_pk_mul_f32 v[110:111], v[110:111], v[64:65]
	v_pk_fma_f32 v[12:13], v[60:61], v[74:75], v[12:13] op_sel_hi:[0,1,1]
	v_pk_fma_f32 v[62:63], v[170:171], v[122:123], v[62:63]
	v_pk_fma_f32 v[110:111], v[66:67], v[112:113], v[110:111]
	v_pk_fma_f32 v[84:85], v[166:167], v[18:19], v[12:13]
	v_add_f32_e32 v62, v62, v63
	v_pk_fma_f32 v[110:111], v[160:161], v[120:121], v[110:111]
	v_pk_mul_f32 v[162:163], v[98:99], v[86:87] op_sel_hi:[1,0]
	v_add_f32_dpp v62, v62, v62 quad_perm:[1,0,3,2] row_mask:0xf bank_mask:0xf bound_ctrl:1
	v_pk_fma_f32 v[110:111], v[84:85], v[122:123], v[110:111]
	v_pk_mul_f32 v[58:59], v[76:77], v[102:103]
	v_add_f32_dpp v62, v62, v62 quad_perm:[2,3,0,1] row_mask:0xf bank_mask:0xf bound_ctrl:1
	v_add_f32_e32 v105, v110, v111
	v_pk_mul_f32 v[98:99], v[98:99], v[86:87] op_sel:[0,1]
	v_add_f32_dpp v62, v62, v62 row_half_mirror row_mask:0xf bank_mask:0xf bound_ctrl:1
	v_add_f32_dpp v105, v105, v105 quad_perm:[1,0,3,2] row_mask:0xf bank_mask:0xf bound_ctrl:1
	s_waitcnt lgkmcnt(3)
	v_pk_fma_f32 v[162:163], v[62:63], v[124:125], v[162:163] op_sel_hi:[0,1,1]
	v_pk_fma_f32 v[102:103], v[102:103], v[90:91], v[162:163]
	v_add_f32_dpp v105, v105, v105 quad_perm:[2,3,0,1] row_mask:0xf bank_mask:0xf bound_ctrl:1
	v_pk_mul_f32 v[162:163], v[100:101], v[86:87] op_sel_hi:[1,0]
	v_pk_mul_f32 v[12:13], v[76:77], v[64:65]
	v_add_f32_dpp v110, v105, v105 row_half_mirror row_mask:0xf bank_mask:0xf bound_ctrl:1
	v_pk_fma_f32 v[162:163], v[62:63], v[126:127], v[162:163] op_sel_hi:[0,1,1]
	v_pk_fma_f32 v[98:99], v[110:111], v[124:125], v[98:99] op_sel_hi:[0,1,1]
	v_pk_fma_f32 v[58:59], v[114:115], v[78:79], v[58:59]
	v_pk_fma_f32 v[12:13], v[66:67], v[78:79], v[12:13]
	v_pk_fma_f32 v[114:115], v[114:115], v[92:93], v[162:163]
	v_pk_mul_f32 v[162:163], v[106:107], v[86:87] op_sel_hi:[1,0]
	v_pk_fma_f32 v[166:167], v[64:65], v[90:91], v[98:99]
	v_pk_mul_f32 v[64:65], v[100:101], v[86:87] op_sel:[0,1]
	v_pk_fma_f32 v[58:59], v[168:169], v[80:81], v[58:59]
	v_pk_fma_f32 v[12:13], v[160:161], v[80:81], v[12:13]
	s_waitcnt lgkmcnt(2)
	v_pk_fma_f32 v[162:163], v[62:63], v[128:129], v[162:163] op_sel_hi:[0,1,1]
	v_pk_fma_f32 v[64:65], v[110:111], v[126:127], v[64:65] op_sel_hi:[0,1,1]
	v_pk_fma_f32 v[58:59], v[170:171], v[82:83], v[58:59]
	v_pk_fma_f32 v[60:61], v[84:85], v[82:83], v[12:13]
	ds_read_b128 v[12:15], v88 offset:6144
	ds_read_b128 v[16:19], v88 offset:6160
	ds_read_b128 v[20:23], v88 offset:6400
	ds_read_b128 v[24:27], v88 offset:6416
	ds_read_b128 v[68:71], v88 offset:6656
	ds_read_b128 v[72:75], v88 offset:6672
	ds_read_b128 v[76:79], v88 offset:6912
	ds_read_b128 v[80:83], v88 offset:6928
	ds_read_b128 v[148:151], v88 offset:7168
	ds_read_b128 v[152:155], v88 offset:7184
	ds_read2st64_b64 v[156:159], v104 offset0:12 offset1:15
	v_pk_fma_f32 v[162:163], v[168:169], v[94:95], v[162:163]
	v_pk_mul_f32 v[164:165], v[108:109], v[86:87] op_sel_hi:[1,0]
	v_pk_fma_f32 v[168:169], v[66:67], v[92:93], v[64:65]
	s_waitcnt lgkmcnt(6)
	v_pk_mul_f32 v[66:67], v[68:69], v[102:103]
	v_pk_fma_f32 v[62:63], v[62:63], v[130:131], v[164:165] op_sel_hi:[0,1,1]
	v_pk_mul_f32 v[64:65], v[106:107], v[86:87] op_sel:[0,1]
	v_pk_fma_f32 v[66:67], v[114:115], v[70:71], v[66:67]
	v_pk_fma_f32 v[164:165], v[170:171], v[96:97], v[62:63]
	v_pk_fma_f32 v[64:65], v[110:111], v[128:129], v[64:65] op_sel_hi:[0,1,1]
	s_waitcnt lgkmcnt(5)
	v_pk_fma_f32 v[66:67], v[162:163], v[72:73], v[66:67]
	v_pk_fma_f32 v[160:161], v[160:161], v[94:95], v[64:65]
	v_pk_mul_f32 v[64:65], v[108:109], v[86:87] op_sel:[0,1]
	v_pk_fma_f32 v[66:67], v[164:165], v[74:75], v[66:67]
	v_pk_fma_f32 v[64:65], v[110:111], v[130:131], v[64:65] op_sel_hi:[0,1,1]
	v_add_f32_e32 v66, v66, v67
	v_pk_mul_f32 v[62:63], v[132:133], v[102:103]
	v_pk_fma_f32 v[170:171], v[84:85], v[96:97], v[64:65]
	v_pk_mul_f32 v[64:65], v[132:133], v[166:167]
	v_add_f32_dpp v66, v66, v66 quad_perm:[1,0,3,2] row_mask:0xf bank_mask:0xf bound_ctrl:1
	v_pk_mul_f32 v[68:69], v[68:69], v[166:167]
	v_pk_fma_f32 v[62:63], v[114:115], v[134:135], v[62:63]
	v_pk_fma_f32 v[64:65], v[168:169], v[134:135], v[64:65]
	v_add_f32_dpp v66, v66, v66 quad_perm:[2,3,0,1] row_mask:0xf bank_mask:0xf bound_ctrl:1
	v_pk_fma_f32 v[68:69], v[168:169], v[70:71], v[68:69]
	v_pk_fma_f32 v[62:63], v[162:163], v[144:145], v[62:63]
	v_pk_fma_f32 v[64:65], v[160:161], v[144:145], v[64:65]
	v_add_f32_dpp v66, v66, v66 row_half_mirror row_mask:0xf bank_mask:0xf bound_ctrl:1
	s_waitcnt lgkmcnt(0)
	v_pk_mul_f32 v[144:145], v[20:21], v[156:157] op_sel_hi:[1,0]
	v_pk_fma_f32 v[68:69], v[160:161], v[72:73], v[68:69]
	v_pk_fma_f32 v[144:145], v[66:67], v[76:77], v[144:145] op_sel_hi:[0,1,1]
	v_pk_fma_f32 v[68:69], v[170:171], v[74:75], v[68:69]
	v_pk_fma_f32 v[102:103], v[102:103], v[12:13], v[144:145]
	v_pk_mul_f32 v[144:145], v[22:23], v[156:157] op_sel_hi:[1,0]
	v_add_f32_e32 v68, v68, v69
	v_pk_fma_f32 v[144:145], v[66:67], v[78:79], v[144:145] op_sel_hi:[0,1,1]
	v_pk_fma_f32 v[114:115], v[114:115], v[14:15], v[144:145]
	v_add_f32_dpp v68, v68, v68 quad_perm:[1,0,3,2] row_mask:0xf bank_mask:0xf bound_ctrl:1
	v_pk_mul_f32 v[144:145], v[24:25], v[156:157] op_sel_hi:[1,0]
	v_pk_mul_f32 v[20:21], v[20:21], v[156:157] op_sel:[0,1]
	v_add_f32_dpp v68, v68, v68 quad_perm:[2,3,0,1] row_mask:0xf bank_mask:0xf bound_ctrl:1
	v_pk_fma_f32 v[144:145], v[66:67], v[80:81], v[144:145] op_sel_hi:[0,1,1]
	ds_read_b128 v[84:87], v88 offset:7680
	ds_read_b128 v[90:93], v88 offset:7696
	ds_read_b128 v[94:97], v88 offset:7936
	ds_read_b128 v[98:101], v88 offset:7952
	ds_read_b128 v[106:109], v88 offset:8192
	ds_read_b128 v[110:113], v88 offset:8208
	ds_read_b128 v[120:123], v88 offset:8448
	ds_read_b128 v[124:127], v88 offset:8464
	ds_read_b128 v[128:131], v88 offset:8704
	ds_read_b128 v[132:135], v88 offset:8720
	v_add_f32_dpp v68, v68, v68 row_half_mirror row_mask:0xf bank_mask:0xf bound_ctrl:1
	v_pk_fma_f32 v[172:173], v[162:163], v[16:17], v[144:145]
	v_pk_mul_f32 v[144:145], v[26:27], v[156:157] op_sel_hi:[1,0]
	v_pk_fma_f32 v[20:21], v[68:69], v[76:77], v[20:21] op_sel_hi:[0,1,1]
	s_waitcnt lgkmcnt(5)
	v_pk_mul_f32 v[70:71], v[106:107], v[102:103]
	v_pk_fma_f32 v[66:67], v[66:67], v[82:83], v[144:145] op_sel_hi:[0,1,1]
	v_pk_fma_f32 v[72:73], v[166:167], v[12:13], v[20:21]
	v_pk_mul_f32 v[12:13], v[22:23], v[156:157] op_sel:[0,1]
	v_pk_fma_f32 v[70:71], v[114:115], v[108:109], v[70:71]
	v_pk_fma_f32 v[174:175], v[164:165], v[18:19], v[66:67]
	v_pk_fma_f32 v[12:13], v[68:69], v[78:79], v[12:13] op_sel_hi:[0,1,1]
	s_waitcnt lgkmcnt(4)
	v_pk_fma_f32 v[70:71], v[172:173], v[110:111], v[70:71]
	v_pk_fma_f32 v[74:75], v[168:169], v[14:15], v[12:13]
	v_pk_mul_f32 v[12:13], v[24:25], v[156:157] op_sel:[0,1]
	v_pk_fma_f32 v[70:71], v[174:175], v[112:113], v[70:71]
	v_pk_fma_f32 v[12:13], v[68:69], v[80:81], v[12:13] op_sel_hi:[0,1,1]
	v_add_f32_e32 v70, v70, v71
	v_pk_fma_f32 v[168:169], v[160:161], v[16:17], v[12:13]
	v_pk_mul_f32 v[12:13], v[26:27], v[156:157] op_sel:[0,1]
	v_add_f32_dpp v70, v70, v70 quad_perm:[1,0,3,2] row_mask:0xf bank_mask:0xf bound_ctrl:1
	v_pk_fma_f32 v[12:13], v[68:69], v[82:83], v[12:13] op_sel_hi:[0,1,1]
	v_pk_mul_f32 v[106:107], v[106:107], v[72:73]
	v_add_f32_dpp v70, v70, v70 quad_perm:[2,3,0,1] row_mask:0xf bank_mask:0xf bound_ctrl:1
	v_pk_fma_f32 v[64:65], v[170:171], v[146:147], v[64:65]
	v_pk_fma_f32 v[156:157], v[170:171], v[18:19], v[12:13]
	v_add_f32_dpp v70, v70, v70 row_half_mirror row_mask:0xf bank_mask:0xf bound_ctrl:1
	v_pk_mul_f32 v[170:171], v[94:95], v[158:159] op_sel_hi:[1,0]
	v_pk_fma_f32 v[106:107], v[74:75], v[108:109], v[106:107]
	s_waitcnt lgkmcnt(3)
	v_pk_fma_f32 v[170:171], v[70:71], v[120:121], v[170:171] op_sel_hi:[0,1,1]
	v_pk_fma_f32 v[106:107], v[168:169], v[110:111], v[106:107]
	v_pk_mul_f32 v[66:67], v[148:149], v[102:103]
	v_pk_fma_f32 v[102:103], v[102:103], v[84:85], v[170:171]
	v_pk_mul_f32 v[170:171], v[96:97], v[158:159] op_sel_hi:[1,0]
	v_pk_fma_f32 v[106:107], v[156:157], v[112:113], v[106:107]
	v_pk_fma_f32 v[170:171], v[70:71], v[122:123], v[170:171] op_sel_hi:[0,1,1]
	v_add_f32_e32 v105, v106, v107
	v_pk_fma_f32 v[66:67], v[114:115], v[150:151], v[66:67]
	v_pk_fma_f32 v[114:115], v[114:115], v[86:87], v[170:171]
	v_pk_mul_f32 v[170:171], v[98:99], v[158:159] op_sel_hi:[1,0]
	v_add_f32_dpp v105, v105, v105 quad_perm:[1,0,3,2] row_mask:0xf bank_mask:0xf bound_ctrl:1
	s_waitcnt lgkmcnt(2)
	v_pk_fma_f32 v[170:171], v[70:71], v[124:125], v[170:171] op_sel_hi:[0,1,1]
	v_pk_fma_f32 v[66:67], v[172:173], v[152:153], v[66:67]
	v_add_f32_dpp v105, v105, v105 quad_perm:[2,3,0,1] row_mask:0xf bank_mask:0xf bound_ctrl:1
	v_pk_fma_f32 v[170:171], v[172:173], v[90:91], v[170:171]
	v_pk_mul_f32 v[172:173], v[100:101], v[158:159] op_sel_hi:[1,0]
	v_add_f32_dpp v106, v105, v105 row_half_mirror row_mask:0xf bank_mask:0xf bound_ctrl:1
	v_pk_mul_f32 v[94:95], v[94:95], v[158:159] op_sel:[0,1]
	v_pk_mul_f32 v[12:13], v[148:149], v[72:73]
	v_pk_fma_f32 v[70:71], v[70:71], v[126:127], v[172:173] op_sel_hi:[0,1,1]
	v_pk_fma_f32 v[94:95], v[106:107], v[120:121], v[94:95] op_sel_hi:[0,1,1]
	v_pk_fma_f32 v[66:67], v[174:175], v[154:155], v[66:67]
	v_pk_fma_f32 v[12:13], v[74:75], v[150:151], v[12:13]
	v_pk_fma_f32 v[172:173], v[174:175], v[92:93], v[70:71]
	v_pk_fma_f32 v[174:175], v[72:73], v[84:85], v[94:95]
	v_pk_mul_f32 v[72:73], v[96:97], v[158:159] op_sel:[0,1]
	v_pk_fma_f32 v[12:13], v[168:169], v[152:153], v[12:13]
	v_pk_fma_f32 v[72:73], v[106:107], v[122:123], v[72:73] op_sel_hi:[0,1,1]
	v_pk_fma_f32 v[62:63], v[164:165], v[146:147], v[62:63]
	v_pk_fma_f32 v[68:69], v[156:157], v[154:155], v[12:13]
	ds_read_b128 v[12:15], v88 offset:9216
	ds_read_b128 v[16:19], v88 offset:9232
	ds_read_b128 v[20:23], v88 offset:9472
	ds_read_b128 v[24:27], v88 offset:9488
	ds_read_b128 v[76:79], v88 offset:9728
	ds_read_b128 v[80:83], v88 offset:9744
	ds_read_b128 v[144:147], v88 offset:9984
	ds_read_b128 v[148:151], v88 offset:10000
	ds_read_b128 v[152:155], v88 offset:10240
	ds_read_b128 v[160:163], v88 offset:10256
	ds_read2st64_b64 v[164:167], v104 offset0:18 offset1:21
	v_pk_fma_f32 v[176:177], v[74:75], v[86:87], v[72:73]
	s_waitcnt lgkmcnt(6)
	v_pk_mul_f32 v[74:75], v[76:77], v[102:103]
	v_pk_mul_f32 v[72:73], v[98:99], v[158:159] op_sel:[0,1]
	v_pk_fma_f32 v[74:75], v[114:115], v[78:79], v[74:75]
	v_pk_fma_f32 v[72:73], v[106:107], v[124:125], v[72:73] op_sel_hi:[0,1,1]
	s_waitcnt lgkmcnt(5)
	v_pk_fma_f32 v[74:75], v[170:171], v[80:81], v[74:75]
	v_pk_fma_f32 v[168:169], v[168:169], v[90:91], v[72:73]
	v_pk_fma_f32 v[74:75], v[172:173], v[82:83], v[74:75]
	v_pk_mul_f32 v[72:73], v[100:101], v[158:159] op_sel:[0,1]
	v_add_f32_e32 v74, v74, v75
	v_pk_mul_f32 v[76:77], v[76:77], v[174:175]
	v_pk_fma_f32 v[72:73], v[106:107], v[126:127], v[72:73] op_sel_hi:[0,1,1]
	v_add_f32_dpp v74, v74, v74 quad_perm:[1,0,3,2] row_mask:0xf bank_mask:0xf bound_ctrl:1
	s_waitcnt lgkmcnt(0)
	v_pk_mul_f32 v[158:159], v[20:21], v[164:165] op_sel_hi:[1,0]
	v_pk_fma_f32 v[76:77], v[176:177], v[78:79], v[76:77]
	v_add_f32_dpp v74, v74, v74 quad_perm:[2,3,0,1] row_mask:0xf bank_mask:0xf bound_ctrl:1
	v_pk_fma_f32 v[156:157], v[156:157], v[92:93], v[72:73]
	v_pk_fma_f32 v[76:77], v[168:169], v[80:81], v[76:77]
	v_add_f32_dpp v74, v74, v74 row_half_mirror row_mask:0xf bank_mask:0xf bound_ctrl:1
	v_pk_fma_f32 v[158:159], v[74:75], v[144:145], v[158:159] op_sel_hi:[0,1,1]
	v_pk_mul_f32 v[70:71], v[128:129], v[102:103]
	v_pk_fma_f32 v[102:103], v[102:103], v[12:13], v[158:159]
	v_pk_mul_f32 v[158:159], v[22:23], v[164:165] op_sel_hi:[1,0]
	v_pk_fma_f32 v[76:77], v[156:157], v[82:83], v[76:77]
	v_pk_mul_f32 v[72:73], v[128:129], v[174:175]
	v_pk_fma_f32 v[158:159], v[74:75], v[146:147], v[158:159] op_sel_hi:[0,1,1]
	v_add_f32_e32 v76, v76, v77
	v_pk_fma_f32 v[70:71], v[114:115], v[130:131], v[70:71]
	v_pk_fma_f32 v[72:73], v[176:177], v[130:131], v[72:73]
	v_pk_fma_f32 v[114:115], v[114:115], v[14:15], v[158:159]
	v_pk_mul_f32 v[158:159], v[24:25], v[164:165] op_sel_hi:[1,0]
	v_add_f32_dpp v76, v76, v76 quad_perm:[1,0,3,2] row_mask:0xf bank_mask:0xf bound_ctrl:1
	v_pk_fma_f32 v[70:71], v[170:171], v[132:133], v[70:71]
	v_pk_fma_f32 v[72:73], v[168:169], v[132:133], v[72:73]
	v_pk_fma_f32 v[158:159], v[74:75], v[148:149], v[158:159] op_sel_hi:[0,1,1]
	v_add_f32_dpp v76, v76, v76 quad_perm:[2,3,0,1] row_mask:0xf bank_mask:0xf bound_ctrl:1
	v_pk_fma_f32 v[70:71], v[172:173], v[134:135], v[70:71]
	v_pk_fma_f32 v[72:73], v[156:157], v[134:135], v[72:73]
	ds_read_b128 v[84:87], v88 offset:10752
	ds_read_b128 v[90:93], v88 offset:10768
	ds_read_b128 v[94:97], v88 offset:11008
	ds_read_b128 v[98:101], v88 offset:11024
	ds_read_b128 v[106:109], v88 offset:11264
	ds_read_b128 v[110:113], v88 offset:11280
	ds_read_b128 v[120:123], v88 offset:11520
	ds_read_b128 v[124:127], v88 offset:11536
	ds_read_b128 v[128:131], v88 offset:11776
	ds_read_b128 v[132:135], v88 offset:11792
	v_pk_fma_f32 v[178:179], v[170:171], v[16:17], v[158:159]
	v_pk_mul_f32 v[158:159], v[26:27], v[164:165] op_sel_hi:[1,0]
	v_add_f32_dpp v76, v76, v76 row_half_mirror row_mask:0xf bank_mask:0xf bound_ctrl:1
	v_pk_mul_f32 v[20:21], v[20:21], v[164:165] op_sel:[0,1]
	s_waitcnt lgkmcnt(5)
	v_pk_mul_f32 v[78:79], v[106:107], v[102:103]
	v_pk_fma_f32 v[74:75], v[74:75], v[150:151], v[158:159] op_sel_hi:[0,1,1]
	v_pk_fma_f32 v[20:21], v[76:77], v[144:145], v[20:21] op_sel_hi:[0,1,1]
	v_pk_fma_f32 v[78:79], v[114:115], v[108:109], v[78:79]
	v_pk_fma_f32 v[180:181], v[172:173], v[18:19], v[74:75]
	v_pk_fma_f32 v[80:81], v[174:175], v[12:13], v[20:21]
	v_pk_mul_f32 v[12:13], v[22:23], v[164:165] op_sel:[0,1]
	s_waitcnt lgkmcnt(4)
	v_pk_fma_f32 v[78:79], v[178:179], v[110:111], v[78:79]
	v_pk_fma_f32 v[12:13], v[76:77], v[146:147], v[12:13] op_sel_hi:[0,1,1]
	v_pk_fma_f32 v[78:79], v[180:181], v[112:113], v[78:79]
	v_pk_fma_f32 v[82:83], v[176:177], v[14:15], v[12:13]
	v_pk_mul_f32 v[12:13], v[24:25], v[164:165] op_sel:[0,1]
	v_add_f32_e32 v78, v78, v79
	v_pk_fma_f32 v[12:13], v[76:77], v[148:149], v[12:13] op_sel_hi:[0,1,1]
	v_pk_fma_f32 v[176:177], v[168:169], v[16:17], v[12:13]
	v_add_f32_dpp v78, v78, v78 quad_perm:[1,0,3,2] row_mask:0xf bank_mask:0xf bound_ctrl:1
	v_pk_mul_f32 v[12:13], v[26:27], v[164:165] op_sel:[0,1]
	v_pk_mul_f32 v[106:107], v[106:107], v[80:81]
	v_add_f32_dpp v78, v78, v78 quad_perm:[2,3,0,1] row_mask:0xf bank_mask:0xf bound_ctrl:1
	v_pk_fma_f32 v[12:13], v[76:77], v[150:151], v[12:13] op_sel_hi:[0,1,1]
	v_pk_mul_f32 v[182:183], v[94:95], v[166:167] op_sel_hi:[1,0]
	v_add_f32_dpp v78, v78, v78 row_half_mirror row_mask:0xf bank_mask:0xf bound_ctrl:1
	v_pk_fma_f32 v[106:107], v[82:83], v[108:109], v[106:107]
	v_pk_fma_f32 v[164:165], v[156:157], v[18:19], v[12:13]
	s_waitcnt lgkmcnt(3)
	v_pk_fma_f32 v[182:183], v[78:79], v[120:121], v[182:183] op_sel_hi:[0,1,1]
	v_pk_fma_f32 v[106:107], v[176:177], v[110:111], v[106:107]
	v_pk_mul_f32 v[74:75], v[152:153], v[102:103]
	v_pk_fma_f32 v[102:103], v[102:103], v[84:85], v[182:183]
	v_pk_mul_f32 v[182:183], v[96:97], v[166:167] op_sel_hi:[1,0]
	v_pk_fma_f32 v[106:107], v[164:165], v[112:113], v[106:107]
	v_pk_fma_f32 v[182:183], v[78:79], v[122:123], v[182:183] op_sel_hi:[0,1,1]
	v_add_f32_e32 v105, v106, v107
	v_pk_fma_f32 v[74:75], v[114:115], v[154:155], v[74:75]
	v_pk_mul_f32 v[12:13], v[152:153], v[80:81]
	v_pk_fma_f32 v[114:115], v[114:115], v[86:87], v[182:183]
	v_pk_mul_f32 v[182:183], v[98:99], v[166:167] op_sel_hi:[1,0]
	v_add_f32_dpp v105, v105, v105 quad_perm:[1,0,3,2] row_mask:0xf bank_mask:0xf bound_ctrl:1
	v_pk_fma_f32 v[12:13], v[82:83], v[154:155], v[12:13]
	s_waitcnt lgkmcnt(2)
	v_pk_fma_f32 v[182:183], v[78:79], v[124:125], v[182:183] op_sel_hi:[0,1,1]
	v_add_f32_dpp v105, v105, v105 quad_perm:[2,3,0,1] row_mask:0xf bank_mask:0xf bound_ctrl:1
	v_pk_fma_f32 v[74:75], v[178:179], v[160:161], v[74:75]
	v_pk_fma_f32 v[12:13], v[176:177], v[160:161], v[12:13]
	v_pk_fma_f32 v[178:179], v[178:179], v[90:91], v[182:183]
	v_pk_mul_f32 v[182:183], v[100:101], v[166:167] op_sel_hi:[1,0]
	v_add_f32_dpp v106, v105, v105 row_half_mirror row_mask:0xf bank_mask:0xf bound_ctrl:1
	v_pk_mul_f32 v[94:95], v[94:95], v[166:167] op_sel:[0,1]
	v_pk_fma_f32 v[74:75], v[180:181], v[162:163], v[74:75]
	v_pk_fma_f32 v[76:77], v[164:165], v[162:163], v[12:13]
	ds_read_b128 v[12:15], v88 offset:12288
	ds_read_b128 v[16:19], v88 offset:12304
	ds_read_b128 v[20:23], v88 offset:12544
	ds_read_b128 v[24:27], v88 offset:12560
	ds_read_b128 v[144:147], v88 offset:12800
	ds_read_b128 v[148:151], v88 offset:12816
	ds_read_b128 v[152:155], v88 offset:13056
	ds_read_b128 v[156:159], v88 offset:13072
	ds_read_b128 v[160:163], v88 offset:13312
	ds_read_b128 v[168:171], v88 offset:13328
	ds_read2st64_b64 v[172:175], v104 offset0:24 offset1:27
	v_pk_fma_f32 v[78:79], v[78:79], v[126:127], v[182:183] op_sel_hi:[0,1,1]
	v_pk_fma_f32 v[94:95], v[106:107], v[120:121], v[94:95] op_sel_hi:[0,1,1]
	s_waitcnt lgkmcnt(6)
	v_pk_mul_f32 v[182:183], v[144:145], v[102:103]
	v_pk_fma_f32 v[84:85], v[80:81], v[84:85], v[94:95]
	v_pk_mul_f32 v[80:81], v[96:97], v[166:167] op_sel:[0,1]
	v_pk_fma_f32 v[182:183], v[114:115], v[146:147], v[182:183]
	v_pk_fma_f32 v[180:181], v[180:181], v[92:93], v[78:79]
	v_pk_fma_f32 v[80:81], v[106:107], v[122:123], v[80:81] op_sel_hi:[0,1,1]
	s_waitcnt lgkmcnt(5)
	v_pk_fma_f32 v[182:183], v[178:179], v[148:149], v[182:183]
	v_pk_fma_f32 v[82:83], v[82:83], v[86:87], v[80:81]
	v_pk_mul_f32 v[80:81], v[98:99], v[166:167] op_sel:[0,1]
	v_pk_fma_f32 v[182:183], v[180:181], v[150:151], v[182:183]
	v_pk_fma_f32 v[80:81], v[106:107], v[124:125], v[80:81] op_sel_hi:[0,1,1]
	v_add_f32_e32 v105, v182, v183
	v_pk_fma_f32 v[86:87], v[176:177], v[90:91], v[80:81]
	v_pk_mul_f32 v[80:81], v[100:101], v[166:167] op_sel:[0,1]
	v_add_f32_dpp v105, v105, v105 quad_perm:[1,0,3,2] row_mask:0xf bank_mask:0xf bound_ctrl:1
	v_pk_mul_f32 v[144:145], v[144:145], v[84:85]
	v_pk_fma_f32 v[80:81], v[106:107], v[126:127], v[80:81] op_sel_hi:[0,1,1]
	v_add_f32_dpp v105, v105, v105 quad_perm:[2,3,0,1] row_mask:0xf bank_mask:0xf bound_ctrl:1
	v_pk_fma_f32 v[144:145], v[82:83], v[146:147], v[144:145]
	v_pk_fma_f32 v[176:177], v[164:165], v[92:93], v[80:81]
	v_add_f32_dpp v182, v105, v105 row_half_mirror row_mask:0xf bank_mask:0xf bound_ctrl:1
	s_waitcnt lgkmcnt(0)
	v_pk_mul_f32 v[184:185], v[20:21], v[172:173] op_sel_hi:[1,0]
	v_pk_fma_f32 v[144:145], v[86:87], v[148:149], v[144:145]
	v_pk_fma_f32 v[184:185], v[182:183], v[152:153], v[184:185] op_sel_hi:[0,1,1]
	v_pk_fma_f32 v[144:145], v[176:177], v[150:151], v[144:145]
	v_pk_mul_f32 v[78:79], v[128:129], v[102:103]
	v_pk_fma_f32 v[102:103], v[102:103], v[12:13], v[184:185]
	v_pk_mul_f32 v[184:185], v[22:23], v[172:173] op_sel_hi:[1,0]
	v_add_f32_e32 v105, v144, v145
	v_pk_mul_f32 v[80:81], v[128:129], v[84:85]
	v_pk_fma_f32 v[184:185], v[182:183], v[154:155], v[184:185] op_sel_hi:[0,1,1]
	v_add_f32_dpp v105, v105, v105 quad_perm:[1,0,3,2] row_mask:0xf bank_mask:0xf bound_ctrl:1
	v_pk_fma_f32 v[78:79], v[114:115], v[130:131], v[78:79]
	v_pk_fma_f32 v[80:81], v[82:83], v[130:131], v[80:81]
	v_pk_fma_f32 v[114:115], v[114:115], v[14:15], v[184:185]
	v_pk_mul_f32 v[184:185], v[24:25], v[172:173] op_sel_hi:[1,0]
	v_add_f32_dpp v105, v105, v105 quad_perm:[2,3,0,1] row_mask:0xf bank_mask:0xf bound_ctrl:1
	v_pk_fma_f32 v[78:79], v[178:179], v[132:133], v[78:79]
	v_pk_fma_f32 v[80:81], v[86:87], v[132:133], v[80:81]
	v_pk_fma_f32 v[184:185], v[182:183], v[156:157], v[184:185] op_sel_hi:[0,1,1]
	v_add_f32_dpp v144, v105, v105 row_half_mirror row_mask:0xf bank_mask:0xf bound_ctrl:1
	v_pk_mul_f32 v[20:21], v[20:21], v[172:173] op_sel:[0,1]
	v_pk_fma_f32 v[78:79], v[180:181], v[134:135], v[78:79]
	v_pk_fma_f32 v[80:81], v[176:177], v[134:135], v[80:81]
	ds_read_b128 v[90:93], v88 offset:13824
	ds_read_b128 v[94:97], v88 offset:13840
	ds_read_b128 v[98:101], v88 offset:14080
	ds_read_b128 v[106:109], v88 offset:14096
	ds_read_b128 v[110:113], v88 offset:14336
	ds_read_b128 v[120:123], v88 offset:14352
	ds_read_b128 v[124:127], v88 offset:14592
	ds_read_b128 v[128:131], v88 offset:14608
	ds_read_b128 v[132:135], v88 offset:14848
	ds_read_b128 v[164:167], v88 offset:14864
	v_pk_fma_f32 v[184:185], v[178:179], v[16:17], v[184:185]
	v_pk_mul_f32 v[178:179], v[26:27], v[172:173] op_sel_hi:[1,0]
	v_pk_fma_f32 v[20:21], v[144:145], v[152:153], v[20:21] op_sel_hi:[0,1,1]
	s_waitcnt lgkmcnt(5)
	v_pk_mul_f32 v[188:189], v[110:111], v[102:103]
	v_pk_fma_f32 v[178:179], v[182:183], v[158:159], v[178:179] op_sel_hi:[0,1,1]
	v_pk_fma_f32 v[182:183], v[84:85], v[12:13], v[20:21]
	v_pk_mul_f32 v[12:13], v[22:23], v[172:173] op_sel:[0,1]
	v_pk_fma_f32 v[188:189], v[114:115], v[112:113], v[188:189]
	v_pk_fma_f32 v[180:181], v[180:181], v[18:19], v[178:179]
	v_pk_fma_f32 v[12:13], v[144:145], v[154:155], v[12:13] op_sel_hi:[0,1,1]
	s_waitcnt lgkmcnt(4)
	v_pk_fma_f32 v[188:189], v[184:185], v[120:121], v[188:189]
	v_pk_fma_f32 v[186:187], v[82:83], v[14:15], v[12:13]
	v_pk_mul_f32 v[12:13], v[24:25], v[172:173] op_sel:[0,1]
	v_pk_fma_f32 v[188:189], v[180:181], v[122:123], v[188:189]
	v_pk_fma_f32 v[12:13], v[144:145], v[156:157], v[12:13] op_sel_hi:[0,1,1]
	v_add_f32_e32 v105, v188, v189
	v_pk_fma_f32 v[86:87], v[86:87], v[16:17], v[12:13]
	v_pk_mul_f32 v[12:13], v[26:27], v[172:173] op_sel:[0,1]
	v_add_f32_dpp v105, v105, v105 quad_perm:[1,0,3,2] row_mask:0xf bank_mask:0xf bound_ctrl:1
	v_pk_mul_f32 v[110:111], v[110:111], v[182:183]
	v_pk_fma_f32 v[12:13], v[144:145], v[158:159], v[12:13] op_sel_hi:[0,1,1]
	v_add_f32_dpp v105, v105, v105 quad_perm:[2,3,0,1] row_mask:0xf bank_mask:0xf bound_ctrl:1
	v_pk_fma_f32 v[110:111], v[186:187], v[112:113], v[110:111]
	v_pk_fma_f32 v[172:173], v[176:177], v[18:19], v[12:13]
	v_add_f32_dpp v188, v105, v105 row_half_mirror row_mask:0xf bank_mask:0xf bound_ctrl:1
	v_pk_mul_f32 v[190:191], v[98:99], v[174:175] op_sel_hi:[1,0]
	v_pk_fma_f32 v[110:111], v[86:87], v[120:121], v[110:111]
	s_waitcnt lgkmcnt(3)
	v_pk_fma_f32 v[190:191], v[188:189], v[124:125], v[190:191] op_sel_hi:[0,1,1]
	v_pk_fma_f32 v[110:111], v[172:173], v[122:123], v[110:111]
	v_pk_mul_f32 v[178:179], v[160:161], v[102:103]
	v_pk_fma_f32 v[102:103], v[102:103], v[90:91], v[190:191]
	v_pk_mul_f32 v[190:191], v[100:101], v[174:175] op_sel_hi:[1,0]
	v_add_f32_e32 v105, v110, v111
	v_pk_mul_f32 v[12:13], v[160:161], v[182:183]
	v_pk_fma_f32 v[190:191], v[188:189], v[126:127], v[190:191] op_sel_hi:[0,1,1]
	v_add_f32_dpp v105, v105, v105 quad_perm:[1,0,3,2] row_mask:0xf bank_mask:0xf bound_ctrl:1
	v_pk_fma_f32 v[178:179], v[114:115], v[162:163], v[178:179]
	v_pk_fma_f32 v[12:13], v[186:187], v[162:163], v[12:13]
	v_pk_fma_f32 v[114:115], v[114:115], v[92:93], v[190:191]
	v_pk_mul_f32 v[190:191], v[106:107], v[174:175] op_sel_hi:[1,0]
	v_add_f32_dpp v105, v105, v105 quad_perm:[2,3,0,1] row_mask:0xf bank_mask:0xf bound_ctrl:1
	v_pk_fma_f32 v[178:179], v[184:185], v[168:169], v[178:179]
	v_pk_fma_f32 v[12:13], v[86:87], v[168:169], v[12:13]
	s_waitcnt lgkmcnt(2)
	v_pk_fma_f32 v[190:191], v[188:189], v[128:129], v[190:191] op_sel_hi:[0,1,1]
	v_add_f32_dpp v110, v105, v105 row_half_mirror row_mask:0xf bank_mask:0xf bound_ctrl:1
	v_pk_mul_f32 v[98:99], v[98:99], v[174:175] op_sel:[0,1]
	v_pk_fma_f32 v[178:179], v[180:181], v[170:171], v[178:179]
	v_pk_fma_f32 v[12:13], v[172:173], v[170:171], v[12:13]
	v_pk_fma_f32 v[184:185], v[184:185], v[94:95], v[190:191]
	v_pk_mul_f32 v[190:191], v[108:109], v[174:175] op_sel_hi:[1,0]
	v_pk_fma_f32 v[98:99], v[110:111], v[124:125], v[98:99] op_sel_hi:[0,1,1]
	v_add_f32_e32 v226, v178, v179
	v_add_f32_e32 v234, v12, v13
	v_pk_fma_f32 v[188:189], v[188:189], v[130:131], v[190:191] op_sel_hi:[0,1,1]
	v_pk_fma_f32 v[190:191], v[182:183], v[90:91], v[98:99]
	v_pk_mul_f32 v[90:91], v[100:101], v[174:175] op_sel:[0,1]
	v_pk_fma_f32 v[90:91], v[110:111], v[126:127], v[90:91] op_sel_hi:[0,1,1]
	v_pk_fma_f32 v[186:187], v[186:187], v[92:93], v[90:91]
	v_pk_mul_f32 v[90:91], v[106:107], v[174:175] op_sel:[0,1]
	ds_read_b128 v[12:15], v88 offset:15360
	ds_read_b128 v[16:19], v88 offset:15376
	ds_read_b128 v[20:23], v88 offset:15616
	ds_read_b128 v[24:27], v88 offset:15632
	ds_read_b128 v[144:147], v88 offset:15872
	ds_read_b128 v[148:151], v88 offset:15888
	ds_read_b128 v[152:155], v88 offset:16128
	ds_read_b128 v[156:159], v88 offset:16144
	ds_read_b128 v[160:163], v88 offset:16384
	ds_read_b128 v[168:171], v88 offset:16400
	ds_read2st64_b64 v[176:179], v104 offset0:30 offset1:33
	v_pk_fma_f32 v[90:91], v[110:111], v[128:129], v[90:91] op_sel_hi:[0,1,1]
	v_pk_fma_f32 v[94:95], v[86:87], v[94:95], v[90:91]
	v_pk_mul_f32 v[86:87], v[108:109], v[174:175] op_sel:[0,1]
	s_waitcnt lgkmcnt(6)
	v_pk_mul_f32 v[92:93], v[144:145], v[102:103]
	v_pk_mul_f32 v[144:145], v[144:145], v[190:191]
	v_pk_fma_f32 v[86:87], v[110:111], v[130:131], v[86:87] op_sel_hi:[0,1,1]
	v_pk_fma_f32 v[92:93], v[114:115], v[146:147], v[92:93]
	v_pk_fma_f32 v[144:145], v[186:187], v[146:147], v[144:145]
	v_pk_fma_f32 v[188:189], v[180:181], v[96:97], v[188:189]
	v_pk_fma_f32 v[96:97], v[172:173], v[96:97], v[86:87]
	s_waitcnt lgkmcnt(5)
	v_pk_fma_f32 v[92:93], v[184:185], v[148:149], v[92:93]
	v_pk_fma_f32 v[144:145], v[94:95], v[148:149], v[144:145]
	v_pk_fma_f32 v[92:93], v[188:189], v[150:151], v[92:93]
	v_pk_fma_f32 v[144:145], v[96:97], v[150:151], v[144:145]
	v_add_f32_e32 v92, v92, v93
	v_add_f32_e32 v105, v144, v145
	s_waitcnt lgkmcnt(0)
	v_pk_mul_f32 v[192:193], v[20:21], v[176:177] op_sel_hi:[1,0]
	v_add_f32_dpp v92, v92, v92 quad_perm:[1,0,3,2] row_mask:0xf bank_mask:0xf bound_ctrl:1
	v_add_f32_dpp v105, v105, v105 quad_perm:[1,0,3,2] row_mask:0xf bank_mask:0xf bound_ctrl:1
	v_pk_mul_f32 v[20:21], v[20:21], v[176:177] op_sel:[0,1]
	v_add_f32_dpp v92, v92, v92 quad_perm:[2,3,0,1] row_mask:0xf bank_mask:0xf bound_ctrl:1
	v_add_f32_dpp v105, v105, v105 quad_perm:[2,3,0,1] row_mask:0xf bank_mask:0xf bound_ctrl:1
	v_pk_mul_f32 v[180:181], v[132:133], v[102:103]
	v_add_f32_dpp v92, v92, v92 row_half_mirror row_mask:0xf bank_mask:0xf bound_ctrl:1
	v_add_f32_dpp v144, v105, v105 row_half_mirror row_mask:0xf bank_mask:0xf bound_ctrl:1
	v_pk_fma_f32 v[192:193], v[92:93], v[152:153], v[192:193] op_sel_hi:[0,1,1]
	v_pk_fma_f32 v[20:21], v[144:145], v[152:153], v[20:21] op_sel_hi:[0,1,1]
	v_pk_mul_f32 v[86:87], v[132:133], v[190:191]
	v_pk_fma_f32 v[102:103], v[102:103], v[12:13], v[192:193]
	v_pk_fma_f32 v[190:191], v[190:191], v[12:13], v[20:21]
	v_pk_mul_f32 v[12:13], v[22:23], v[176:177] op_sel:[0,1]
	v_pk_mul_f32 v[192:193], v[22:23], v[176:177] op_sel_hi:[1,0]
	v_pk_fma_f32 v[12:13], v[144:145], v[154:155], v[12:13] op_sel_hi:[0,1,1]
	v_pk_fma_f32 v[194:195], v[186:187], v[14:15], v[12:13]
	v_pk_mul_f32 v[12:13], v[24:25], v[176:177] op_sel:[0,1]
	v_pk_fma_f32 v[180:181], v[114:115], v[134:135], v[180:181]
	v_pk_fma_f32 v[86:87], v[186:187], v[134:135], v[86:87]
	v_pk_fma_f32 v[192:193], v[92:93], v[154:155], v[192:193] op_sel_hi:[0,1,1]
	v_pk_fma_f32 v[12:13], v[144:145], v[156:157], v[12:13] op_sel_hi:[0,1,1]
	v_pk_fma_f32 v[180:181], v[184:185], v[164:165], v[180:181]
	v_pk_fma_f32 v[86:87], v[94:95], v[164:165], v[86:87]
	v_pk_fma_f32 v[114:115], v[114:115], v[14:15], v[192:193]
	v_pk_mul_f32 v[192:193], v[24:25], v[176:177] op_sel_hi:[1,0]
	v_pk_fma_f32 v[196:197], v[94:95], v[16:17], v[12:13]
	v_pk_mul_f32 v[12:13], v[26:27], v[176:177] op_sel:[0,1]
	v_pk_fma_f32 v[180:181], v[188:189], v[166:167], v[180:181]
	v_pk_fma_f32 v[86:87], v[96:97], v[166:167], v[86:87]
	v_pk_fma_f32 v[192:193], v[92:93], v[156:157], v[192:193] op_sel_hi:[0,1,1]
	v_pk_fma_f32 v[12:13], v[144:145], v[158:159], v[12:13] op_sel_hi:[0,1,1]
	v_add_f32_e32 v227, v180, v181
	v_add_f32_e32 v235, v86, v87
	ds_read_b128 v[98:101], v88 offset:16896
	ds_read_b128 v[106:109], v88 offset:16912
	ds_read_b128 v[110:113], v88 offset:17152
	ds_read_b128 v[120:123], v88 offset:17168
	ds_read_b128 v[124:127], v88 offset:17408
	ds_read_b128 v[128:131], v88 offset:17424
	ds_read_b128 v[132:135], v88 offset:17664
	ds_read_b128 v[164:167], v88 offset:17680
	ds_read_b128 v[172:175], v88 offset:17920
	ds_read_b128 v[180:183], v88 offset:17936
	v_pk_fma_f32 v[192:193], v[184:185], v[16:17], v[192:193]
	v_pk_mul_f32 v[184:185], v[26:27], v[176:177] op_sel_hi:[1,0]
	v_pk_fma_f32 v[176:177], v[96:97], v[18:19], v[12:13]
	s_waitcnt lgkmcnt(5)
	v_pk_mul_f32 v[96:97], v[124:125], v[102:103]
	v_pk_fma_f32 v[92:93], v[92:93], v[158:159], v[184:185] op_sel_hi:[0,1,1]
	v_pk_fma_f32 v[96:97], v[114:115], v[126:127], v[96:97]
	v_pk_fma_f32 v[188:189], v[188:189], v[18:19], v[92:93]
	s_waitcnt lgkmcnt(4)
	v_pk_fma_f32 v[96:97], v[192:193], v[128:129], v[96:97]
	v_pk_mul_f32 v[124:125], v[124:125], v[190:191]
	v_pk_fma_f32 v[96:97], v[188:189], v[130:131], v[96:97]
	v_pk_fma_f32 v[124:125], v[194:195], v[126:127], v[124:125]
	v_add_f32_e32 v96, v96, v97
	v_pk_fma_f32 v[124:125], v[196:197], v[128:129], v[124:125]
	v_pk_mul_f32 v[198:199], v[110:111], v[178:179] op_sel_hi:[1,0]
	v_add_f32_dpp v96, v96, v96 quad_perm:[1,0,3,2] row_mask:0xf bank_mask:0xf bound_ctrl:1
	v_pk_fma_f32 v[124:125], v[176:177], v[130:131], v[124:125]
	v_pk_mul_f32 v[92:93], v[160:161], v[102:103]
	v_add_f32_dpp v96, v96, v96 quad_perm:[2,3,0,1] row_mask:0xf bank_mask:0xf bound_ctrl:1
	v_add_f32_e32 v105, v124, v125
	v_pk_mul_f32 v[110:111], v[110:111], v[178:179] op_sel:[0,1]
	v_add_f32_dpp v96, v96, v96 row_half_mirror row_mask:0xf bank_mask:0xf bound_ctrl:1
	v_add_f32_dpp v105, v105, v105 quad_perm:[1,0,3,2] row_mask:0xf bank_mask:0xf bound_ctrl:1
	s_waitcnt lgkmcnt(3)
	v_pk_fma_f32 v[198:199], v[96:97], v[132:133], v[198:199] op_sel_hi:[0,1,1]
	v_pk_fma_f32 v[102:103], v[102:103], v[98:99], v[198:199]
	v_add_f32_dpp v105, v105, v105 quad_perm:[2,3,0,1] row_mask:0xf bank_mask:0xf bound_ctrl:1
	v_pk_mul_f32 v[198:199], v[112:113], v[178:179] op_sel_hi:[1,0]
	v_pk_mul_f32 v[12:13], v[160:161], v[190:191]
	v_add_f32_dpp v124, v105, v105 row_half_mirror row_mask:0xf bank_mask:0xf bound_ctrl:1
	v_pk_fma_f32 v[198:199], v[96:97], v[134:135], v[198:199] op_sel_hi:[0,1,1]
	v_pk_fma_f32 v[110:111], v[124:125], v[132:133], v[110:111] op_sel_hi:[0,1,1]
	v_pk_fma_f32 v[92:93], v[114:115], v[162:163], v[92:93]
	v_pk_fma_f32 v[12:13], v[194:195], v[162:163], v[12:13]
	v_pk_fma_f32 v[114:115], v[114:115], v[100:101], v[198:199]
	v_pk_mul_f32 v[198:199], v[120:121], v[178:179] op_sel_hi:[1,0]
	v_pk_fma_f32 v[190:191], v[190:191], v[98:99], v[110:111]
	v_pk_mul_f32 v[98:99], v[112:113], v[178:179] op_sel:[0,1]
	v_pk_fma_f32 v[92:93], v[192:193], v[168:169], v[92:93]
	v_pk_fma_f32 v[12:13], v[196:197], v[168:169], v[12:13]
	s_waitcnt lgkmcnt(2)
	v_pk_fma_f32 v[198:199], v[96:97], v[164:165], v[198:199] op_sel_hi:[0,1,1]
	v_pk_fma_f32 v[98:99], v[124:125], v[134:135], v[98:99] op_sel_hi:[0,1,1]
	v_pk_fma_f32 v[92:93], v[188:189], v[170:171], v[92:93]
	v_pk_fma_f32 v[94:95], v[176:177], v[170:171], v[12:13]
	ds_read_b128 v[12:15], v88 offset:18432
	ds_read_b128 v[16:19], v88 offset:18448
	ds_read_b128 v[20:23], v88 offset:18688
	ds_read_b128 v[24:27], v88 offset:18704
	ds_read_b128 v[144:147], v88 offset:18944
	ds_read_b128 v[148:151], v88 offset:18960
	ds_read_b128 v[152:155], v88 offset:19200
	ds_read_b128 v[156:159], v88 offset:19216
	ds_read_b128 v[160:163], v88 offset:19456
	ds_read_b128 v[168:171], v88 offset:19472
	ds_read2st64_b64 v[184:187], v104 offset0:36 offset1:39
	v_pk_fma_f32 v[192:193], v[192:193], v[106:107], v[198:199]
	v_pk_mul_f32 v[198:199], v[122:123], v[178:179] op_sel_hi:[1,0]
	v_pk_fma_f32 v[194:195], v[194:195], v[100:101], v[98:99]
	s_waitcnt lgkmcnt(6)
	v_pk_mul_f32 v[100:101], v[144:145], v[102:103]
	v_pk_fma_f32 v[96:97], v[96:97], v[166:167], v[198:199] op_sel_hi:[0,1,1]
	v_pk_fma_f32 v[100:101], v[114:115], v[146:147], v[100:101]
	v_pk_fma_f32 v[188:189], v[188:189], v[108:109], v[96:97]
	s_waitcnt lgkmcnt(5)
	v_pk_fma_f32 v[100:101], v[192:193], v[148:149], v[100:101]
	s_waitcnt lgkmcnt(0)
	v_pk_mul_f32 v[200:201], v[20:21], v[184:185] op_sel_hi:[1,0]
	v_pk_fma_f32 v[100:101], v[188:189], v[150:151], v[100:101]
	v_pk_mul_f32 v[96:97], v[172:173], v[102:103]
	v_add_f32_e32 v100, v100, v101
	v_pk_fma_f32 v[96:97], v[114:115], v[174:175], v[96:97]
	v_pk_mul_f32 v[98:99], v[120:121], v[178:179] op_sel:[0,1]
	v_add_f32_dpp v100, v100, v100 quad_perm:[1,0,3,2] row_mask:0xf bank_mask:0xf bound_ctrl:1
	v_pk_fma_f32 v[96:97], v[192:193], v[180:181], v[96:97]
	v_pk_fma_f32 v[98:99], v[124:125], v[164:165], v[98:99] op_sel_hi:[0,1,1]
	v_add_f32_dpp v100, v100, v100 quad_perm:[2,3,0,1] row_mask:0xf bank_mask:0xf bound_ctrl:1
	v_pk_fma_f32 v[196:197], v[196:197], v[106:107], v[98:99]
	v_pk_mul_f32 v[98:99], v[122:123], v[178:179] op_sel:[0,1]
	v_add_f32_dpp v100, v100, v100 row_half_mirror row_mask:0xf bank_mask:0xf bound_ctrl:1
	v_pk_fma_f32 v[200:201], v[100:101], v[152:153], v[200:201] op_sel_hi:[0,1,1]
	v_pk_fma_f32 v[200:201], v[102:103], v[12:13], v[200:201]
	v_pk_mul_f32 v[102:103], v[22:23], v[184:185] op_sel_hi:[1,0]
	v_pk_fma_f32 v[98:99], v[124:125], v[166:167], v[98:99] op_sel_hi:[0,1,1]
	v_pk_fma_f32 v[102:103], v[100:101], v[154:155], v[102:103] op_sel_hi:[0,1,1]
	v_pk_fma_f32 v[114:115], v[114:115], v[14:15], v[102:103]
	v_pk_mul_f32 v[102:103], v[24:25], v[184:185] op_sel_hi:[1,0]
	v_pk_fma_f32 v[198:199], v[176:177], v[108:109], v[98:99]
	v_pk_fma_f32 v[102:103], v[100:101], v[156:157], v[102:103] op_sel_hi:[0,1,1]
	v_pk_fma_f32 v[192:193], v[192:193], v[16:17], v[102:103]
	v_pk_mul_f32 v[102:103], v[26:27], v[184:185] op_sel_hi:[1,0]
	v_pk_mul_f32 v[20:21], v[20:21], v[184:185] op_sel:[0,1]
	v_pk_fma_f32 v[100:101], v[100:101], v[158:159], v[102:103] op_sel_hi:[0,1,1]
	v_pk_mul_f32 v[102:103], v[144:145], v[190:191]
	v_pk_mul_f32 v[98:99], v[172:173], v[190:191]
	v_pk_fma_f32 v[102:103], v[194:195], v[146:147], v[102:103]
	v_pk_fma_f32 v[98:99], v[194:195], v[174:175], v[98:99]
	v_pk_fma_f32 v[102:103], v[196:197], v[148:149], v[102:103]
	v_pk_fma_f32 v[98:99], v[196:197], v[180:181], v[98:99]
	v_pk_fma_f32 v[102:103], v[198:199], v[150:151], v[102:103]
	v_pk_fma_f32 v[202:203], v[188:189], v[18:19], v[100:101]
	v_add_f32_e32 v102, v102, v103
	v_pk_mul_f32 v[100:101], v[160:161], v[200:201]
	v_pk_fma_f32 v[96:97], v[188:189], v[182:183], v[96:97]
	v_add_f32_dpp v102, v102, v102 quad_perm:[1,0,3,2] row_mask:0xf bank_mask:0xf bound_ctrl:1
	v_pk_fma_f32 v[100:101], v[114:115], v[162:163], v[100:101]
	v_pk_fma_f32 v[98:99], v[198:199], v[182:183], v[98:99]
	v_add_f32_dpp v102, v102, v102 quad_perm:[2,3,0,1] row_mask:0xf bank_mask:0xf bound_ctrl:1
	ds_read_b128 v[106:109], v88 offset:19968
	ds_read_b128 v[110:113], v88 offset:19984
	ds_read_b128 v[120:123], v88 offset:20224
	ds_read_b128 v[124:127], v88 offset:20240
	ds_read_b128 v[128:131], v88 offset:20480
	ds_read_b128 v[132:135], v88 offset:20496
	ds_read_b128 v[164:167], v88 offset:20736
	ds_read_b128 v[172:175], v88 offset:20752
	ds_read_b128 v[176:179], v88 offset:20992
	ds_read_b128 v[180:183], v88 offset:21008
	v_add_f32_dpp v102, v102, v102 row_half_mirror row_mask:0xf bank_mask:0xf bound_ctrl:1
	v_pk_fma_f32 v[20:21], v[102:103], v[152:153], v[20:21] op_sel_hi:[0,1,1]
	v_pk_fma_f32 v[204:205], v[190:191], v[12:13], v[20:21]
	v_pk_mul_f32 v[12:13], v[22:23], v[184:185] op_sel:[0,1]
	v_pk_fma_f32 v[100:101], v[192:193], v[168:169], v[100:101]
	v_pk_fma_f32 v[12:13], v[102:103], v[154:155], v[12:13] op_sel_hi:[0,1,1]
	v_pk_fma_f32 v[194:195], v[194:195], v[14:15], v[12:13]
	v_pk_mul_f32 v[12:13], v[24:25], v[184:185] op_sel:[0,1]
	v_pk_fma_f32 v[100:101], v[202:203], v[170:171], v[100:101]
	v_pk_fma_f32 v[12:13], v[102:103], v[156:157], v[12:13] op_sel_hi:[0,1,1]
	v_pk_fma_f32 v[196:197], v[196:197], v[16:17], v[12:13]
	v_pk_mul_f32 v[12:13], v[26:27], v[184:185] op_sel:[0,1]
	v_pk_fma_f32 v[12:13], v[102:103], v[158:159], v[12:13] op_sel_hi:[0,1,1]
	v_pk_fma_f32 v[184:185], v[198:199], v[18:19], v[12:13]
	v_pk_mul_f32 v[12:13], v[160:161], v[204:205]
	s_waitcnt lgkmcnt(7)
	v_pk_mul_f32 v[198:199], v[120:121], v[186:187] op_sel_hi:[1,0]
	v_pk_fma_f32 v[12:13], v[194:195], v[162:163], v[12:13]
	v_pk_mul_f32 v[120:121], v[120:121], v[186:187] op_sel:[0,1]
	v_pk_fma_f32 v[12:13], v[196:197], v[168:169], v[12:13]
	v_pk_fma_f32 v[102:103], v[184:185], v[170:171], v[12:13]
	ds_read_b128 v[12:15], v88 offset:21504
	ds_read_b128 v[16:19], v88 offset:21520
	ds_read_b128 v[20:23], v88 offset:21760
	ds_read_b128 v[24:27], v88 offset:21776
	ds_read_b128 v[144:147], v88 offset:22016
	ds_read_b128 v[148:151], v88 offset:22032
	ds_read_b128 v[152:155], v88 offset:22272
	ds_read_b128 v[156:159], v88 offset:22288
	ds_read_b128 v[160:163], v88 offset:22528
	ds_read_b128 v[168:171], v88 offset:22544
	ds_read2st64_b64 v[188:191], v104 offset0:42 offset1:45
	s_waitcnt lgkmcnt(14)
	v_pk_mul_f32 v[104:105], v[128:129], v[200:201]
	v_pk_mul_f32 v[128:129], v[128:129], v[204:205]
	v_pk_fma_f32 v[104:105], v[114:115], v[130:131], v[104:105]
	v_pk_fma_f32 v[128:129], v[194:195], v[130:131], v[128:129]
	v_pk_fma_f32 v[104:105], v[192:193], v[132:133], v[104:105]
	v_pk_fma_f32 v[128:129], v[196:197], v[132:133], v[128:129]
	v_pk_fma_f32 v[104:105], v[202:203], v[134:135], v[104:105]
	v_pk_fma_f32 v[128:129], v[184:185], v[134:135], v[128:129]
	v_add_f32_e32 v104, v104, v105
	v_add_f32_e32 v128, v128, v129
	s_nop 0
	v_add_f32_dpp v104, v104, v104 quad_perm:[1,0,3,2] row_mask:0xf bank_mask:0xf bound_ctrl:1
	v_add_f32_dpp v128, v128, v128 quad_perm:[1,0,3,2] row_mask:0xf bank_mask:0xf bound_ctrl:1
	s_nop 0
	v_add_f32_dpp v104, v104, v104 quad_perm:[2,3,0,1] row_mask:0xf bank_mask:0xf bound_ctrl:1
	v_add_f32_dpp v128, v128, v128 quad_perm:[2,3,0,1] row_mask:0xf bank_mask:0xf bound_ctrl:1
	s_nop 0
	v_add_f32_dpp v104, v104, v104 row_half_mirror row_mask:0xf bank_mask:0xf bound_ctrl:1
	v_add_f32_dpp v128, v128, v128 row_half_mirror row_mask:0xf bank_mask:0xf bound_ctrl:1
	v_pk_fma_f32 v[198:199], v[104:105], v[164:165], v[198:199] op_sel_hi:[0,1,1]
	v_pk_fma_f32 v[120:121], v[128:129], v[164:165], v[120:121] op_sel_hi:[0,1,1]
	v_pk_fma_f32 v[198:199], v[200:201], v[106:107], v[198:199]
	v_pk_mul_f32 v[200:201], v[122:123], v[186:187] op_sel_hi:[1,0]
	v_pk_fma_f32 v[204:205], v[204:205], v[106:107], v[120:121]
	v_pk_mul_f32 v[106:107], v[122:123], v[186:187] op_sel:[0,1]
	v_pk_fma_f32 v[200:201], v[104:105], v[166:167], v[200:201] op_sel_hi:[0,1,1]
	v_pk_fma_f32 v[106:107], v[128:129], v[166:167], v[106:107] op_sel_hi:[0,1,1]
	v_pk_fma_f32 v[114:115], v[114:115], v[108:109], v[200:201]
	v_pk_mul_f32 v[200:201], v[124:125], v[186:187] op_sel_hi:[1,0]
	v_pk_fma_f32 v[206:207], v[194:195], v[108:109], v[106:107]
	v_pk_mul_f32 v[106:107], v[124:125], v[186:187] op_sel:[0,1]
	s_waitcnt lgkmcnt(13)
	v_pk_fma_f32 v[200:201], v[104:105], v[172:173], v[200:201] op_sel_hi:[0,1,1]
	v_pk_fma_f32 v[106:107], v[128:129], v[172:173], v[106:107] op_sel_hi:[0,1,1]
	v_pk_fma_f32 v[200:201], v[192:193], v[110:111], v[200:201]
	v_pk_mul_f32 v[192:193], v[126:127], v[186:187] op_sel_hi:[1,0]
	v_pk_fma_f32 v[110:111], v[196:197], v[110:111], v[106:107]
	v_pk_mul_f32 v[106:107], v[126:127], v[186:187] op_sel:[0,1]
	v_pk_fma_f32 v[104:105], v[104:105], v[174:175], v[192:193] op_sel_hi:[0,1,1]
	v_pk_fma_f32 v[106:107], v[128:129], v[174:175], v[106:107] op_sel_hi:[0,1,1]
	s_waitcnt lgkmcnt(6)
	v_pk_mul_f32 v[108:109], v[144:145], v[198:199]
	v_pk_fma_f32 v[202:203], v[202:203], v[112:113], v[104:105]
	v_pk_mul_f32 v[104:105], v[176:177], v[198:199]
	v_pk_fma_f32 v[112:113], v[184:185], v[112:113], v[106:107]
	v_pk_mul_f32 v[106:107], v[176:177], v[204:205]
	v_pk_fma_f32 v[108:109], v[114:115], v[146:147], v[108:109]
	v_pk_fma_f32 v[104:105], v[114:115], v[178:179], v[104:105]
	v_pk_fma_f32 v[106:107], v[206:207], v[178:179], v[106:107]
	s_waitcnt lgkmcnt(5)
	v_pk_fma_f32 v[108:109], v[200:201], v[148:149], v[108:109]
	v_pk_fma_f32 v[104:105], v[200:201], v[180:181], v[104:105]
	v_pk_fma_f32 v[106:107], v[110:111], v[180:181], v[106:107]
	v_pk_fma_f32 v[108:109], v[202:203], v[150:151], v[108:109]
	v_pk_fma_f32 v[104:105], v[202:203], v[182:183], v[104:105]
	v_pk_fma_f32 v[106:107], v[112:113], v[182:183], v[106:107]
	ds_read_b128 v[120:123], v88 offset:23040
	ds_read_b128 v[124:127], v88 offset:23056
	ds_read_b128 v[128:131], v88 offset:23296
	ds_read_b128 v[132:135], v88 offset:23312
	ds_read_b128 v[164:167], v88 offset:23552
	ds_read_b128 v[172:175], v88 offset:23568
	ds_read_b128 v[176:179], v88 offset:23808
	ds_read_b128 v[180:183], v88 offset:23824
	ds_read_b128 v[184:187], v88 offset:24064
	ds_read_b128 v[192:195], v88 offset:24080
	v_add_f32_e32 v88, v108, v109
	s_waitcnt lgkmcnt(10)
	v_pk_mul_f32 v[108:109], v[20:21], v[188:189] op_sel_hi:[1,0]
	v_pk_mul_f32 v[144:145], v[144:145], v[204:205]
	v_add_f32_dpp v88, v88, v88 quad_perm:[1,0,3,2] row_mask:0xf bank_mask:0xf bound_ctrl:1
	v_pk_fma_f32 v[144:145], v[206:207], v[146:147], v[144:145]
	v_pk_mul_f32 v[20:21], v[20:21], v[188:189] op_sel:[0,1]
	v_add_f32_dpp v88, v88, v88 quad_perm:[2,3,0,1] row_mask:0xf bank_mask:0xf bound_ctrl:1
	v_pk_fma_f32 v[144:145], v[110:111], v[148:149], v[144:145]
	s_nop 0
	v_add_f32_dpp v88, v88, v88 row_half_mirror row_mask:0xf bank_mask:0xf bound_ctrl:1
	v_pk_fma_f32 v[108:109], v[88:89], v[152:153], v[108:109] op_sel_hi:[0,1,1]
	v_pk_fma_f32 v[196:197], v[198:199], v[12:13], v[108:109]
	v_pk_mul_f32 v[108:109], v[22:23], v[188:189] op_sel_hi:[1,0]
	v_pk_fma_f32 v[144:145], v[112:113], v[150:151], v[144:145]
	v_pk_fma_f32 v[108:109], v[88:89], v[154:155], v[108:109] op_sel_hi:[0,1,1]
	v_pk_fma_f32 v[114:115], v[114:115], v[14:15], v[108:109]
	v_pk_mul_f32 v[108:109], v[24:25], v[188:189] op_sel_hi:[1,0]
	v_pk_fma_f32 v[108:109], v[88:89], v[156:157], v[108:109] op_sel_hi:[0,1,1]
	v_pk_fma_f32 v[198:199], v[200:201], v[16:17], v[108:109]
	v_pk_mul_f32 v[108:109], v[26:27], v[188:189] op_sel_hi:[1,0]
	v_pk_fma_f32 v[108:109], v[88:89], v[158:159], v[108:109] op_sel_hi:[0,1,1]
	v_add_f32_e32 v88, v144, v145
	v_pk_fma_f32 v[200:201], v[202:203], v[18:19], v[108:109]
	v_pk_mul_f32 v[108:109], v[160:161], v[196:197]
	v_add_f32_dpp v88, v88, v88 quad_perm:[1,0,3,2] row_mask:0xf bank_mask:0xf bound_ctrl:1
	v_pk_fma_f32 v[108:109], v[114:115], v[162:163], v[108:109]
	s_nop 0
	v_add_f32_dpp v88, v88, v88 quad_perm:[2,3,0,1] row_mask:0xf bank_mask:0xf bound_ctrl:1
	v_pk_fma_f32 v[108:109], v[198:199], v[168:169], v[108:109]
	s_nop 0
	v_add_f32_dpp v88, v88, v88 row_half_mirror row_mask:0xf bank_mask:0xf bound_ctrl:1
	v_pk_fma_f32 v[20:21], v[88:89], v[152:153], v[20:21] op_sel_hi:[0,1,1]
	v_pk_fma_f32 v[12:13], v[204:205], v[12:13], v[20:21]
	v_pk_mul_f32 v[20:21], v[22:23], v[188:189] op_sel:[0,1]
	v_pk_fma_f32 v[108:109], v[200:201], v[170:171], v[108:109]
	v_pk_fma_f32 v[20:21], v[88:89], v[154:155], v[20:21] op_sel_hi:[0,1,1]
	v_pk_fma_f32 v[14:15], v[206:207], v[14:15], v[20:21]
	v_pk_mul_f32 v[20:21], v[24:25], v[188:189] op_sel:[0,1]
	s_nop 0
	v_pk_fma_f32 v[20:21], v[88:89], v[156:157], v[20:21] op_sel_hi:[0,1,1]
	v_pk_fma_f32 v[144:145], v[110:111], v[16:17], v[20:21]
	v_pk_mul_f32 v[16:17], v[26:27], v[188:189] op_sel:[0,1]
	s_nop 0
	v_pk_fma_f32 v[16:17], v[88:89], v[158:159], v[16:17] op_sel_hi:[0,1,1]
	v_pk_fma_f32 v[146:147], v[112:113], v[18:19], v[16:17]
	v_pk_mul_f32 v[16:17], v[160:161], v[12:13]
	s_waitcnt lgkmcnt(7)
	v_pk_mul_f32 v[18:19], v[128:129], v[190:191] op_sel_hi:[1,0]
	v_pk_fma_f32 v[16:17], v[14:15], v[162:163], v[16:17]
	s_nop 0
	v_pk_fma_f32 v[16:17], v[144:145], v[168:169], v[16:17]
	s_nop 0
	v_pk_fma_f32 v[110:111], v[146:147], v[170:171], v[16:17]
	s_waitcnt lgkmcnt(5)
	v_pk_mul_f32 v[16:17], v[164:165], v[196:197]
	s_nop 0
	v_pk_fma_f32 v[16:17], v[114:115], v[166:167], v[16:17]
	s_waitcnt lgkmcnt(4)
	v_pk_fma_f32 v[16:17], v[198:199], v[172:173], v[16:17]
	s_nop 0
	v_pk_fma_f32 v[16:17], v[200:201], v[174:175], v[16:17]
	s_nop 0
	v_add_f32_e32 v16, v16, v17
	s_nop 1
	v_add_f32_dpp v16, v16, v16 quad_perm:[1,0,3,2] row_mask:0xf bank_mask:0xf bound_ctrl:1
	s_nop 1
	v_add_f32_dpp v16, v16, v16 quad_perm:[2,3,0,1] row_mask:0xf bank_mask:0xf bound_ctrl:1
	s_nop 1
	v_add_f32_dpp v16, v16, v16 row_half_mirror row_mask:0xf bank_mask:0xf bound_ctrl:1
	s_waitcnt lgkmcnt(3)
	v_pk_fma_f32 v[18:19], v[16:17], v[176:177], v[18:19] op_sel_hi:[0,1,1]
	v_pk_fma_f32 v[24:25], v[196:197], v[120:121], v[18:19]
	v_pk_mul_f32 v[18:19], v[130:131], v[190:191] op_sel_hi:[1,0]
	s_nop 0
	v_pk_fma_f32 v[18:19], v[16:17], v[178:179], v[18:19] op_sel_hi:[0,1,1]
	v_pk_fma_f32 v[26:27], v[114:115], v[122:123], v[18:19]
	v_pk_mul_f32 v[18:19], v[132:133], v[190:191] op_sel_hi:[1,0]
	s_waitcnt lgkmcnt(2)
	v_pk_fma_f32 v[18:19], v[16:17], v[180:181], v[18:19] op_sel_hi:[0,1,1]
	v_pk_fma_f32 v[20:21], v[198:199], v[124:125], v[18:19]
	v_pk_mul_f32 v[18:19], v[134:135], v[190:191] op_sel_hi:[1,0]
	s_nop 0
	v_pk_fma_f32 v[16:17], v[16:17], v[182:183], v[18:19] op_sel_hi:[0,1,1]
	v_pk_fma_f32 v[22:23], v[200:201], v[126:127], v[16:17]
	s_waitcnt lgkmcnt(1)
	v_pk_mul_f32 v[16:17], v[184:185], v[24:25]
	s_nop 0
	v_pk_fma_f32 v[16:17], v[26:27], v[186:187], v[16:17]
	s_waitcnt lgkmcnt(0)
	v_pk_fma_f32 v[16:17], v[20:21], v[192:193], v[16:17]
	s_nop 0
	v_pk_fma_f32 v[112:113], v[22:23], v[194:195], v[16:17]
	v_pk_mul_f32 v[16:17], v[164:165], v[12:13]
	s_nop 0
	v_pk_fma_f32 v[16:17], v[14:15], v[166:167], v[16:17]
	s_nop 0
	v_pk_fma_f32 v[16:17], v[144:145], v[172:173], v[16:17]
	s_nop 0
	v_pk_fma_f32 v[16:17], v[146:147], v[174:175], v[16:17]
	s_nop 0
	v_add_f32_e32 v16, v16, v17
	s_nop 1
	v_add_f32_dpp v16, v16, v16 quad_perm:[1,0,3,2] row_mask:0xf bank_mask:0xf bound_ctrl:1
	s_nop 1
	v_add_f32_dpp v16, v16, v16 quad_perm:[2,3,0,1] row_mask:0xf bank_mask:0xf bound_ctrl:1
	s_nop 1
	v_add_f32_dpp v88, v16, v16 row_half_mirror row_mask:0xf bank_mask:0xf bound_ctrl:1
	v_pk_mul_f32 v[16:17], v[128:129], v[190:191] op_sel:[0,1]
	s_nop 0
	v_pk_fma_f32 v[16:17], v[88:89], v[176:177], v[16:17] op_sel_hi:[0,1,1]
	v_pk_fma_f32 v[16:17], v[12:13], v[120:121], v[16:17]
	v_pk_mul_f32 v[12:13], v[130:131], v[190:191] op_sel:[0,1]
	v_add_u32_e32 v120, 8, v29
	v_pk_fma_f32 v[12:13], v[88:89], v[178:179], v[12:13] op_sel_hi:[0,1,1]
	v_pk_fma_f32 v[18:19], v[14:15], v[122:123], v[12:13]
	v_pk_mul_f32 v[12:13], v[132:133], v[190:191] op_sel:[0,1]
	v_pk_mul_f32 v[14:15], v[134:135], v[190:191] op_sel:[0,1]
	v_add_u32_e32 v122, s27, v118
	v_pk_fma_f32 v[12:13], v[88:89], v[180:181], v[12:13] op_sel_hi:[0,1,1]
	v_pk_fma_f32 v[14:15], v[88:89], v[182:183], v[14:15] op_sel_hi:[0,1,1]
	v_add_u32_e32 v88, -16, v122
	v_cndmask_b32_e64 v88, v120, v88, s[2:3]
	v_add_u32_e32 v88, s26, v88
	v_mul_lo_u32 v88, v88, s50
	v_lshl_add_u64 v[120:121], v[88:89], 1, v[36:37]
	v_pk_mul_f32 v[114:115], v[184:185], v[16:17]
	v_pk_fma_f32 v[12:13], v[144:145], v[124:125], v[12:13]
	v_pk_fma_f32 v[114:115], v[18:19], v[186:187], v[114:115]
	v_pk_fma_f32 v[14:15], v[146:147], v[126:127], v[14:15]
	v_pk_fma_f32 v[114:115], v[12:13], v[192:193], v[114:115]
	v_add_f32_e32 v212, v58, v59
	v_add_f32_e32 v220, v60, v61
	v_pk_fma_f32 v[114:115], v[14:15], v[194:195], v[114:115]
	s_nop 0
	v_add_f32_e32 v213, v62, v63
	v_add_f32_e32 v221, v64, v65
	s_nop 0
	v_add_f32_e32 v214, v66, v67
	v_add_f32_e32 v222, v68, v69
	s_nop 0
	v_add_f32_e32 v215, v70, v71
	v_add_f32_e32 v223, v72, v73
	s_nop 0
	v_add_f32_e32 v216, v74, v75
	v_add_f32_e32 v224, v76, v77
	s_nop 0
	v_add_f32_e32 v217, v78, v79
	v_add_f32_e32 v225, v80, v81
	s_nop 1
	v_add_f32_dpp v210, v210, v210 row_shl:4 row_mask:0xf bank_mask:0x5 bound_ctrl:1
	v_add_f32_dpp v210, v214, v214 row_shr:4 row_mask:0xf bank_mask:0xa bound_ctrl:1
	v_add_f32_dpp v218, v218, v218 row_shl:4 row_mask:0xf bank_mask:0x5 bound_ctrl:1
	v_add_f32_dpp v218, v222, v222 row_shr:4 row_mask:0xf bank_mask:0xa bound_ctrl:1
	v_add_f32_dpp v211, v211, v211 row_shl:4 row_mask:0xf bank_mask:0x5 bound_ctrl:1
	v_add_f32_dpp v211, v215, v215 row_shr:4 row_mask:0xf bank_mask:0xa bound_ctrl:1
	v_add_f32_dpp v219, v219, v219 row_shl:4 row_mask:0xf bank_mask:0x5 bound_ctrl:1
	v_add_f32_dpp v219, v223, v223 row_shr:4 row_mask:0xf bank_mask:0xa bound_ctrl:1
	v_add_f32_dpp v212, v212, v212 row_shl:4 row_mask:0xf bank_mask:0x5 bound_ctrl:1
	v_add_f32_dpp v212, v216, v216 row_shr:4 row_mask:0xf bank_mask:0xa bound_ctrl:1
	v_add_f32_dpp v220, v220, v220 row_shl:4 row_mask:0xf bank_mask:0x5 bound_ctrl:1
	v_add_f32_dpp v220, v224, v224 row_shr:4 row_mask:0xf bank_mask:0xa bound_ctrl:1
	v_add_f32_dpp v213, v213, v213 row_shl:4 row_mask:0xf bank_mask:0x5 bound_ctrl:1
	v_add_f32_dpp v213, v217, v217 row_shr:4 row_mask:0xf bank_mask:0xa bound_ctrl:1
	v_add_f32_dpp v221, v221, v221 row_shl:4 row_mask:0xf bank_mask:0x5 bound_ctrl:1
	v_add_f32_dpp v221, v225, v225 row_shr:4 row_mask:0xf bank_mask:0xa bound_ctrl:1
	v_and_b32_e32 v214, 1, v137
	v_cmp_ne_u32_e64 s[100:101], 0, v214
	v_add_f32_dpp v210, v210, v210 quad_perm:[1,0,3,2] row_mask:0xf bank_mask:0xf bound_ctrl:1
	v_add_f32_dpp v218, v218, v218 quad_perm:[1,0,3,2] row_mask:0xf bank_mask:0xf bound_ctrl:1
	v_add_f32_dpp v211, v211, v211 quad_perm:[1,0,3,2] row_mask:0xf bank_mask:0xf bound_ctrl:1
	v_add_f32_dpp v219, v219, v219 quad_perm:[1,0,3,2] row_mask:0xf bank_mask:0xf bound_ctrl:1
	v_add_f32_dpp v212, v212, v212 quad_perm:[1,0,3,2] row_mask:0xf bank_mask:0xf bound_ctrl:1
	v_add_f32_dpp v220, v220, v220 quad_perm:[1,0,3,2] row_mask:0xf bank_mask:0xf bound_ctrl:1
	v_add_f32_dpp v213, v213, v213 quad_perm:[1,0,3,2] row_mask:0xf bank_mask:0xf bound_ctrl:1
	v_add_f32_dpp v221, v221, v221 quad_perm:[1,0,3,2] row_mask:0xf bank_mask:0xf bound_ctrl:1
	v_cndmask_b32_e64 v210, v210, v211, s[100:101]
	v_cndmask_b32_e64 v218, v218, v219, s[100:101]
	v_cndmask_b32_e64 v212, v212, v213, s[100:101]
	v_cndmask_b32_e64 v220, v220, v221, s[100:101]
	v_and_b32_e32 v214, 2, v137
	s_nop 0
	v_cmp_ne_u32_e64 s[100:101], 0, v214
	v_add_f32_dpp v210, v210, v210 quad_perm:[2,3,0,1] row_mask:0xf bank_mask:0xf bound_ctrl:1
	v_add_f32_dpp v218, v218, v218 quad_perm:[2,3,0,1] row_mask:0xf bank_mask:0xf bound_ctrl:1
	v_add_f32_dpp v212, v212, v212 quad_perm:[2,3,0,1] row_mask:0xf bank_mask:0xf bound_ctrl:1
	v_add_f32_dpp v220, v220, v220 quad_perm:[2,3,0,1] row_mask:0xf bank_mask:0xf bound_ctrl:1
	s_nop 0
	v_cndmask_b32_e64 v50, v210, v212, s[100:101]
	v_cndmask_b32_e64 v51, v218, v220, s[100:101]
	v_cvt_pk_bf16_f32 v50, v50, v51
	global_store_dword v[120:121], v50, off
	v_add_u32_e32 v50, -8, v122
	v_cndmask_b32_e64 v50, v29, v50, s[2:3]
	v_add_u32_e32 v50, s26, v50
	v_mul_lo_u32 v88, v50, s50
	v_add_f32_e32 v228, v92, v93
	v_add_f32_e32 v236, v94, v95
	v_lshl_add_u64 v[50:51], v[88:89], 1, v[36:37]
	s_nop 0
	v_add_f32_e32 v229, v96, v97
	v_add_f32_e32 v237, v98, v99
	s_nop 0
	v_add_f32_e32 v230, v100, v101
	v_add_f32_e32 v238, v102, v103
	s_nop 0
	v_add_f32_e32 v231, v104, v105
	v_add_f32_e32 v239, v106, v107
	s_nop 0
	v_add_f32_e32 v232, v108, v109
	v_add_f32_e32 v240, v110, v111
	s_nop 0
	v_add_f32_e32 v233, v112, v113
	v_add_f32_e32 v145, v114, v115
	s_nop 0
	s_nop 1
	v_add_f32_dpp v226, v226, v226 row_shl:4 row_mask:0xf bank_mask:0x5 bound_ctrl:1
	v_add_f32_dpp v226, v230, v230 row_shr:4 row_mask:0xf bank_mask:0xa bound_ctrl:1
	v_add_f32_dpp v234, v234, v234 row_shl:4 row_mask:0xf bank_mask:0x5 bound_ctrl:1
	v_add_f32_dpp v234, v238, v238 row_shr:4 row_mask:0xf bank_mask:0xa bound_ctrl:1
	v_add_f32_dpp v227, v227, v227 row_shl:4 row_mask:0xf bank_mask:0x5 bound_ctrl:1
	v_add_f32_dpp v227, v231, v231 row_shr:4 row_mask:0xf bank_mask:0xa bound_ctrl:1
	v_add_f32_dpp v235, v235, v235 row_shl:4 row_mask:0xf bank_mask:0x5 bound_ctrl:1
	v_add_f32_dpp v235, v239, v239 row_shr:4 row_mask:0xf bank_mask:0xa bound_ctrl:1
	v_add_f32_dpp v228, v228, v228 row_shl:4 row_mask:0xf bank_mask:0x5 bound_ctrl:1
	v_add_f32_dpp v228, v232, v232 row_shr:4 row_mask:0xf bank_mask:0xa bound_ctrl:1
	v_add_f32_dpp v236, v236, v236 row_shl:4 row_mask:0xf bank_mask:0x5 bound_ctrl:1
	v_add_f32_dpp v236, v240, v240 row_shr:4 row_mask:0xf bank_mask:0xa bound_ctrl:1
	v_add_f32_dpp v229, v229, v229 row_shl:4 row_mask:0xf bank_mask:0x5 bound_ctrl:1
	v_add_f32_dpp v229, v233, v233 row_shr:4 row_mask:0xf bank_mask:0xa bound_ctrl:1
	v_add_f32_dpp v237, v237, v237 row_shl:4 row_mask:0xf bank_mask:0x5 bound_ctrl:1
	v_add_f32_dpp v237, v145, v145 row_shr:4 row_mask:0xf bank_mask:0xa bound_ctrl:1
	v_and_b32_e32 v230, 1, v137
	v_cmp_ne_u32_e64 s[100:101], 0, v230
	v_add_f32_dpp v226, v226, v226 quad_perm:[1,0,3,2] row_mask:0xf bank_mask:0xf bound_ctrl:1
	v_add_f32_dpp v234, v234, v234 quad_perm:[1,0,3,2] row_mask:0xf bank_mask:0xf bound_ctrl:1
	v_add_f32_dpp v227, v227, v227 quad_perm:[1,0,3,2] row_mask:0xf bank_mask:0xf bound_ctrl:1
	v_add_f32_dpp v235, v235, v235 quad_perm:[1,0,3,2] row_mask:0xf bank_mask:0xf bound_ctrl:1
	v_add_f32_dpp v228, v228, v228 quad_perm:[1,0,3,2] row_mask:0xf bank_mask:0xf bound_ctrl:1
	v_add_f32_dpp v236, v236, v236 quad_perm:[1,0,3,2] row_mask:0xf bank_mask:0xf bound_ctrl:1
	v_add_f32_dpp v229, v229, v229 quad_perm:[1,0,3,2] row_mask:0xf bank_mask:0xf bound_ctrl:1
	v_add_f32_dpp v237, v237, v237 quad_perm:[1,0,3,2] row_mask:0xf bank_mask:0xf bound_ctrl:1
	v_cndmask_b32_e64 v226, v226, v227, s[100:101]
	v_cndmask_b32_e64 v234, v234, v235, s[100:101]
	v_cndmask_b32_e64 v228, v228, v229, s[100:101]
	v_cndmask_b32_e64 v236, v236, v237, s[100:101]
	v_and_b32_e32 v230, 2, v137
	s_nop 0
	v_cmp_ne_u32_e64 s[100:101], 0, v230
	v_add_f32_dpp v226, v226, v226 quad_perm:[2,3,0,1] row_mask:0xf bank_mask:0xf bound_ctrl:1
	v_add_f32_dpp v234, v234, v234 quad_perm:[2,3,0,1] row_mask:0xf bank_mask:0xf bound_ctrl:1
	v_add_f32_dpp v228, v228, v228 quad_perm:[2,3,0,1] row_mask:0xf bank_mask:0xf bound_ctrl:1
	v_add_f32_dpp v236, v236, v236 quad_perm:[2,3,0,1] row_mask:0xf bank_mask:0xf bound_ctrl:1
	s_nop 0
	v_cndmask_b32_e64 v52, v226, v228, s[100:101]
	v_cndmask_b32_e64 v53, v234, v236, s[100:101]
	v_cvt_pk_bf16_f32 v52, v52, v53
	global_store_dword v[50:51], v52, off
	s_cbranch_vccnz .LBB0_1952
	s_and_b32 s0, s27, 16
	v_add_u32_e32 v50, s0, v33
	v_mad_u64_u32 v[54:55], s[0:1], v50, s45, v[32:33]
	s_waitcnt vmcnt(5)
	v_lshlrev_b32_e32 v55, 16, v34
	v_and_b32_e32 v56, 0xffff0000, v34
	v_lshlrev_b32_e32 v57, 16, v35
	v_and_b32_e32 v58, 0xffff0000, v35
	v_lshlrev_b32_e32 v50, 16, v30
	v_and_b32_e32 v51, 0xffff0000, v30
	v_lshlrev_b32_e32 v52, 16, v31
	v_and_b32_e32 v53, 0xffff0000, v31
	ds_write_b128 v54, v[50:53] offset:256
	v_xor_b32_e32 v51, 0x80000000, v56
	v_xor_b32_e32 v50, 0x80000000, v55
	v_xor_b32_e32 v53, 0x80000000, v58
	v_xor_b32_e32 v52, 0x80000000, v57
	ds_write_b128 v54, v[50:53] offset:512
	s_waitcnt vmcnt(4)
	v_lshlrev_b32_e32 v50, 16, v38
	v_and_b32_e32 v51, 0xffff0000, v38
	v_lshlrev_b32_e32 v52, 16, v39
	v_and_b32_e32 v53, 0xffff0000, v39
	ds_write_b128 v54, v[0:3]
	ds_write_b128 v54, v[50:53] offset:768
	s_waitcnt vmcnt(3)
	ds_write_b128 v54, v[4:7] offset:1024
	s_waitcnt vmcnt(2)
	ds_write_b128 v54, v[8:11] offset:1280
	s_branch .LBB0_1952
